# v55 + LDS read base addresses hoisted out of the K-loops into per-tile persistent VGPRs (4 fewer VALU ops per iteration per wave)
# speedup vs baseline: 1.1510x; 1.0031x over previous
.LBB0_260:
	s_ashr_i32 s65, s64, 31
	s_lshl_b64 s[22:23], s[64:65], 20
	s_add_u32 s62, s79, s22
	s_addc_u32 s63, s28, s23
	s_and_b64 s[22:23], s[4:5], exec
	s_cselect_b32 s22, s63, s77
	s_cselect_b32 s23, s62, s76
	s_ashr_i32 s49, s48, 31
	s_lshl_b64 s[70:71], s[48:49], 20
	s_add_u32 s70, s8, s70
	s_addc_u32 s71, s9, s71
	s_and_b64 s[90:91], s[4:5], exec
	s_cselect_b32 s49, s71, s85
	s_cselect_b32 s57, s70, s84
	s_ashr_i32 s51, s50, 31
	s_lshl_b32 s90, s44, 8
	s_lshl_b64 vcc, s[50:51], 10
	s_ashr_i32 s0, s50, 5
	s_ashr_i32 s91, s90, 31
	s_add_u32 s76, s76, 0x80080
	v_lshl_add_u64 v[2:3], s[90:91], 2, v[134:135]
	v_mov_b32_e32 v4, 0x6000
	s_addc_u32 s77, s77, 0
	v_lshl_add_u64 v[142:143], v[136:137], 0, vcc
	v_mad_i64_i32 v[144:145], vcc, s0, v4, v[2:3]
	s_add_u32 s51, s84, 0x100
	s_addc_u32 s58, s85, 0
	s_mov_b32 s65, -2
	v_add_u32_e32 v175, 0x10000, v176
	v_add_u32_e32 v224, 0x14000, v176
	v_add_u32_e32 v225, 0x18000, v176
	v_add_u32_e32 v226, 0x1c000, v176
	s_branch .LBB0_262
.LBB0_261:
	s_add_u32 s0, s76, 0xfff80080
	s_addc_u32 s1, s77, -1
	s_and_b64 s[84:85], s[84:85], exec
	s_cselect_b32 vcc_hi, s22, s1
	s_cselect_b32 vcc_lo, s23, s0
	s_cselect_b32 s85, s49, s58
	s_cselect_b32 s84, s57, s51
	s_add_i32 s0, 0, 0x10000
	s_add_i32 s1, 0, 0x14000
	ds_read_b128 v[146:149], v175
	ds_read_b128 v[150:153], v175 offset:1024
	ds_read_b128 v[154:157], v175 offset:2048
	ds_read_b128 v[158:161], v175 offset:3072
	ds_read_b128 v[162:165], v224
	ds_read_b128 v[166:169], v224 offset:1024
	ds_read_b128 v[170:173], v224 offset:2048
	ds_read_b128 v[178:181], v224 offset:3072
	s_add_i32 m0, s21, 0xc000
	ds_read_b128 v[182:185], v177
	ds_read_b128 v[186:189], v177 offset:1024
	ds_read_b128 v[190:193], v177 offset:2048
	ds_read_b128 v[204:207], v177 offset:3072
	ds_read_b128 v[208:211], v177 offset:4096
	ds_read_b128 v[212:215], v177 offset:5120
	ds_read_b128 v[216:219], v177 offset:6144
	ds_read_b128 v[220:223], v177 offset:7168
	global_load_lds_dwordx4 v138, s[76:77]
	s_add_i32 m0, s21, 0xe000
	s_nop 0
	global_load_lds_dwordx4 v140, s[76:77]
	s_waitcnt vmcnt(8)
	s_waitcnt lgkmcnt(0)
	s_barrier
	s_waitcnt lgkmcnt(0)
	v_mfma_f32_16x16x32_bf16 v[126:129], v[146:149], v[182:185], v[126:129]
	v_mfma_f32_16x16x32_bf16 v[126:129], v[150:153], v[186:189], v[126:129]
	v_mfma_f32_16x16x32_bf16 v[122:125], v[158:161], v[186:189], v[122:125]
	v_mfma_f32_16x16x32_bf16 v[122:125], v[154:157], v[182:185], v[122:125]
	v_mfma_f32_16x16x32_bf16 v[118:121], v[162:165], v[182:185], v[118:121]
	v_mfma_f32_16x16x32_bf16 v[118:121], v[166:169], v[186:189], v[118:121]
	v_mfma_f32_16x16x32_bf16 v[114:117], v[178:181], v[186:189], v[114:117]
	v_mfma_f32_16x16x32_bf16 v[114:117], v[170:173], v[182:185], v[114:117]
	v_mfma_f32_16x16x32_bf16 v[98:101], v[170:173], v[190:193], v[98:101]
	v_mfma_f32_16x16x32_bf16 v[98:101], v[178:181], v[204:207], v[98:101]
	v_mfma_f32_16x16x32_bf16 v[102:105], v[166:169], v[204:207], v[102:105]
	v_mfma_f32_16x16x32_bf16 v[102:105], v[162:165], v[190:193], v[102:105]
	v_mfma_f32_16x16x32_bf16 v[106:109], v[154:157], v[190:193], v[106:109]
	v_mfma_f32_16x16x32_bf16 v[106:109], v[158:161], v[204:207], v[106:109]
	v_mfma_f32_16x16x32_bf16 v[110:113], v[150:153], v[204:207], v[110:113]
	v_mfma_f32_16x16x32_bf16 v[110:113], v[146:149], v[190:193], v[110:113]
	v_mfma_f32_16x16x32_bf16 v[94:97], v[146:149], v[208:211], v[94:97]
	v_mfma_f32_16x16x32_bf16 v[94:97], v[150:153], v[212:215], v[94:97]
	v_mfma_f32_16x16x32_bf16 v[90:93], v[158:161], v[212:215], v[90:93]
	v_mfma_f32_16x16x32_bf16 v[90:93], v[154:157], v[208:211], v[90:93]
	v_mfma_f32_16x16x32_bf16 v[86:89], v[162:165], v[208:211], v[86:89]
	v_mfma_f32_16x16x32_bf16 v[86:89], v[166:169], v[212:215], v[86:89]
	v_mfma_f32_16x16x32_bf16 v[82:85], v[178:181], v[212:215], v[82:85]
	v_mfma_f32_16x16x32_bf16 v[82:85], v[170:173], v[208:211], v[82:85]
	v_mfma_f32_16x16x32_bf16 v[66:69], v[170:173], v[216:219], v[66:69]
	v_mfma_f32_16x16x32_bf16 v[66:69], v[178:181], v[220:223], v[66:69]
	v_mfma_f32_16x16x32_bf16 v[70:73], v[166:169], v[220:223], v[70:73]
	v_mfma_f32_16x16x32_bf16 v[70:73], v[162:165], v[216:219], v[70:73]
	v_mfma_f32_16x16x32_bf16 v[74:77], v[154:157], v[216:219], v[74:77]
	v_mfma_f32_16x16x32_bf16 v[74:77], v[158:161], v[220:223], v[74:77]
	v_mfma_f32_16x16x32_bf16 v[78:81], v[150:153], v[220:223], v[78:81]
	v_mfma_f32_16x16x32_bf16 v[78:81], v[146:149], v[216:219], v[78:81]
	s_barrier
	s_add_i32 s0, s0, s20
	s_mov_b32 m0, s0
	ds_read_b128 v[182:185], v177 offset:16384
	ds_read_b128 v[186:189], v177 offset:17408
	ds_read_b128 v[190:193], v177 offset:18432
	ds_read_b128 v[204:207], v177 offset:19456
	ds_read_b128 v[208:211], v177 offset:20480
	ds_read_b128 v[212:215], v177 offset:21504
	ds_read_b128 v[216:219], v177 offset:22528
	ds_read_b128 v[220:223], v177 offset:23552
	global_load_lds_dwordx4 v132, s[84:85]
	s_add_i32 m0, s0, 0x2000
	s_add_u32 s94, s84, 0x80000
	s_addc_u32 s95, s85, 0
	s_add_i32 s0, s1, s20
	global_load_lds_dwordx4 v130, s[84:85]
	s_mov_b32 m0, s0
	s_nop 0
	global_load_lds_dwordx4 v132, s[94:95]
	s_add_i32 m0, s0, 0x2000
	s_nop 0
	global_load_lds_dwordx4 v130, s[94:95]
	s_mov_b32 m0, s21
	s_nop 0
	global_load_lds_dwordx4 v132, vcc
	s_mov_b32 m0, s26
	s_nop 0
	global_load_lds_dwordx4 v130, vcc
	s_waitcnt vmcnt(8)
	s_waitcnt lgkmcnt(0)
	s_barrier
	s_waitcnt lgkmcnt(0)
	v_mfma_f32_16x16x32_bf16 v[62:65], v[146:149], v[182:185], v[62:65]
	v_mfma_f32_16x16x32_bf16 v[62:65], v[150:153], v[186:189], v[62:65]
	v_mfma_f32_16x16x32_bf16 v[58:61], v[158:161], v[186:189], v[58:61]
	v_mfma_f32_16x16x32_bf16 v[58:61], v[154:157], v[182:185], v[58:61]
	v_mfma_f32_16x16x32_bf16 v[54:57], v[162:165], v[182:185], v[54:57]
	v_mfma_f32_16x16x32_bf16 v[54:57], v[166:169], v[186:189], v[54:57]
	v_mfma_f32_16x16x32_bf16 v[50:53], v[178:181], v[186:189], v[50:53]
	v_mfma_f32_16x16x32_bf16 v[50:53], v[170:173], v[182:185], v[50:53]
	v_mfma_f32_16x16x32_bf16 v[34:37], v[170:173], v[190:193], v[34:37]
	v_mfma_f32_16x16x32_bf16 v[34:37], v[178:181], v[204:207], v[34:37]
	v_mfma_f32_16x16x32_bf16 v[38:41], v[166:169], v[204:207], v[38:41]
	v_mfma_f32_16x16x32_bf16 v[38:41], v[162:165], v[190:193], v[38:41]
	v_mfma_f32_16x16x32_bf16 v[42:45], v[154:157], v[190:193], v[42:45]
	v_mfma_f32_16x16x32_bf16 v[42:45], v[158:161], v[204:207], v[42:45]
	v_mfma_f32_16x16x32_bf16 v[46:49], v[150:153], v[204:207], v[46:49]
	v_mfma_f32_16x16x32_bf16 v[46:49], v[146:149], v[190:193], v[46:49]
	v_mfma_f32_16x16x32_bf16 v[30:33], v[146:149], v[208:211], v[30:33]
	v_mfma_f32_16x16x32_bf16 v[30:33], v[150:153], v[212:215], v[30:33]
	v_mfma_f32_16x16x32_bf16 v[26:29], v[158:161], v[212:215], v[26:29]
	v_mfma_f32_16x16x32_bf16 v[26:29], v[154:157], v[208:211], v[26:29]
	v_mfma_f32_16x16x32_bf16 v[22:25], v[162:165], v[208:211], v[22:25]
	v_mfma_f32_16x16x32_bf16 v[22:25], v[166:169], v[212:215], v[22:25]
	v_mfma_f32_16x16x32_bf16 v[18:21], v[178:181], v[212:215], v[18:21]
	v_mfma_f32_16x16x32_bf16 v[18:21], v[170:173], v[208:211], v[18:21]
	v_mfma_f32_16x16x32_bf16 v[2:5], v[170:173], v[216:219], v[2:5]
	v_mfma_f32_16x16x32_bf16 v[2:5], v[178:181], v[220:223], v[2:5]
	v_mfma_f32_16x16x32_bf16 v[6:9], v[166:169], v[220:223], v[6:9]
	v_mfma_f32_16x16x32_bf16 v[6:9], v[162:165], v[216:219], v[6:9]
	v_mfma_f32_16x16x32_bf16 v[10:13], v[154:157], v[216:219], v[10:13]
	v_mfma_f32_16x16x32_bf16 v[10:13], v[158:161], v[220:223], v[10:13]
	v_mfma_f32_16x16x32_bf16 v[14:17], v[150:153], v[220:223], v[14:17]
	v_mfma_f32_16x16x32_bf16 v[14:17], v[146:149], v[216:219], v[14:17]
	s_barrier
	s_add_i32 s0, 0, 0x18000
	s_add_i32 s1, 0, 0x1c000
	ds_read_b128 v[146:149], v225
	ds_read_b128 v[150:153], v225 offset:1024
	ds_read_b128 v[154:157], v225 offset:2048
	ds_read_b128 v[158:161], v225 offset:3072
	ds_read_b128 v[162:165], v226
	ds_read_b128 v[166:169], v226 offset:1024
	ds_read_b128 v[170:173], v226 offset:2048
	ds_read_b128 v[178:181], v226 offset:3072
	s_add_u32 s94, vcc_lo, 0x80000
	s_addc_u32 s95, vcc_hi, 0
	s_mov_b32 m0, s27
	ds_read_b128 v[182:185], v177 offset:32768
	ds_read_b128 v[186:189], v177 offset:33792
	ds_read_b128 v[190:193], v177 offset:34816
	ds_read_b128 v[204:207], v177 offset:35840
	ds_read_b128 v[208:211], v177 offset:36864
	ds_read_b128 v[212:215], v177 offset:37888
	ds_read_b128 v[216:219], v177 offset:38912
	ds_read_b128 v[220:223], v177 offset:39936
	global_load_lds_dwordx4 v132, s[94:95]
	s_mov_b32 m0, s29
	s_nop 0
	global_load_lds_dwordx4 v130, s[94:95]
	s_waitcnt vmcnt(8)
	s_waitcnt lgkmcnt(0)
	s_barrier
	s_waitcnt lgkmcnt(0)
	v_mfma_f32_16x16x32_bf16 v[126:129], v[146:149], v[182:185], v[126:129]
	v_mfma_f32_16x16x32_bf16 v[126:129], v[150:153], v[186:189], v[126:129]
	v_mfma_f32_16x16x32_bf16 v[122:125], v[158:161], v[186:189], v[122:125]
	v_mfma_f32_16x16x32_bf16 v[122:125], v[154:157], v[182:185], v[122:125]
	v_mfma_f32_16x16x32_bf16 v[118:121], v[162:165], v[182:185], v[118:121]
	v_mfma_f32_16x16x32_bf16 v[118:121], v[166:169], v[186:189], v[118:121]
	v_mfma_f32_16x16x32_bf16 v[114:117], v[178:181], v[186:189], v[114:117]
	v_mfma_f32_16x16x32_bf16 v[114:117], v[170:173], v[182:185], v[114:117]
	v_mfma_f32_16x16x32_bf16 v[98:101], v[170:173], v[190:193], v[98:101]
	v_mfma_f32_16x16x32_bf16 v[98:101], v[178:181], v[204:207], v[98:101]
	v_mfma_f32_16x16x32_bf16 v[102:105], v[166:169], v[204:207], v[102:105]
	v_mfma_f32_16x16x32_bf16 v[102:105], v[162:165], v[190:193], v[102:105]
	v_mfma_f32_16x16x32_bf16 v[106:109], v[154:157], v[190:193], v[106:109]
	v_mfma_f32_16x16x32_bf16 v[106:109], v[158:161], v[204:207], v[106:109]
	v_mfma_f32_16x16x32_bf16 v[110:113], v[150:153], v[204:207], v[110:113]
	v_mfma_f32_16x16x32_bf16 v[110:113], v[146:149], v[190:193], v[110:113]
	v_mfma_f32_16x16x32_bf16 v[94:97], v[146:149], v[208:211], v[94:97]
	v_mfma_f32_16x16x32_bf16 v[94:97], v[150:153], v[212:215], v[94:97]
	v_mfma_f32_16x16x32_bf16 v[90:93], v[158:161], v[212:215], v[90:93]
	v_mfma_f32_16x16x32_bf16 v[90:93], v[154:157], v[208:211], v[90:93]
	v_mfma_f32_16x16x32_bf16 v[86:89], v[162:165], v[208:211], v[86:89]
	v_mfma_f32_16x16x32_bf16 v[86:89], v[166:169], v[212:215], v[86:89]
	v_mfma_f32_16x16x32_bf16 v[82:85], v[178:181], v[212:215], v[82:85]
	v_mfma_f32_16x16x32_bf16 v[82:85], v[170:173], v[208:211], v[82:85]
	v_mfma_f32_16x16x32_bf16 v[66:69], v[170:173], v[216:219], v[66:69]
	v_mfma_f32_16x16x32_bf16 v[66:69], v[178:181], v[220:223], v[66:69]
	v_mfma_f32_16x16x32_bf16 v[70:73], v[166:169], v[220:223], v[70:73]
	v_mfma_f32_16x16x32_bf16 v[70:73], v[162:165], v[216:219], v[70:73]
	v_mfma_f32_16x16x32_bf16 v[74:77], v[154:157], v[216:219], v[74:77]
	v_mfma_f32_16x16x32_bf16 v[74:77], v[158:161], v[220:223], v[74:77]
	v_mfma_f32_16x16x32_bf16 v[78:81], v[150:153], v[220:223], v[78:81]
	v_mfma_f32_16x16x32_bf16 v[78:81], v[146:149], v[216:219], v[78:81]
	s_barrier
	s_add_u32 s98, s84, 0x80
	s_addc_u32 s99, s85, 0
	s_add_u32 s100, vcc_lo, 0x80
	s_addc_u32 s101, vcc_hi, 0
	s_add_i32 s0, s0, s20
	s_mov_b32 m0, s0
	ds_read_b128 v[182:185], v177 offset:49152
	ds_read_b128 v[186:189], v177 offset:50176
	ds_read_b128 v[190:193], v177 offset:51200
	ds_read_b128 v[204:207], v177 offset:52224
	ds_read_b128 v[208:211], v177 offset:53248
	ds_read_b128 v[212:215], v177 offset:54272
	ds_read_b128 v[216:219], v177 offset:55296
	ds_read_b128 v[220:223], v177 offset:56320
	global_load_lds_dwordx4 v132, s[98:99]
	s_add_i32 m0, s0, 0x2000
	s_add_u32 s84, s84, 0x80080
	s_addc_u32 s85, s85, 0
	s_add_i32 s0, s1, s20
	global_load_lds_dwordx4 v130, s[98:99]
	s_mov_b32 m0, s0
	s_nop 0
	global_load_lds_dwordx4 v132, s[84:85]
	s_add_i32 m0, s0, 0x2000
	s_nop 0
	global_load_lds_dwordx4 v130, s[84:85]
	s_mov_b32 m0, s40
	s_nop 0
	global_load_lds_dwordx4 v132, s[100:101]
	s_mov_b32 m0, s41
	s_nop 0
	global_load_lds_dwordx4 v130, s[100:101]
	s_waitcnt vmcnt(8)
	s_waitcnt lgkmcnt(0)
	s_barrier
	s_waitcnt lgkmcnt(0)
	v_mfma_f32_16x16x32_bf16 v[62:65], v[146:149], v[182:185], v[62:65]
	v_mfma_f32_16x16x32_bf16 v[62:65], v[150:153], v[186:189], v[62:65]
	v_mfma_f32_16x16x32_bf16 v[58:61], v[158:161], v[186:189], v[58:61]
	v_mfma_f32_16x16x32_bf16 v[58:61], v[154:157], v[182:185], v[58:61]
	v_mfma_f32_16x16x32_bf16 v[54:57], v[162:165], v[182:185], v[54:57]
	v_mfma_f32_16x16x32_bf16 v[54:57], v[166:169], v[186:189], v[54:57]
	v_mfma_f32_16x16x32_bf16 v[50:53], v[178:181], v[186:189], v[50:53]
	v_mfma_f32_16x16x32_bf16 v[50:53], v[170:173], v[182:185], v[50:53]
	v_mfma_f32_16x16x32_bf16 v[34:37], v[170:173], v[190:193], v[34:37]
	v_mfma_f32_16x16x32_bf16 v[34:37], v[178:181], v[204:207], v[34:37]
	v_mfma_f32_16x16x32_bf16 v[38:41], v[166:169], v[204:207], v[38:41]
	v_mfma_f32_16x16x32_bf16 v[38:41], v[162:165], v[190:193], v[38:41]
	v_mfma_f32_16x16x32_bf16 v[42:45], v[154:157], v[190:193], v[42:45]
	v_mfma_f32_16x16x32_bf16 v[42:45], v[158:161], v[204:207], v[42:45]
	v_mfma_f32_16x16x32_bf16 v[46:49], v[150:153], v[204:207], v[46:49]
	v_mfma_f32_16x16x32_bf16 v[46:49], v[146:149], v[190:193], v[46:49]
	v_mfma_f32_16x16x32_bf16 v[30:33], v[146:149], v[208:211], v[30:33]
	v_mfma_f32_16x16x32_bf16 v[30:33], v[150:153], v[212:215], v[30:33]
	v_mfma_f32_16x16x32_bf16 v[26:29], v[158:161], v[212:215], v[26:29]
	v_mfma_f32_16x16x32_bf16 v[26:29], v[154:157], v[208:211], v[26:29]
	v_mfma_f32_16x16x32_bf16 v[22:25], v[162:165], v[208:211], v[22:25]
	v_mfma_f32_16x16x32_bf16 v[22:25], v[166:169], v[212:215], v[22:25]
	v_mfma_f32_16x16x32_bf16 v[18:21], v[178:181], v[212:215], v[18:21]
	v_mfma_f32_16x16x32_bf16 v[18:21], v[170:173], v[208:211], v[18:21]
	v_mfma_f32_16x16x32_bf16 v[2:5], v[170:173], v[216:219], v[2:5]
	v_mfma_f32_16x16x32_bf16 v[2:5], v[178:181], v[220:223], v[2:5]
	v_mfma_f32_16x16x32_bf16 v[6:9], v[166:169], v[220:223], v[6:9]
	v_mfma_f32_16x16x32_bf16 v[6:9], v[162:165], v[216:219], v[6:9]
	v_mfma_f32_16x16x32_bf16 v[10:13], v[154:157], v[216:219], v[10:13]
	v_mfma_f32_16x16x32_bf16 v[10:13], v[158:161], v[220:223], v[10:13]
	v_mfma_f32_16x16x32_bf16 v[14:17], v[150:153], v[220:223], v[14:17]
	v_mfma_f32_16x16x32_bf16 v[14:17], v[146:149], v[216:219], v[14:17]
	s_barrier
	s_add_i32 s65, s65, 2
	s_add_u32 s76, s76, 0x100
	s_addc_u32 s77, s77, 0
	s_add_u32 s51, s51, 0x100
	s_addc_u32 s58, s58, 0
	s_cmp_gt_u32 s65, 29
	s_cbranch_scc1 .LBB0_264

.Lpeel_disp_ine:
	s_cmp_lg_u32 s65, -2
	s_cbranch_scc1 .LBB0_261
	s_add_u32 s0, s76, 0xfff80080
	s_addc_u32 s1, s77, -1
	s_and_b64 s[84:85], s[84:85], exec
	s_cselect_b32 vcc_hi, s22, s1
	s_cselect_b32 vcc_lo, s23, s0
	s_cselect_b32 s85, s49, s58
	s_cselect_b32 s84, s57, s51
	s_add_i32 s0, 0, 0x10000
	s_add_i32 s1, 0, 0x14000
	ds_read_b128 v[146:149], v175
	ds_read_b128 v[150:153], v175 offset:1024
	ds_read_b128 v[154:157], v175 offset:2048
	ds_read_b128 v[158:161], v175 offset:3072
	ds_read_b128 v[162:165], v224
	ds_read_b128 v[166:169], v224 offset:1024
	ds_read_b128 v[170:173], v224 offset:2048
	ds_read_b128 v[178:181], v224 offset:3072
	s_add_i32 m0, s21, 0xc000
	ds_read_b128 v[182:185], v177
	ds_read_b128 v[186:189], v177 offset:1024
	ds_read_b128 v[190:193], v177 offset:2048
	ds_read_b128 v[204:207], v177 offset:3072
	ds_read_b128 v[208:211], v177 offset:4096
	ds_read_b128 v[212:215], v177 offset:5120
	ds_read_b128 v[216:219], v177 offset:6144
	ds_read_b128 v[220:223], v177 offset:7168
	global_load_lds_dwordx4 v138, s[76:77]
	s_add_i32 m0, s21, 0xe000
	s_nop 0
	global_load_lds_dwordx4 v140, s[76:77]
	s_waitcnt vmcnt(8)
	s_waitcnt lgkmcnt(0)
	s_barrier
	s_waitcnt lgkmcnt(0)
	v_mfma_f32_16x16x32_bf16 v[126:129], v[146:149], v[182:185], 0
	v_mfma_f32_16x16x32_bf16 v[126:129], v[150:153], v[186:189], v[126:129]
	v_mfma_f32_16x16x32_bf16 v[122:125], v[158:161], v[186:189], 0
	v_mfma_f32_16x16x32_bf16 v[122:125], v[154:157], v[182:185], v[122:125]
	v_mfma_f32_16x16x32_bf16 v[118:121], v[162:165], v[182:185], 0
	v_mfma_f32_16x16x32_bf16 v[118:121], v[166:169], v[186:189], v[118:121]
	v_mfma_f32_16x16x32_bf16 v[114:117], v[178:181], v[186:189], 0
	v_mfma_f32_16x16x32_bf16 v[114:117], v[170:173], v[182:185], v[114:117]
	v_mfma_f32_16x16x32_bf16 v[98:101], v[170:173], v[190:193], 0
	v_mfma_f32_16x16x32_bf16 v[98:101], v[178:181], v[204:207], v[98:101]
	v_mfma_f32_16x16x32_bf16 v[102:105], v[166:169], v[204:207], 0
	v_mfma_f32_16x16x32_bf16 v[102:105], v[162:165], v[190:193], v[102:105]
	v_mfma_f32_16x16x32_bf16 v[106:109], v[154:157], v[190:193], 0
	v_mfma_f32_16x16x32_bf16 v[106:109], v[158:161], v[204:207], v[106:109]
	v_mfma_f32_16x16x32_bf16 v[110:113], v[150:153], v[204:207], 0
	v_mfma_f32_16x16x32_bf16 v[110:113], v[146:149], v[190:193], v[110:113]
	v_mfma_f32_16x16x32_bf16 v[94:97], v[146:149], v[208:211], 0
	v_mfma_f32_16x16x32_bf16 v[94:97], v[150:153], v[212:215], v[94:97]
	v_mfma_f32_16x16x32_bf16 v[90:93], v[158:161], v[212:215], 0
	v_mfma_f32_16x16x32_bf16 v[90:93], v[154:157], v[208:211], v[90:93]
	v_mfma_f32_16x16x32_bf16 v[86:89], v[162:165], v[208:211], 0
	v_mfma_f32_16x16x32_bf16 v[86:89], v[166:169], v[212:215], v[86:89]
	v_mfma_f32_16x16x32_bf16 v[82:85], v[178:181], v[212:215], 0
	v_mfma_f32_16x16x32_bf16 v[82:85], v[170:173], v[208:211], v[82:85]
	v_mfma_f32_16x16x32_bf16 v[66:69], v[170:173], v[216:219], 0
	v_mfma_f32_16x16x32_bf16 v[66:69], v[178:181], v[220:223], v[66:69]
	v_mfma_f32_16x16x32_bf16 v[70:73], v[166:169], v[220:223], 0
	v_mfma_f32_16x16x32_bf16 v[70:73], v[162:165], v[216:219], v[70:73]
	v_mfma_f32_16x16x32_bf16 v[74:77], v[154:157], v[216:219], 0
	v_mfma_f32_16x16x32_bf16 v[74:77], v[158:161], v[220:223], v[74:77]
	v_mfma_f32_16x16x32_bf16 v[78:81], v[150:153], v[220:223], 0
	v_mfma_f32_16x16x32_bf16 v[78:81], v[146:149], v[216:219], v[78:81]
	s_barrier
	s_add_i32 s0, s0, s20
	s_mov_b32 m0, s0
	ds_read_b128 v[182:185], v177 offset:16384
	ds_read_b128 v[186:189], v177 offset:17408
	ds_read_b128 v[190:193], v177 offset:18432
	ds_read_b128 v[204:207], v177 offset:19456
	ds_read_b128 v[208:211], v177 offset:20480
	ds_read_b128 v[212:215], v177 offset:21504
	ds_read_b128 v[216:219], v177 offset:22528
	ds_read_b128 v[220:223], v177 offset:23552
	global_load_lds_dwordx4 v132, s[84:85]
	s_add_i32 m0, s0, 0x2000
	s_add_u32 s94, s84, 0x80000
	s_addc_u32 s95, s85, 0
	s_add_i32 s0, s1, s20
	global_load_lds_dwordx4 v130, s[84:85]
	s_mov_b32 m0, s0
	s_nop 0
	global_load_lds_dwordx4 v132, s[94:95]
	s_add_i32 m0, s0, 0x2000
	s_nop 0
	global_load_lds_dwordx4 v130, s[94:95]
	s_mov_b32 m0, s21
	s_nop 0
	global_load_lds_dwordx4 v132, vcc
	s_mov_b32 m0, s26
	s_nop 0
	global_load_lds_dwordx4 v130, vcc
	s_waitcnt vmcnt(8)
	s_waitcnt lgkmcnt(0)
	s_barrier
	s_waitcnt lgkmcnt(0)
	v_mfma_f32_16x16x32_bf16 v[62:65], v[146:149], v[182:185], 0
	v_mfma_f32_16x16x32_bf16 v[62:65], v[150:153], v[186:189], v[62:65]
	v_mfma_f32_16x16x32_bf16 v[58:61], v[158:161], v[186:189], 0
	v_mfma_f32_16x16x32_bf16 v[58:61], v[154:157], v[182:185], v[58:61]
	v_mfma_f32_16x16x32_bf16 v[54:57], v[162:165], v[182:185], 0
	v_mfma_f32_16x16x32_bf16 v[54:57], v[166:169], v[186:189], v[54:57]
	v_mfma_f32_16x16x32_bf16 v[50:53], v[178:181], v[186:189], 0
	v_mfma_f32_16x16x32_bf16 v[50:53], v[170:173], v[182:185], v[50:53]
	v_mfma_f32_16x16x32_bf16 v[34:37], v[170:173], v[190:193], 0
	v_mfma_f32_16x16x32_bf16 v[34:37], v[178:181], v[204:207], v[34:37]
	v_mfma_f32_16x16x32_bf16 v[38:41], v[166:169], v[204:207], 0
	v_mfma_f32_16x16x32_bf16 v[38:41], v[162:165], v[190:193], v[38:41]
	v_mfma_f32_16x16x32_bf16 v[42:45], v[154:157], v[190:193], 0
	v_mfma_f32_16x16x32_bf16 v[42:45], v[158:161], v[204:207], v[42:45]
	v_mfma_f32_16x16x32_bf16 v[46:49], v[150:153], v[204:207], 0
	v_mfma_f32_16x16x32_bf16 v[46:49], v[146:149], v[190:193], v[46:49]
	v_mfma_f32_16x16x32_bf16 v[30:33], v[146:149], v[208:211], 0
	v_mfma_f32_16x16x32_bf16 v[30:33], v[150:153], v[212:215], v[30:33]
	v_mfma_f32_16x16x32_bf16 v[26:29], v[158:161], v[212:215], 0
	v_mfma_f32_16x16x32_bf16 v[26:29], v[154:157], v[208:211], v[26:29]
	v_mfma_f32_16x16x32_bf16 v[22:25], v[162:165], v[208:211], 0
	v_mfma_f32_16x16x32_bf16 v[22:25], v[166:169], v[212:215], v[22:25]
	v_mfma_f32_16x16x32_bf16 v[18:21], v[178:181], v[212:215], 0
	v_mfma_f32_16x16x32_bf16 v[18:21], v[170:173], v[208:211], v[18:21]
	v_mfma_f32_16x16x32_bf16 v[2:5], v[170:173], v[216:219], 0
	v_mfma_f32_16x16x32_bf16 v[2:5], v[178:181], v[220:223], v[2:5]
	v_mfma_f32_16x16x32_bf16 v[6:9], v[166:169], v[220:223], 0
	v_mfma_f32_16x16x32_bf16 v[6:9], v[162:165], v[216:219], v[6:9]
	v_mfma_f32_16x16x32_bf16 v[10:13], v[154:157], v[216:219], 0
	v_mfma_f32_16x16x32_bf16 v[10:13], v[158:161], v[220:223], v[10:13]
	v_mfma_f32_16x16x32_bf16 v[14:17], v[150:153], v[220:223], 0
	v_mfma_f32_16x16x32_bf16 v[14:17], v[146:149], v[216:219], v[14:17]
	s_barrier
	s_add_i32 s0, 0, 0x18000
	s_add_i32 s1, 0, 0x1c000
	ds_read_b128 v[146:149], v225
	ds_read_b128 v[150:153], v225 offset:1024
	ds_read_b128 v[154:157], v225 offset:2048
	ds_read_b128 v[158:161], v225 offset:3072
	ds_read_b128 v[162:165], v226
	ds_read_b128 v[166:169], v226 offset:1024
	ds_read_b128 v[170:173], v226 offset:2048
	ds_read_b128 v[178:181], v226 offset:3072
	s_add_u32 s94, vcc_lo, 0x80000
	s_addc_u32 s95, vcc_hi, 0
	s_mov_b32 m0, s27
	ds_read_b128 v[182:185], v177 offset:32768
	ds_read_b128 v[186:189], v177 offset:33792
	ds_read_b128 v[190:193], v177 offset:34816
	ds_read_b128 v[204:207], v177 offset:35840
	ds_read_b128 v[208:211], v177 offset:36864
	ds_read_b128 v[212:215], v177 offset:37888
	ds_read_b128 v[216:219], v177 offset:38912
	ds_read_b128 v[220:223], v177 offset:39936
	global_load_lds_dwordx4 v132, s[94:95]
	s_mov_b32 m0, s29
	s_nop 0
	global_load_lds_dwordx4 v130, s[94:95]
	s_waitcnt vmcnt(8)
	s_waitcnt lgkmcnt(0)
	s_barrier
	s_waitcnt lgkmcnt(0)
	v_mfma_f32_16x16x32_bf16 v[126:129], v[146:149], v[182:185], v[126:129]
	v_mfma_f32_16x16x32_bf16 v[126:129], v[150:153], v[186:189], v[126:129]
	v_mfma_f32_16x16x32_bf16 v[122:125], v[158:161], v[186:189], v[122:125]
	v_mfma_f32_16x16x32_bf16 v[122:125], v[154:157], v[182:185], v[122:125]
	v_mfma_f32_16x16x32_bf16 v[118:121], v[162:165], v[182:185], v[118:121]
	v_mfma_f32_16x16x32_bf16 v[118:121], v[166:169], v[186:189], v[118:121]
	v_mfma_f32_16x16x32_bf16 v[114:117], v[178:181], v[186:189], v[114:117]
	v_mfma_f32_16x16x32_bf16 v[114:117], v[170:173], v[182:185], v[114:117]
	v_mfma_f32_16x16x32_bf16 v[98:101], v[170:173], v[190:193], v[98:101]
	v_mfma_f32_16x16x32_bf16 v[98:101], v[178:181], v[204:207], v[98:101]
	v_mfma_f32_16x16x32_bf16 v[102:105], v[166:169], v[204:207], v[102:105]
	v_mfma_f32_16x16x32_bf16 v[102:105], v[162:165], v[190:193], v[102:105]
	v_mfma_f32_16x16x32_bf16 v[106:109], v[154:157], v[190:193], v[106:109]
	v_mfma_f32_16x16x32_bf16 v[106:109], v[158:161], v[204:207], v[106:109]
	v_mfma_f32_16x16x32_bf16 v[110:113], v[150:153], v[204:207], v[110:113]
	v_mfma_f32_16x16x32_bf16 v[110:113], v[146:149], v[190:193], v[110:113]
	v_mfma_f32_16x16x32_bf16 v[94:97], v[146:149], v[208:211], v[94:97]
	v_mfma_f32_16x16x32_bf16 v[94:97], v[150:153], v[212:215], v[94:97]
	v_mfma_f32_16x16x32_bf16 v[90:93], v[158:161], v[212:215], v[90:93]
	v_mfma_f32_16x16x32_bf16 v[90:93], v[154:157], v[208:211], v[90:93]
	v_mfma_f32_16x16x32_bf16 v[86:89], v[162:165], v[208:211], v[86:89]
	v_mfma_f32_16x16x32_bf16 v[86:89], v[166:169], v[212:215], v[86:89]
	v_mfma_f32_16x16x32_bf16 v[82:85], v[178:181], v[212:215], v[82:85]
	v_mfma_f32_16x16x32_bf16 v[82:85], v[170:173], v[208:211], v[82:85]
	v_mfma_f32_16x16x32_bf16 v[66:69], v[170:173], v[216:219], v[66:69]
	v_mfma_f32_16x16x32_bf16 v[66:69], v[178:181], v[220:223], v[66:69]
	v_mfma_f32_16x16x32_bf16 v[70:73], v[166:169], v[220:223], v[70:73]
	v_mfma_f32_16x16x32_bf16 v[70:73], v[162:165], v[216:219], v[70:73]
	v_mfma_f32_16x16x32_bf16 v[74:77], v[154:157], v[216:219], v[74:77]
	v_mfma_f32_16x16x32_bf16 v[74:77], v[158:161], v[220:223], v[74:77]
	v_mfma_f32_16x16x32_bf16 v[78:81], v[150:153], v[220:223], v[78:81]
	v_mfma_f32_16x16x32_bf16 v[78:81], v[146:149], v[216:219], v[78:81]
	s_barrier
	s_add_u32 s98, s84, 0x80
	s_addc_u32 s99, s85, 0
	s_add_u32 s100, vcc_lo, 0x80
	s_addc_u32 s101, vcc_hi, 0
	s_add_i32 s0, s0, s20
	s_mov_b32 m0, s0
	ds_read_b128 v[182:185], v177 offset:49152
	ds_read_b128 v[186:189], v177 offset:50176
	ds_read_b128 v[190:193], v177 offset:51200
	ds_read_b128 v[204:207], v177 offset:52224
	ds_read_b128 v[208:211], v177 offset:53248
	ds_read_b128 v[212:215], v177 offset:54272
	ds_read_b128 v[216:219], v177 offset:55296
	ds_read_b128 v[220:223], v177 offset:56320
	global_load_lds_dwordx4 v132, s[98:99]
	s_add_i32 m0, s0, 0x2000
	s_add_u32 s84, s84, 0x80080
	s_addc_u32 s85, s85, 0
	s_add_i32 s0, s1, s20
	global_load_lds_dwordx4 v130, s[98:99]
	s_mov_b32 m0, s0
	s_nop 0
	global_load_lds_dwordx4 v132, s[84:85]
	s_add_i32 m0, s0, 0x2000
	s_nop 0
	global_load_lds_dwordx4 v130, s[84:85]
	s_mov_b32 m0, s40
	s_nop 0
	global_load_lds_dwordx4 v132, s[100:101]
	s_mov_b32 m0, s41
	s_nop 0
	global_load_lds_dwordx4 v130, s[100:101]
	s_waitcnt vmcnt(8)
	s_waitcnt lgkmcnt(0)
	s_barrier
	s_waitcnt lgkmcnt(0)
	v_mfma_f32_16x16x32_bf16 v[62:65], v[146:149], v[182:185], v[62:65]
	v_mfma_f32_16x16x32_bf16 v[62:65], v[150:153], v[186:189], v[62:65]
	v_mfma_f32_16x16x32_bf16 v[58:61], v[158:161], v[186:189], v[58:61]
	v_mfma_f32_16x16x32_bf16 v[58:61], v[154:157], v[182:185], v[58:61]
	v_mfma_f32_16x16x32_bf16 v[54:57], v[162:165], v[182:185], v[54:57]
	v_mfma_f32_16x16x32_bf16 v[54:57], v[166:169], v[186:189], v[54:57]
	v_mfma_f32_16x16x32_bf16 v[50:53], v[178:181], v[186:189], v[50:53]
	v_mfma_f32_16x16x32_bf16 v[50:53], v[170:173], v[182:185], v[50:53]
	v_mfma_f32_16x16x32_bf16 v[34:37], v[170:173], v[190:193], v[34:37]
	v_mfma_f32_16x16x32_bf16 v[34:37], v[178:181], v[204:207], v[34:37]
	v_mfma_f32_16x16x32_bf16 v[38:41], v[166:169], v[204:207], v[38:41]
	v_mfma_f32_16x16x32_bf16 v[38:41], v[162:165], v[190:193], v[38:41]
	v_mfma_f32_16x16x32_bf16 v[42:45], v[154:157], v[190:193], v[42:45]
	v_mfma_f32_16x16x32_bf16 v[42:45], v[158:161], v[204:207], v[42:45]
	v_mfma_f32_16x16x32_bf16 v[46:49], v[150:153], v[204:207], v[46:49]
	v_mfma_f32_16x16x32_bf16 v[46:49], v[146:149], v[190:193], v[46:49]
	v_mfma_f32_16x16x32_bf16 v[30:33], v[146:149], v[208:211], v[30:33]
	v_mfma_f32_16x16x32_bf16 v[30:33], v[150:153], v[212:215], v[30:33]
	v_mfma_f32_16x16x32_bf16 v[26:29], v[158:161], v[212:215], v[26:29]
	v_mfma_f32_16x16x32_bf16 v[26:29], v[154:157], v[208:211], v[26:29]
	v_mfma_f32_16x16x32_bf16 v[22:25], v[162:165], v[208:211], v[22:25]
	v_mfma_f32_16x16x32_bf16 v[22:25], v[166:169], v[212:215], v[22:25]
	v_mfma_f32_16x16x32_bf16 v[18:21], v[178:181], v[212:215], v[18:21]
	v_mfma_f32_16x16x32_bf16 v[18:21], v[170:173], v[208:211], v[18:21]
	v_mfma_f32_16x16x32_bf16 v[2:5], v[170:173], v[216:219], v[2:5]
	v_mfma_f32_16x16x32_bf16 v[2:5], v[178:181], v[220:223], v[2:5]
	v_mfma_f32_16x16x32_bf16 v[6:9], v[166:169], v[220:223], v[6:9]
	v_mfma_f32_16x16x32_bf16 v[6:9], v[162:165], v[216:219], v[6:9]
	v_mfma_f32_16x16x32_bf16 v[10:13], v[154:157], v[216:219], v[10:13]
	v_mfma_f32_16x16x32_bf16 v[10:13], v[158:161], v[220:223], v[10:13]
	v_mfma_f32_16x16x32_bf16 v[14:17], v[150:153], v[220:223], v[14:17]
	v_mfma_f32_16x16x32_bf16 v[14:17], v[146:149], v[216:219], v[14:17]
	s_barrier
	s_add_i32 s65, s65, 2
	s_add_u32 s76, s76, 0x100
	s_addc_u32 s77, s77, 0
	s_add_u32 s51, s51, 0x100
	s_addc_u32 s58, s58, 0
	s_cmp_gt_u32 s65, 29
	s_cbranch_scc1 .LBB0_264
	s_branch .LBB0_262

.LBB0_284:
	s_ashr_i32 s49, s48, 31
	s_lshl_b64 s[22:23], s[48:49], 20
	s_add_u32 s50, s79, s22
	s_addc_u32 s51, s28, s23
	s_and_b64 s[22:23], s[4:5], exec
	s_cselect_b32 s21, s51, s77
	s_cselect_b32 s22, s50, s76
	s_ashr_i32 s39, s38, 31
	s_lshl_b64 s[62:63], s[38:39], 20
	s_add_u32 s62, s29, s62
	s_addc_u32 s63, s31, s63
	s_and_b64 s[64:65], s[4:5], exec
	s_cselect_b32 s23, s63, s71
	s_cselect_b32 s39, s62, s70
	s_ashr_i32 s7, s6, 31
	s_lshl_b32 s64, s40, 8
	s_lshl_b64 vcc, s[6:7], 10
	s_ashr_i32 s0, s6, 5
	s_ashr_i32 s65, s64, 31
	s_add_u32 s76, s76, 0x80080
	v_lshl_add_u64 v[2:3], s[64:65], 2, v[166:167]
	v_mov_b32_e32 v4, 0x5800
	s_addc_u32 s77, s77, 0
	v_lshl_add_u64 v[130:131], v[168:169], 0, vcc
	v_mad_i64_i32 v[132:133], vcc, s0, v4, v[2:3]
	s_add_u32 s7, s70, 0x100
	s_addc_u32 s41, s71, 0
	s_mov_b32 s43, -2
	v_add_u32_e32 v220, 0x10000, v1
	v_add_u32_e32 v221, 0x14000, v1
	v_add_u32_e32 v224, 0x18000, v1
	v_add_u32_e32 v225, 0x1c000, v1
	s_branch .LBB0_286
.LBB0_285:
	s_add_u32 s0, s76, 0xfff80080
	s_addc_u32 s1, s77, -1
	s_and_b64 s[70:71], s[70:71], exec
	s_cselect_b32 vcc_hi, s21, s1
	s_cselect_b32 vcc_lo, s22, s0
	s_cselect_b32 s71, s23, s41
	s_cselect_b32 s70, s39, s7
	s_add_i32 s0, 0, 0x10000
	s_add_i32 s1, 0, 0x14000
	ds_read_b128 v[134:137], v220
	ds_read_b128 v[138:141], v220 offset:1024
	ds_read_b128 v[142:145], v220 offset:2048
	ds_read_b128 v[146:149], v220 offset:3072
	ds_read_b128 v[150:153], v221
	ds_read_b128 v[154:157], v221 offset:1024
	ds_read_b128 v[158:161], v221 offset:2048
	ds_read_b128 v[174:177], v221 offset:3072
	s_add_i32 m0, s67, 0xc000
	ds_read_b128 v[178:181], v222
	ds_read_b128 v[182:185], v222 offset:1024
	ds_read_b128 v[186:189], v222 offset:2048
	ds_read_b128 v[190:193], v222 offset:3072
	ds_read_b128 v[204:207], v222 offset:4096
	ds_read_b128 v[208:211], v222 offset:5120
	ds_read_b128 v[212:215], v222 offset:6144
	ds_read_b128 v[216:219], v222 offset:7168
	global_load_lds_dwordx4 v170, s[76:77]
	s_add_i32 m0, s67, 0xe000
	s_nop 0
	global_load_lds_dwordx4 v172, s[76:77]
	s_waitcnt vmcnt(8)
	s_waitcnt lgkmcnt(0)
	s_barrier
	s_waitcnt lgkmcnt(0)
	v_mfma_f32_16x16x32_bf16 v[126:129], v[134:137], v[178:181], v[126:129]
	v_mfma_f32_16x16x32_bf16 v[126:129], v[138:141], v[182:185], v[126:129]
	v_mfma_f32_16x16x32_bf16 v[122:125], v[146:149], v[182:185], v[122:125]
	v_mfma_f32_16x16x32_bf16 v[122:125], v[142:145], v[178:181], v[122:125]
	v_mfma_f32_16x16x32_bf16 v[118:121], v[150:153], v[178:181], v[118:121]
	v_mfma_f32_16x16x32_bf16 v[118:121], v[154:157], v[182:185], v[118:121]
	v_mfma_f32_16x16x32_bf16 v[114:117], v[174:177], v[182:185], v[114:117]
	v_mfma_f32_16x16x32_bf16 v[114:117], v[158:161], v[178:181], v[114:117]
	v_mfma_f32_16x16x32_bf16 v[98:101], v[158:161], v[186:189], v[98:101]
	v_mfma_f32_16x16x32_bf16 v[98:101], v[174:177], v[190:193], v[98:101]
	v_mfma_f32_16x16x32_bf16 v[102:105], v[154:157], v[190:193], v[102:105]
	v_mfma_f32_16x16x32_bf16 v[102:105], v[150:153], v[186:189], v[102:105]
	v_mfma_f32_16x16x32_bf16 v[106:109], v[142:145], v[186:189], v[106:109]
	v_mfma_f32_16x16x32_bf16 v[106:109], v[146:149], v[190:193], v[106:109]
	v_mfma_f32_16x16x32_bf16 v[110:113], v[138:141], v[190:193], v[110:113]
	v_mfma_f32_16x16x32_bf16 v[110:113], v[134:137], v[186:189], v[110:113]
	v_mfma_f32_16x16x32_bf16 v[94:97], v[134:137], v[204:207], v[94:97]
	v_mfma_f32_16x16x32_bf16 v[94:97], v[138:141], v[208:211], v[94:97]
	v_mfma_f32_16x16x32_bf16 v[90:93], v[146:149], v[208:211], v[90:93]
	v_mfma_f32_16x16x32_bf16 v[90:93], v[142:145], v[204:207], v[90:93]
	v_mfma_f32_16x16x32_bf16 v[86:89], v[150:153], v[204:207], v[86:89]
	v_mfma_f32_16x16x32_bf16 v[86:89], v[154:157], v[208:211], v[86:89]
	v_mfma_f32_16x16x32_bf16 v[82:85], v[174:177], v[208:211], v[82:85]
	v_mfma_f32_16x16x32_bf16 v[82:85], v[158:161], v[204:207], v[82:85]
	v_mfma_f32_16x16x32_bf16 v[66:69], v[158:161], v[212:215], v[66:69]
	v_mfma_f32_16x16x32_bf16 v[66:69], v[174:177], v[216:219], v[66:69]
	v_mfma_f32_16x16x32_bf16 v[70:73], v[154:157], v[216:219], v[70:73]
	v_mfma_f32_16x16x32_bf16 v[70:73], v[150:153], v[212:215], v[70:73]
	v_mfma_f32_16x16x32_bf16 v[74:77], v[142:145], v[212:215], v[74:77]
	v_mfma_f32_16x16x32_bf16 v[74:77], v[146:149], v[216:219], v[74:77]
	v_mfma_f32_16x16x32_bf16 v[78:81], v[138:141], v[216:219], v[78:81]
	v_mfma_f32_16x16x32_bf16 v[78:81], v[134:137], v[212:215], v[78:81]
	s_barrier
	s_add_i32 s0, s0, s54
	s_mov_b32 m0, s0
	ds_read_b128 v[178:181], v222 offset:16384
	ds_read_b128 v[182:185], v222 offset:17408
	ds_read_b128 v[186:189], v222 offset:18432
	ds_read_b128 v[190:193], v222 offset:19456
	ds_read_b128 v[204:207], v222 offset:20480
	ds_read_b128 v[208:211], v222 offset:21504
	ds_read_b128 v[212:215], v222 offset:22528
	ds_read_b128 v[216:219], v222 offset:23552
	global_load_lds_dwordx4 v164, s[70:71]
	s_add_i32 m0, s0, 0x2000
	s_add_u32 s44, s70, 0x80000
	s_addc_u32 s45, s71, 0
	s_add_i32 s0, s1, s54
	global_load_lds_dwordx4 v162, s[70:71]
	s_mov_b32 m0, s0
	s_nop 0
	global_load_lds_dwordx4 v164, s[44:45]
	s_add_i32 m0, s0, 0x2000
	s_nop 0
	global_load_lds_dwordx4 v162, s[44:45]
	s_mov_b32 m0, s67
	s_nop 0
	global_load_lds_dwordx4 v164, vcc
	s_mov_b32 m0, s68
	s_nop 0
	global_load_lds_dwordx4 v162, vcc
	s_waitcnt vmcnt(8)
	s_waitcnt lgkmcnt(0)
	s_barrier
	s_waitcnt lgkmcnt(0)
	v_mfma_f32_16x16x32_bf16 v[62:65], v[134:137], v[178:181], v[62:65]
	v_mfma_f32_16x16x32_bf16 v[62:65], v[138:141], v[182:185], v[62:65]
	v_mfma_f32_16x16x32_bf16 v[58:61], v[146:149], v[182:185], v[58:61]
	v_mfma_f32_16x16x32_bf16 v[58:61], v[142:145], v[178:181], v[58:61]
	v_mfma_f32_16x16x32_bf16 v[54:57], v[150:153], v[178:181], v[54:57]
	v_mfma_f32_16x16x32_bf16 v[54:57], v[154:157], v[182:185], v[54:57]
	v_mfma_f32_16x16x32_bf16 v[50:53], v[174:177], v[182:185], v[50:53]
	v_mfma_f32_16x16x32_bf16 v[50:53], v[158:161], v[178:181], v[50:53]
	v_mfma_f32_16x16x32_bf16 v[34:37], v[158:161], v[186:189], v[34:37]
	v_mfma_f32_16x16x32_bf16 v[34:37], v[174:177], v[190:193], v[34:37]
	v_mfma_f32_16x16x32_bf16 v[38:41], v[154:157], v[190:193], v[38:41]
	v_mfma_f32_16x16x32_bf16 v[38:41], v[150:153], v[186:189], v[38:41]
	v_mfma_f32_16x16x32_bf16 v[42:45], v[142:145], v[186:189], v[42:45]
	v_mfma_f32_16x16x32_bf16 v[42:45], v[146:149], v[190:193], v[42:45]
	v_mfma_f32_16x16x32_bf16 v[46:49], v[138:141], v[190:193], v[46:49]
	v_mfma_f32_16x16x32_bf16 v[46:49], v[134:137], v[186:189], v[46:49]
	v_mfma_f32_16x16x32_bf16 v[30:33], v[134:137], v[204:207], v[30:33]
	v_mfma_f32_16x16x32_bf16 v[30:33], v[138:141], v[208:211], v[30:33]
	v_mfma_f32_16x16x32_bf16 v[26:29], v[146:149], v[208:211], v[26:29]
	v_mfma_f32_16x16x32_bf16 v[26:29], v[142:145], v[204:207], v[26:29]
	v_mfma_f32_16x16x32_bf16 v[22:25], v[150:153], v[204:207], v[22:25]
	v_mfma_f32_16x16x32_bf16 v[22:25], v[154:157], v[208:211], v[22:25]
	v_mfma_f32_16x16x32_bf16 v[18:21], v[174:177], v[208:211], v[18:21]
	v_mfma_f32_16x16x32_bf16 v[18:21], v[158:161], v[204:207], v[18:21]
	v_mfma_f32_16x16x32_bf16 v[2:5], v[158:161], v[212:215], v[2:5]
	v_mfma_f32_16x16x32_bf16 v[2:5], v[174:177], v[216:219], v[2:5]
	v_mfma_f32_16x16x32_bf16 v[6:9], v[154:157], v[216:219], v[6:9]
	v_mfma_f32_16x16x32_bf16 v[6:9], v[150:153], v[212:215], v[6:9]
	v_mfma_f32_16x16x32_bf16 v[10:13], v[142:145], v[212:215], v[10:13]
	v_mfma_f32_16x16x32_bf16 v[10:13], v[146:149], v[216:219], v[10:13]
	v_mfma_f32_16x16x32_bf16 v[14:17], v[138:141], v[216:219], v[14:17]
	v_mfma_f32_16x16x32_bf16 v[14:17], v[134:137], v[212:215], v[14:17]
	s_barrier
	s_add_i32 s0, 0, 0x18000
	s_add_i32 s1, 0, 0x1c000
	ds_read_b128 v[134:137], v224
	ds_read_b128 v[138:141], v224 offset:1024
	ds_read_b128 v[142:145], v224 offset:2048
	ds_read_b128 v[146:149], v224 offset:3072
	ds_read_b128 v[150:153], v225
	ds_read_b128 v[154:157], v225 offset:1024
	ds_read_b128 v[158:161], v225 offset:2048
	ds_read_b128 v[174:177], v225 offset:3072
	s_add_u32 s44, vcc_lo, 0x80000
	s_addc_u32 s45, vcc_hi, 0
	s_mov_b32 m0, s8
	ds_read_b128 v[178:181], v222 offset:32768
	ds_read_b128 v[182:185], v222 offset:33792
	ds_read_b128 v[186:189], v222 offset:34816
	ds_read_b128 v[190:193], v222 offset:35840
	ds_read_b128 v[204:207], v222 offset:36864
	ds_read_b128 v[208:211], v222 offset:37888
	ds_read_b128 v[212:215], v222 offset:38912
	ds_read_b128 v[216:219], v222 offset:39936
	global_load_lds_dwordx4 v164, s[44:45]
	s_mov_b32 m0, s9
	s_nop 0
	global_load_lds_dwordx4 v162, s[44:45]
	s_waitcnt vmcnt(8)
	s_waitcnt lgkmcnt(0)
	s_barrier
	s_waitcnt lgkmcnt(0)
	v_mfma_f32_16x16x32_bf16 v[126:129], v[134:137], v[178:181], v[126:129]
	v_mfma_f32_16x16x32_bf16 v[126:129], v[138:141], v[182:185], v[126:129]
	v_mfma_f32_16x16x32_bf16 v[122:125], v[146:149], v[182:185], v[122:125]
	v_mfma_f32_16x16x32_bf16 v[122:125], v[142:145], v[178:181], v[122:125]
	v_mfma_f32_16x16x32_bf16 v[118:121], v[150:153], v[178:181], v[118:121]
	v_mfma_f32_16x16x32_bf16 v[118:121], v[154:157], v[182:185], v[118:121]
	v_mfma_f32_16x16x32_bf16 v[114:117], v[174:177], v[182:185], v[114:117]
	v_mfma_f32_16x16x32_bf16 v[114:117], v[158:161], v[178:181], v[114:117]
	v_mfma_f32_16x16x32_bf16 v[98:101], v[158:161], v[186:189], v[98:101]
	v_mfma_f32_16x16x32_bf16 v[98:101], v[174:177], v[190:193], v[98:101]
	v_mfma_f32_16x16x32_bf16 v[102:105], v[154:157], v[190:193], v[102:105]
	v_mfma_f32_16x16x32_bf16 v[102:105], v[150:153], v[186:189], v[102:105]
	v_mfma_f32_16x16x32_bf16 v[106:109], v[142:145], v[186:189], v[106:109]
	v_mfma_f32_16x16x32_bf16 v[106:109], v[146:149], v[190:193], v[106:109]
	v_mfma_f32_16x16x32_bf16 v[110:113], v[138:141], v[190:193], v[110:113]
	v_mfma_f32_16x16x32_bf16 v[110:113], v[134:137], v[186:189], v[110:113]
	v_mfma_f32_16x16x32_bf16 v[94:97], v[134:137], v[204:207], v[94:97]
	v_mfma_f32_16x16x32_bf16 v[94:97], v[138:141], v[208:211], v[94:97]
	v_mfma_f32_16x16x32_bf16 v[90:93], v[146:149], v[208:211], v[90:93]
	v_mfma_f32_16x16x32_bf16 v[90:93], v[142:145], v[204:207], v[90:93]
	v_mfma_f32_16x16x32_bf16 v[86:89], v[150:153], v[204:207], v[86:89]
	v_mfma_f32_16x16x32_bf16 v[86:89], v[154:157], v[208:211], v[86:89]
	v_mfma_f32_16x16x32_bf16 v[82:85], v[174:177], v[208:211], v[82:85]
	v_mfma_f32_16x16x32_bf16 v[82:85], v[158:161], v[204:207], v[82:85]
	v_mfma_f32_16x16x32_bf16 v[66:69], v[158:161], v[212:215], v[66:69]
	v_mfma_f32_16x16x32_bf16 v[66:69], v[174:177], v[216:219], v[66:69]
	v_mfma_f32_16x16x32_bf16 v[70:73], v[154:157], v[216:219], v[70:73]
	v_mfma_f32_16x16x32_bf16 v[70:73], v[150:153], v[212:215], v[70:73]
	v_mfma_f32_16x16x32_bf16 v[74:77], v[142:145], v[212:215], v[74:77]
	v_mfma_f32_16x16x32_bf16 v[74:77], v[146:149], v[216:219], v[74:77]
	v_mfma_f32_16x16x32_bf16 v[78:81], v[138:141], v[216:219], v[78:81]
	v_mfma_f32_16x16x32_bf16 v[78:81], v[134:137], v[212:215], v[78:81]
	s_barrier
	s_add_u32 s98, s70, 0x80
	s_addc_u32 s99, s71, 0
	s_add_u32 s100, vcc_lo, 0x80
	s_addc_u32 s101, vcc_hi, 0
	s_add_i32 s0, s0, s54
	s_mov_b32 m0, s0
	ds_read_b128 v[178:181], v222 offset:49152
	ds_read_b128 v[182:185], v222 offset:50176
	ds_read_b128 v[186:189], v222 offset:51200
	ds_read_b128 v[190:193], v222 offset:52224
	ds_read_b128 v[204:207], v222 offset:53248
	ds_read_b128 v[208:211], v222 offset:54272
	ds_read_b128 v[212:215], v222 offset:55296
	ds_read_b128 v[216:219], v222 offset:56320
	global_load_lds_dwordx4 v164, s[98:99]
	s_add_i32 m0, s0, 0x2000
	s_add_u32 s44, s70, 0x80080
	s_addc_u32 s45, s71, 0
	s_add_i32 s0, s1, s54
	global_load_lds_dwordx4 v162, s[98:99]
	s_mov_b32 m0, s0
	s_nop 0
	global_load_lds_dwordx4 v164, s[44:45]
	s_add_i32 m0, s0, 0x2000
	s_nop 0
	global_load_lds_dwordx4 v162, s[44:45]
	s_mov_b32 m0, s27
	s_nop 0
	global_load_lds_dwordx4 v164, s[100:101]
	s_mov_b32 m0, s26
	s_nop 0
	global_load_lds_dwordx4 v162, s[100:101]
	s_waitcnt vmcnt(8)
	s_waitcnt lgkmcnt(0)
	s_barrier
	s_waitcnt lgkmcnt(0)
	v_mfma_f32_16x16x32_bf16 v[62:65], v[134:137], v[178:181], v[62:65]
	v_mfma_f32_16x16x32_bf16 v[62:65], v[138:141], v[182:185], v[62:65]
	v_mfma_f32_16x16x32_bf16 v[58:61], v[146:149], v[182:185], v[58:61]
	v_mfma_f32_16x16x32_bf16 v[58:61], v[142:145], v[178:181], v[58:61]
	v_mfma_f32_16x16x32_bf16 v[54:57], v[150:153], v[178:181], v[54:57]
	v_mfma_f32_16x16x32_bf16 v[54:57], v[154:157], v[182:185], v[54:57]
	v_mfma_f32_16x16x32_bf16 v[50:53], v[174:177], v[182:185], v[50:53]
	v_mfma_f32_16x16x32_bf16 v[50:53], v[158:161], v[178:181], v[50:53]
	v_mfma_f32_16x16x32_bf16 v[34:37], v[158:161], v[186:189], v[34:37]
	v_mfma_f32_16x16x32_bf16 v[34:37], v[174:177], v[190:193], v[34:37]
	v_mfma_f32_16x16x32_bf16 v[38:41], v[154:157], v[190:193], v[38:41]
	v_mfma_f32_16x16x32_bf16 v[38:41], v[150:153], v[186:189], v[38:41]
	v_mfma_f32_16x16x32_bf16 v[42:45], v[142:145], v[186:189], v[42:45]
	v_mfma_f32_16x16x32_bf16 v[42:45], v[146:149], v[190:193], v[42:45]
	v_mfma_f32_16x16x32_bf16 v[46:49], v[138:141], v[190:193], v[46:49]
	v_mfma_f32_16x16x32_bf16 v[46:49], v[134:137], v[186:189], v[46:49]
	v_mfma_f32_16x16x32_bf16 v[30:33], v[134:137], v[204:207], v[30:33]
	v_mfma_f32_16x16x32_bf16 v[30:33], v[138:141], v[208:211], v[30:33]
	v_mfma_f32_16x16x32_bf16 v[26:29], v[146:149], v[208:211], v[26:29]
	v_mfma_f32_16x16x32_bf16 v[26:29], v[142:145], v[204:207], v[26:29]
	v_mfma_f32_16x16x32_bf16 v[22:25], v[150:153], v[204:207], v[22:25]
	v_mfma_f32_16x16x32_bf16 v[22:25], v[154:157], v[208:211], v[22:25]
	v_mfma_f32_16x16x32_bf16 v[18:21], v[174:177], v[208:211], v[18:21]
	v_mfma_f32_16x16x32_bf16 v[18:21], v[158:161], v[204:207], v[18:21]
	v_mfma_f32_16x16x32_bf16 v[2:5], v[158:161], v[212:215], v[2:5]
	v_mfma_f32_16x16x32_bf16 v[2:5], v[174:177], v[216:219], v[2:5]
	v_mfma_f32_16x16x32_bf16 v[6:9], v[154:157], v[216:219], v[6:9]
	v_mfma_f32_16x16x32_bf16 v[6:9], v[150:153], v[212:215], v[6:9]
	v_mfma_f32_16x16x32_bf16 v[10:13], v[142:145], v[212:215], v[10:13]
	v_mfma_f32_16x16x32_bf16 v[10:13], v[146:149], v[216:219], v[10:13]
	v_mfma_f32_16x16x32_bf16 v[14:17], v[138:141], v[216:219], v[14:17]
	v_mfma_f32_16x16x32_bf16 v[14:17], v[134:137], v[212:215], v[14:17]
	s_barrier
	s_add_i32 s43, s43, 2
	s_add_u32 s76, s76, 0x100
	s_addc_u32 s77, s77, 0
	s_add_u32 s7, s7, 0x100
	s_addc_u32 s41, s41, 0
	s_cmp_gt_u32 s43, 29
	s_cbranch_scc1 .LBB0_288

.Lpeel_disp_ino:
	s_cmp_lg_u32 s43, -2
	s_cbranch_scc1 .LBB0_285
	s_add_u32 s0, s76, 0xfff80080
	s_addc_u32 s1, s77, -1
	s_and_b64 s[70:71], s[70:71], exec
	s_cselect_b32 vcc_hi, s21, s1
	s_cselect_b32 vcc_lo, s22, s0
	s_cselect_b32 s71, s23, s41
	s_cselect_b32 s70, s39, s7
	s_add_i32 s0, 0, 0x10000
	s_add_i32 s1, 0, 0x14000
	ds_read_b128 v[134:137], v220
	ds_read_b128 v[138:141], v220 offset:1024
	ds_read_b128 v[142:145], v220 offset:2048
	ds_read_b128 v[146:149], v220 offset:3072
	ds_read_b128 v[150:153], v221
	ds_read_b128 v[154:157], v221 offset:1024
	ds_read_b128 v[158:161], v221 offset:2048
	ds_read_b128 v[174:177], v221 offset:3072
	s_add_i32 m0, s67, 0xc000
	ds_read_b128 v[178:181], v222
	ds_read_b128 v[182:185], v222 offset:1024
	ds_read_b128 v[186:189], v222 offset:2048
	ds_read_b128 v[190:193], v222 offset:3072
	ds_read_b128 v[204:207], v222 offset:4096
	ds_read_b128 v[208:211], v222 offset:5120
	ds_read_b128 v[212:215], v222 offset:6144
	ds_read_b128 v[216:219], v222 offset:7168
	global_load_lds_dwordx4 v170, s[76:77]
	s_add_i32 m0, s67, 0xe000
	s_nop 0
	global_load_lds_dwordx4 v172, s[76:77]
	s_waitcnt vmcnt(8)
	s_waitcnt lgkmcnt(0)
	s_barrier
	s_waitcnt lgkmcnt(0)
	v_mfma_f32_16x16x32_bf16 v[126:129], v[134:137], v[178:181], 0
	v_mfma_f32_16x16x32_bf16 v[126:129], v[138:141], v[182:185], v[126:129]
	v_mfma_f32_16x16x32_bf16 v[122:125], v[146:149], v[182:185], 0
	v_mfma_f32_16x16x32_bf16 v[122:125], v[142:145], v[178:181], v[122:125]
	v_mfma_f32_16x16x32_bf16 v[118:121], v[150:153], v[178:181], 0
	v_mfma_f32_16x16x32_bf16 v[118:121], v[154:157], v[182:185], v[118:121]
	v_mfma_f32_16x16x32_bf16 v[114:117], v[174:177], v[182:185], 0
	v_mfma_f32_16x16x32_bf16 v[114:117], v[158:161], v[178:181], v[114:117]
	v_mfma_f32_16x16x32_bf16 v[98:101], v[158:161], v[186:189], 0
	v_mfma_f32_16x16x32_bf16 v[98:101], v[174:177], v[190:193], v[98:101]
	v_mfma_f32_16x16x32_bf16 v[102:105], v[154:157], v[190:193], 0
	v_mfma_f32_16x16x32_bf16 v[102:105], v[150:153], v[186:189], v[102:105]
	v_mfma_f32_16x16x32_bf16 v[106:109], v[142:145], v[186:189], 0
	v_mfma_f32_16x16x32_bf16 v[106:109], v[146:149], v[190:193], v[106:109]
	v_mfma_f32_16x16x32_bf16 v[110:113], v[138:141], v[190:193], 0
	v_mfma_f32_16x16x32_bf16 v[110:113], v[134:137], v[186:189], v[110:113]
	v_mfma_f32_16x16x32_bf16 v[94:97], v[134:137], v[204:207], 0
	v_mfma_f32_16x16x32_bf16 v[94:97], v[138:141], v[208:211], v[94:97]
	v_mfma_f32_16x16x32_bf16 v[90:93], v[146:149], v[208:211], 0
	v_mfma_f32_16x16x32_bf16 v[90:93], v[142:145], v[204:207], v[90:93]
	v_mfma_f32_16x16x32_bf16 v[86:89], v[150:153], v[204:207], 0
	v_mfma_f32_16x16x32_bf16 v[86:89], v[154:157], v[208:211], v[86:89]
	v_mfma_f32_16x16x32_bf16 v[82:85], v[174:177], v[208:211], 0
	v_mfma_f32_16x16x32_bf16 v[82:85], v[158:161], v[204:207], v[82:85]
	v_mfma_f32_16x16x32_bf16 v[66:69], v[158:161], v[212:215], 0
	v_mfma_f32_16x16x32_bf16 v[66:69], v[174:177], v[216:219], v[66:69]
	v_mfma_f32_16x16x32_bf16 v[70:73], v[154:157], v[216:219], 0
	v_mfma_f32_16x16x32_bf16 v[70:73], v[150:153], v[212:215], v[70:73]
	v_mfma_f32_16x16x32_bf16 v[74:77], v[142:145], v[212:215], 0
	v_mfma_f32_16x16x32_bf16 v[74:77], v[146:149], v[216:219], v[74:77]
	v_mfma_f32_16x16x32_bf16 v[78:81], v[138:141], v[216:219], 0
	v_mfma_f32_16x16x32_bf16 v[78:81], v[134:137], v[212:215], v[78:81]
	s_barrier
	s_add_i32 s0, s0, s54
	s_mov_b32 m0, s0
	ds_read_b128 v[178:181], v222 offset:16384
	ds_read_b128 v[182:185], v222 offset:17408
	ds_read_b128 v[186:189], v222 offset:18432
	ds_read_b128 v[190:193], v222 offset:19456
	ds_read_b128 v[204:207], v222 offset:20480
	ds_read_b128 v[208:211], v222 offset:21504
	ds_read_b128 v[212:215], v222 offset:22528
	ds_read_b128 v[216:219], v222 offset:23552
	global_load_lds_dwordx4 v164, s[70:71]
	s_add_i32 m0, s0, 0x2000
	s_add_u32 s44, s70, 0x80000
	s_addc_u32 s45, s71, 0
	s_add_i32 s0, s1, s54
	global_load_lds_dwordx4 v162, s[70:71]
	s_mov_b32 m0, s0
	s_nop 0
	global_load_lds_dwordx4 v164, s[44:45]
	s_add_i32 m0, s0, 0x2000
	s_nop 0
	global_load_lds_dwordx4 v162, s[44:45]
	s_mov_b32 m0, s67
	s_nop 0
	global_load_lds_dwordx4 v164, vcc
	s_mov_b32 m0, s68
	s_nop 0
	global_load_lds_dwordx4 v162, vcc
	s_waitcnt vmcnt(8)
	s_waitcnt lgkmcnt(0)
	s_barrier
	s_waitcnt lgkmcnt(0)
	v_mfma_f32_16x16x32_bf16 v[62:65], v[134:137], v[178:181], 0
	v_mfma_f32_16x16x32_bf16 v[62:65], v[138:141], v[182:185], v[62:65]
	v_mfma_f32_16x16x32_bf16 v[58:61], v[146:149], v[182:185], 0
	v_mfma_f32_16x16x32_bf16 v[58:61], v[142:145], v[178:181], v[58:61]
	v_mfma_f32_16x16x32_bf16 v[54:57], v[150:153], v[178:181], 0
	v_mfma_f32_16x16x32_bf16 v[54:57], v[154:157], v[182:185], v[54:57]
	v_mfma_f32_16x16x32_bf16 v[50:53], v[174:177], v[182:185], 0
	v_mfma_f32_16x16x32_bf16 v[50:53], v[158:161], v[178:181], v[50:53]
	v_mfma_f32_16x16x32_bf16 v[34:37], v[158:161], v[186:189], 0
	v_mfma_f32_16x16x32_bf16 v[34:37], v[174:177], v[190:193], v[34:37]
	v_mfma_f32_16x16x32_bf16 v[38:41], v[154:157], v[190:193], 0
	v_mfma_f32_16x16x32_bf16 v[38:41], v[150:153], v[186:189], v[38:41]
	v_mfma_f32_16x16x32_bf16 v[42:45], v[142:145], v[186:189], 0
	v_mfma_f32_16x16x32_bf16 v[42:45], v[146:149], v[190:193], v[42:45]
	v_mfma_f32_16x16x32_bf16 v[46:49], v[138:141], v[190:193], 0
	v_mfma_f32_16x16x32_bf16 v[46:49], v[134:137], v[186:189], v[46:49]
	v_mfma_f32_16x16x32_bf16 v[30:33], v[134:137], v[204:207], 0
	v_mfma_f32_16x16x32_bf16 v[30:33], v[138:141], v[208:211], v[30:33]
	v_mfma_f32_16x16x32_bf16 v[26:29], v[146:149], v[208:211], 0
	v_mfma_f32_16x16x32_bf16 v[26:29], v[142:145], v[204:207], v[26:29]
	v_mfma_f32_16x16x32_bf16 v[22:25], v[150:153], v[204:207], 0
	v_mfma_f32_16x16x32_bf16 v[22:25], v[154:157], v[208:211], v[22:25]
	v_mfma_f32_16x16x32_bf16 v[18:21], v[174:177], v[208:211], 0
	v_mfma_f32_16x16x32_bf16 v[18:21], v[158:161], v[204:207], v[18:21]
	v_mfma_f32_16x16x32_bf16 v[2:5], v[158:161], v[212:215], 0
	v_mfma_f32_16x16x32_bf16 v[2:5], v[174:177], v[216:219], v[2:5]
	v_mfma_f32_16x16x32_bf16 v[6:9], v[154:157], v[216:219], 0
	v_mfma_f32_16x16x32_bf16 v[6:9], v[150:153], v[212:215], v[6:9]
	v_mfma_f32_16x16x32_bf16 v[10:13], v[142:145], v[212:215], 0
	v_mfma_f32_16x16x32_bf16 v[10:13], v[146:149], v[216:219], v[10:13]
	v_mfma_f32_16x16x32_bf16 v[14:17], v[138:141], v[216:219], 0
	v_mfma_f32_16x16x32_bf16 v[14:17], v[134:137], v[212:215], v[14:17]
	s_barrier
	s_add_i32 s0, 0, 0x18000
	s_add_i32 s1, 0, 0x1c000
	ds_read_b128 v[134:137], v224
	ds_read_b128 v[138:141], v224 offset:1024
	ds_read_b128 v[142:145], v224 offset:2048
	ds_read_b128 v[146:149], v224 offset:3072
	ds_read_b128 v[150:153], v225
	ds_read_b128 v[154:157], v225 offset:1024
	ds_read_b128 v[158:161], v225 offset:2048
	ds_read_b128 v[174:177], v225 offset:3072
	s_add_u32 s44, vcc_lo, 0x80000
	s_addc_u32 s45, vcc_hi, 0
	s_mov_b32 m0, s8
	ds_read_b128 v[178:181], v222 offset:32768
	ds_read_b128 v[182:185], v222 offset:33792
	ds_read_b128 v[186:189], v222 offset:34816
	ds_read_b128 v[190:193], v222 offset:35840
	ds_read_b128 v[204:207], v222 offset:36864
	ds_read_b128 v[208:211], v222 offset:37888
	ds_read_b128 v[212:215], v222 offset:38912
	ds_read_b128 v[216:219], v222 offset:39936
	global_load_lds_dwordx4 v164, s[44:45]
	s_mov_b32 m0, s9
	s_nop 0
	global_load_lds_dwordx4 v162, s[44:45]
	s_waitcnt vmcnt(8)
	s_waitcnt lgkmcnt(0)
	s_barrier
	s_waitcnt lgkmcnt(0)
	v_mfma_f32_16x16x32_bf16 v[126:129], v[134:137], v[178:181], v[126:129]
	v_mfma_f32_16x16x32_bf16 v[126:129], v[138:141], v[182:185], v[126:129]
	v_mfma_f32_16x16x32_bf16 v[122:125], v[146:149], v[182:185], v[122:125]
	v_mfma_f32_16x16x32_bf16 v[122:125], v[142:145], v[178:181], v[122:125]
	v_mfma_f32_16x16x32_bf16 v[118:121], v[150:153], v[178:181], v[118:121]
	v_mfma_f32_16x16x32_bf16 v[118:121], v[154:157], v[182:185], v[118:121]
	v_mfma_f32_16x16x32_bf16 v[114:117], v[174:177], v[182:185], v[114:117]
	v_mfma_f32_16x16x32_bf16 v[114:117], v[158:161], v[178:181], v[114:117]
	v_mfma_f32_16x16x32_bf16 v[98:101], v[158:161], v[186:189], v[98:101]
	v_mfma_f32_16x16x32_bf16 v[98:101], v[174:177], v[190:193], v[98:101]
	v_mfma_f32_16x16x32_bf16 v[102:105], v[154:157], v[190:193], v[102:105]
	v_mfma_f32_16x16x32_bf16 v[102:105], v[150:153], v[186:189], v[102:105]
	v_mfma_f32_16x16x32_bf16 v[106:109], v[142:145], v[186:189], v[106:109]
	v_mfma_f32_16x16x32_bf16 v[106:109], v[146:149], v[190:193], v[106:109]
	v_mfma_f32_16x16x32_bf16 v[110:113], v[138:141], v[190:193], v[110:113]
	v_mfma_f32_16x16x32_bf16 v[110:113], v[134:137], v[186:189], v[110:113]
	v_mfma_f32_16x16x32_bf16 v[94:97], v[134:137], v[204:207], v[94:97]
	v_mfma_f32_16x16x32_bf16 v[94:97], v[138:141], v[208:211], v[94:97]
	v_mfma_f32_16x16x32_bf16 v[90:93], v[146:149], v[208:211], v[90:93]
	v_mfma_f32_16x16x32_bf16 v[90:93], v[142:145], v[204:207], v[90:93]
	v_mfma_f32_16x16x32_bf16 v[86:89], v[150:153], v[204:207], v[86:89]
	v_mfma_f32_16x16x32_bf16 v[86:89], v[154:157], v[208:211], v[86:89]
	v_mfma_f32_16x16x32_bf16 v[82:85], v[174:177], v[208:211], v[82:85]
	v_mfma_f32_16x16x32_bf16 v[82:85], v[158:161], v[204:207], v[82:85]
	v_mfma_f32_16x16x32_bf16 v[66:69], v[158:161], v[212:215], v[66:69]
	v_mfma_f32_16x16x32_bf16 v[66:69], v[174:177], v[216:219], v[66:69]
	v_mfma_f32_16x16x32_bf16 v[70:73], v[154:157], v[216:219], v[70:73]
	v_mfma_f32_16x16x32_bf16 v[70:73], v[150:153], v[212:215], v[70:73]
	v_mfma_f32_16x16x32_bf16 v[74:77], v[142:145], v[212:215], v[74:77]
	v_mfma_f32_16x16x32_bf16 v[74:77], v[146:149], v[216:219], v[74:77]
	v_mfma_f32_16x16x32_bf16 v[78:81], v[138:141], v[216:219], v[78:81]
	v_mfma_f32_16x16x32_bf16 v[78:81], v[134:137], v[212:215], v[78:81]
	s_barrier
	s_add_u32 s98, s70, 0x80
	s_addc_u32 s99, s71, 0
	s_add_u32 s100, vcc_lo, 0x80
	s_addc_u32 s101, vcc_hi, 0
	s_add_i32 s0, s0, s54
	s_mov_b32 m0, s0
	ds_read_b128 v[178:181], v222 offset:49152
	ds_read_b128 v[182:185], v222 offset:50176
	ds_read_b128 v[186:189], v222 offset:51200
	ds_read_b128 v[190:193], v222 offset:52224
	ds_read_b128 v[204:207], v222 offset:53248
	ds_read_b128 v[208:211], v222 offset:54272
	ds_read_b128 v[212:215], v222 offset:55296
	ds_read_b128 v[216:219], v222 offset:56320
	global_load_lds_dwordx4 v164, s[98:99]
	s_add_i32 m0, s0, 0x2000
	s_add_u32 s44, s70, 0x80080
	s_addc_u32 s45, s71, 0
	s_add_i32 s0, s1, s54
	global_load_lds_dwordx4 v162, s[98:99]
	s_mov_b32 m0, s0
	s_nop 0
	global_load_lds_dwordx4 v164, s[44:45]
	s_add_i32 m0, s0, 0x2000
	s_nop 0
	global_load_lds_dwordx4 v162, s[44:45]
	s_mov_b32 m0, s27
	s_nop 0
	global_load_lds_dwordx4 v164, s[100:101]
	s_mov_b32 m0, s26
	s_nop 0
	global_load_lds_dwordx4 v162, s[100:101]
	s_waitcnt vmcnt(8)
	s_waitcnt lgkmcnt(0)
	s_barrier
	s_waitcnt lgkmcnt(0)
	v_mfma_f32_16x16x32_bf16 v[62:65], v[134:137], v[178:181], v[62:65]
	v_mfma_f32_16x16x32_bf16 v[62:65], v[138:141], v[182:185], v[62:65]
	v_mfma_f32_16x16x32_bf16 v[58:61], v[146:149], v[182:185], v[58:61]
	v_mfma_f32_16x16x32_bf16 v[58:61], v[142:145], v[178:181], v[58:61]
	v_mfma_f32_16x16x32_bf16 v[54:57], v[150:153], v[178:181], v[54:57]
	v_mfma_f32_16x16x32_bf16 v[54:57], v[154:157], v[182:185], v[54:57]
	v_mfma_f32_16x16x32_bf16 v[50:53], v[174:177], v[182:185], v[50:53]
	v_mfma_f32_16x16x32_bf16 v[50:53], v[158:161], v[178:181], v[50:53]
	v_mfma_f32_16x16x32_bf16 v[34:37], v[158:161], v[186:189], v[34:37]
	v_mfma_f32_16x16x32_bf16 v[34:37], v[174:177], v[190:193], v[34:37]
	v_mfma_f32_16x16x32_bf16 v[38:41], v[154:157], v[190:193], v[38:41]
	v_mfma_f32_16x16x32_bf16 v[38:41], v[150:153], v[186:189], v[38:41]
	v_mfma_f32_16x16x32_bf16 v[42:45], v[142:145], v[186:189], v[42:45]
	v_mfma_f32_16x16x32_bf16 v[42:45], v[146:149], v[190:193], v[42:45]
	v_mfma_f32_16x16x32_bf16 v[46:49], v[138:141], v[190:193], v[46:49]
	v_mfma_f32_16x16x32_bf16 v[46:49], v[134:137], v[186:189], v[46:49]
	v_mfma_f32_16x16x32_bf16 v[30:33], v[134:137], v[204:207], v[30:33]
	v_mfma_f32_16x16x32_bf16 v[30:33], v[138:141], v[208:211], v[30:33]
	v_mfma_f32_16x16x32_bf16 v[26:29], v[146:149], v[208:211], v[26:29]
	v_mfma_f32_16x16x32_bf16 v[26:29], v[142:145], v[204:207], v[26:29]
	v_mfma_f32_16x16x32_bf16 v[22:25], v[150:153], v[204:207], v[22:25]
	v_mfma_f32_16x16x32_bf16 v[22:25], v[154:157], v[208:211], v[22:25]
	v_mfma_f32_16x16x32_bf16 v[18:21], v[174:177], v[208:211], v[18:21]
	v_mfma_f32_16x16x32_bf16 v[18:21], v[158:161], v[204:207], v[18:21]
	v_mfma_f32_16x16x32_bf16 v[2:5], v[158:161], v[212:215], v[2:5]
	v_mfma_f32_16x16x32_bf16 v[2:5], v[174:177], v[216:219], v[2:5]
	v_mfma_f32_16x16x32_bf16 v[6:9], v[154:157], v[216:219], v[6:9]
	v_mfma_f32_16x16x32_bf16 v[6:9], v[150:153], v[212:215], v[6:9]
	v_mfma_f32_16x16x32_bf16 v[10:13], v[142:145], v[212:215], v[10:13]
	v_mfma_f32_16x16x32_bf16 v[10:13], v[146:149], v[216:219], v[10:13]
	v_mfma_f32_16x16x32_bf16 v[14:17], v[138:141], v[216:219], v[14:17]
	v_mfma_f32_16x16x32_bf16 v[14:17], v[134:137], v[212:215], v[14:17]
	s_barrier
	s_add_i32 s43, s43, 2
	s_add_u32 s76, s76, 0x100
	s_addc_u32 s77, s77, 0
	s_add_u32 s7, s7, 0x100
	s_addc_u32 s41, s41, 0
	s_cmp_gt_u32 s43, 29
	s_cbranch_scc1 .LBB0_288
	s_branch .LBB0_286

.LBB0_508:
	s_ashr_i32 s53, s52, 31
	s_lshl_b64 s[0:1], s[52:53], 20
	s_add_u32 s62, s20, s0
	s_addc_u32 s63, s21, s1
	s_and_b64 s[0:1], s[6:7], exec
	s_cselect_b32 s22, s63, s77
	s_cselect_b32 s23, s62, s76
	s_ashr_i32 s51, s50, 31
	s_lshl_b64 s[0:1], s[50:51], 20
	s_add_u32 s84, s26, s0
	s_addc_u32 s85, s27, s1
	s_and_b64 s[0:1], s[6:7], exec
	s_cselect_b32 s41, s85, s91
	s_cselect_b32 s44, s84, s90
	s_lshl_b32 s64, s57, 8
	s_ashr_i32 s65, s64, 31
	s_lshl_b64 s[0:1], s[64:65], 2
	s_ashr_i32 s18, s40, 5
	v_lshl_add_u64 v[2:3], v[206:207], 0, s[0:1]
	v_lshl_add_u64 v[4:5], v[208:209], 0, s[0:1]
	v_mad_i64_i32 v[70:71], s[0:1], s18, v235, v[2:3]
	s_add_u32 s51, s90, 0x100
	v_mad_i64_i32 v[72:73], s[0:1], s18, v235, v[4:5]
	s_addc_u32 s53, s91, 0
	s_mov_b32 s57, -2
	v_add_u32_e32 v218, 0x10000, v1
	v_add_u32_e32 v219, 0x14000, v1
	v_add_u32_e32 v220, 0x18000, v1
	v_add_u32_e32 v221, 0x1c000, v1
	s_branch .LBB0_510
.LBB0_509:
	s_add_u32 s90, s76, 0x100
	s_addc_u32 s91, s77, 0
	s_and_b64 s[0:1], s[70:71], exec
	s_cselect_b32 vcc_hi, s22, s91
	s_cselect_b32 vcc_lo, s23, s90
	s_cselect_b32 s71, s41, s53
	s_cselect_b32 s70, s44, s51
	s_add_i32 s0, 0, 0x10000
	s_add_i32 s18, 0, 0x14000
	ds_read_b128 v[78:81], v218
	ds_read_b128 v[90:93], v218 offset:1024
	ds_read_b128 v[102:105], v218 offset:2048
	ds_read_b128 v[114:117], v218 offset:3072
	ds_read_b128 v[126:129], v219
	ds_read_b128 v[134:137], v219 offset:1024
	ds_read_b128 v[142:145], v219 offset:2048
	ds_read_b128 v[154:157], v219 offset:3072
	s_add_i32 m0, s29, 0xc000
	ds_read_b128 v[158:161], v237
	ds_read_b128 v[162:165], v237 offset:1024
	ds_read_b128 v[166:169], v237 offset:2048
	ds_read_b128 v[178:181], v237 offset:3072
	ds_read_b128 v[182:185], v237 offset:4096
	ds_read_b128 v[186:189], v237 offset:5120
	ds_read_b128 v[190:193], v237 offset:6144
	ds_read_b128 v[214:217], v237 offset:7168
	global_load_lds_dwordx4 v210, s[76:77]
	s_add_i32 m0, s29, 0xe000
	s_nop 0
	global_load_lds_dwordx4 v212, s[76:77]
	s_waitcnt vmcnt(8)
	s_waitcnt lgkmcnt(0)
	s_barrier
	s_waitcnt lgkmcnt(0)
	v_mfma_f32_16x16x32_bf16 v[174:177], v[78:81], v[158:161], v[174:177]
	v_mfma_f32_16x16x32_bf16 v[174:177], v[90:93], v[162:165], v[174:177]
	v_mfma_f32_16x16x32_bf16 v[170:173], v[114:117], v[162:165], v[170:173]
	v_mfma_f32_16x16x32_bf16 v[170:173], v[102:105], v[158:161], v[170:173]
	v_mfma_f32_16x16x32_bf16 v[150:153], v[126:129], v[158:161], v[150:153]
	v_mfma_f32_16x16x32_bf16 v[150:153], v[134:137], v[162:165], v[150:153]
	v_mfma_f32_16x16x32_bf16 v[146:149], v[154:157], v[162:165], v[146:149]
	v_mfma_f32_16x16x32_bf16 v[146:149], v[142:145], v[158:161], v[146:149]
	v_mfma_f32_16x16x32_bf16 v[118:121], v[142:145], v[166:169], v[118:121]
	v_mfma_f32_16x16x32_bf16 v[118:121], v[154:157], v[178:181], v[118:121]
	v_mfma_f32_16x16x32_bf16 v[122:125], v[134:137], v[178:181], v[122:125]
	v_mfma_f32_16x16x32_bf16 v[122:125], v[126:129], v[166:169], v[122:125]
	v_mfma_f32_16x16x32_bf16 v[130:133], v[102:105], v[166:169], v[130:133]
	v_mfma_f32_16x16x32_bf16 v[130:133], v[114:117], v[178:181], v[130:133]
	v_mfma_f32_16x16x32_bf16 v[138:141], v[90:93], v[178:181], v[138:141]
	v_mfma_f32_16x16x32_bf16 v[138:141], v[78:81], v[166:169], v[138:141]
	v_mfma_f32_16x16x32_bf16 v[110:113], v[78:81], v[182:185], v[110:113]
	v_mfma_f32_16x16x32_bf16 v[110:113], v[90:93], v[186:189], v[110:113]
	v_mfma_f32_16x16x32_bf16 v[106:109], v[114:117], v[186:189], v[106:109]
	v_mfma_f32_16x16x32_bf16 v[106:109], v[102:105], v[182:185], v[106:109]
	v_mfma_f32_16x16x32_bf16 v[98:101], v[126:129], v[182:185], v[98:101]
	v_mfma_f32_16x16x32_bf16 v[98:101], v[134:137], v[186:189], v[98:101]
	v_mfma_f32_16x16x32_bf16 v[94:97], v[154:157], v[186:189], v[94:97]
	v_mfma_f32_16x16x32_bf16 v[94:97], v[142:145], v[182:185], v[94:97]
	v_mfma_f32_16x16x32_bf16 v[66:69], v[142:145], v[190:193], v[66:69]
	v_mfma_f32_16x16x32_bf16 v[66:69], v[154:157], v[214:217], v[66:69]
	v_mfma_f32_16x16x32_bf16 v[74:77], v[134:137], v[214:217], v[74:77]
	v_mfma_f32_16x16x32_bf16 v[74:77], v[126:129], v[190:193], v[74:77]
	v_mfma_f32_16x16x32_bf16 v[82:85], v[102:105], v[190:193], v[82:85]
	v_mfma_f32_16x16x32_bf16 v[82:85], v[114:117], v[214:217], v[82:85]
	v_mfma_f32_16x16x32_bf16 v[86:89], v[90:93], v[214:217], v[86:89]
	v_mfma_f32_16x16x32_bf16 v[86:89], v[78:81], v[190:193], v[86:89]
	s_barrier
	s_add_i32 s0, s0, s28
	s_mov_b32 m0, s0
	ds_read_b128 v[158:161], v237 offset:16384
	ds_read_b128 v[162:165], v237 offset:17408
	ds_read_b128 v[166:169], v237 offset:18432
	ds_read_b128 v[178:181], v237 offset:19456
	ds_read_b128 v[182:185], v237 offset:20480
	ds_read_b128 v[186:189], v237 offset:21504
	ds_read_b128 v[190:193], v237 offset:22528
	ds_read_b128 v[214:217], v237 offset:23552
	global_load_lds_dwordx4 v194, s[70:71]
	s_add_i32 m0, s0, 0x2000
	s_add_u32 s0, s70, 0x80000
	s_addc_u32 s1, s71, 0
	s_add_i32 s18, s18, s28
	global_load_lds_dwordx4 v204, s[70:71]
	s_mov_b32 m0, s18
	s_nop 0
	global_load_lds_dwordx4 v194, s[0:1]
	s_add_i32 m0, s18, 0x2000
	s_nop 0
	global_load_lds_dwordx4 v204, s[0:1]
	s_mov_b32 m0, s29
	s_nop 0
	global_load_lds_dwordx4 v194, vcc
	s_mov_b32 m0, s31
	s_nop 0
	global_load_lds_dwordx4 v204, vcc
	s_waitcnt vmcnt(8)
	s_waitcnt lgkmcnt(0)
	s_barrier
	s_waitcnt lgkmcnt(0)
	v_mfma_f32_16x16x32_bf16 v[62:65], v[78:81], v[158:161], v[62:65]
	v_mfma_f32_16x16x32_bf16 v[62:65], v[90:93], v[162:165], v[62:65]
	v_mfma_f32_16x16x32_bf16 v[58:61], v[114:117], v[162:165], v[58:61]
	v_mfma_f32_16x16x32_bf16 v[58:61], v[102:105], v[158:161], v[58:61]
	v_mfma_f32_16x16x32_bf16 v[54:57], v[126:129], v[158:161], v[54:57]
	v_mfma_f32_16x16x32_bf16 v[54:57], v[134:137], v[162:165], v[54:57]
	v_mfma_f32_16x16x32_bf16 v[50:53], v[154:157], v[162:165], v[50:53]
	v_mfma_f32_16x16x32_bf16 v[50:53], v[142:145], v[158:161], v[50:53]
	v_mfma_f32_16x16x32_bf16 v[34:37], v[142:145], v[166:169], v[34:37]
	v_mfma_f32_16x16x32_bf16 v[34:37], v[154:157], v[178:181], v[34:37]
	v_mfma_f32_16x16x32_bf16 v[38:41], v[134:137], v[178:181], v[38:41]
	v_mfma_f32_16x16x32_bf16 v[38:41], v[126:129], v[166:169], v[38:41]
	v_mfma_f32_16x16x32_bf16 v[42:45], v[102:105], v[166:169], v[42:45]
	v_mfma_f32_16x16x32_bf16 v[42:45], v[114:117], v[178:181], v[42:45]
	v_mfma_f32_16x16x32_bf16 v[46:49], v[90:93], v[178:181], v[46:49]
	v_mfma_f32_16x16x32_bf16 v[46:49], v[78:81], v[166:169], v[46:49]
	v_mfma_f32_16x16x32_bf16 v[30:33], v[78:81], v[182:185], v[30:33]
	v_mfma_f32_16x16x32_bf16 v[30:33], v[90:93], v[186:189], v[30:33]
	v_mfma_f32_16x16x32_bf16 v[26:29], v[114:117], v[186:189], v[26:29]
	v_mfma_f32_16x16x32_bf16 v[26:29], v[102:105], v[182:185], v[26:29]
	v_mfma_f32_16x16x32_bf16 v[22:25], v[126:129], v[182:185], v[22:25]
	v_mfma_f32_16x16x32_bf16 v[22:25], v[134:137], v[186:189], v[22:25]
	v_mfma_f32_16x16x32_bf16 v[18:21], v[154:157], v[186:189], v[18:21]
	v_mfma_f32_16x16x32_bf16 v[18:21], v[142:145], v[182:185], v[18:21]
	v_mfma_f32_16x16x32_bf16 v[2:5], v[142:145], v[190:193], v[2:5]
	v_mfma_f32_16x16x32_bf16 v[2:5], v[154:157], v[214:217], v[2:5]
	v_mfma_f32_16x16x32_bf16 v[6:9], v[134:137], v[214:217], v[6:9]
	v_mfma_f32_16x16x32_bf16 v[6:9], v[126:129], v[190:193], v[6:9]
	v_mfma_f32_16x16x32_bf16 v[10:13], v[102:105], v[190:193], v[10:13]
	v_mfma_f32_16x16x32_bf16 v[10:13], v[114:117], v[214:217], v[10:13]
	v_mfma_f32_16x16x32_bf16 v[14:17], v[90:93], v[214:217], v[14:17]
	v_mfma_f32_16x16x32_bf16 v[14:17], v[78:81], v[190:193], v[14:17]
	s_barrier
	s_add_i32 s18, 0, 0x18000
	s_add_i32 s19, 0, 0x1c000
	ds_read_b128 v[78:81], v220
	ds_read_b128 v[90:93], v220 offset:1024
	ds_read_b128 v[102:105], v220 offset:2048
	ds_read_b128 v[114:117], v220 offset:3072
	ds_read_b128 v[126:129], v221
	ds_read_b128 v[134:137], v221 offset:1024
	ds_read_b128 v[142:145], v221 offset:2048
	ds_read_b128 v[154:157], v221 offset:3072
	s_add_u32 s0, vcc_lo, 0x80000
	s_addc_u32 s1, vcc_hi, 0
	s_mov_b32 m0, s33
	ds_read_b128 v[158:161], v237 offset:32768
	ds_read_b128 v[162:165], v237 offset:33792
	ds_read_b128 v[166:169], v237 offset:34816
	ds_read_b128 v[178:181], v237 offset:35840
	ds_read_b128 v[182:185], v237 offset:36864
	ds_read_b128 v[186:189], v237 offset:37888
	ds_read_b128 v[190:193], v237 offset:38912
	ds_read_b128 v[214:217], v237 offset:39936
	global_load_lds_dwordx4 v194, s[0:1]
	s_mov_b32 m0, s43
	s_nop 0
	global_load_lds_dwordx4 v204, s[0:1]
	s_waitcnt vmcnt(8)
	s_waitcnt lgkmcnt(0)
	s_barrier
	s_waitcnt lgkmcnt(0)
	v_mfma_f32_16x16x32_bf16 v[174:177], v[78:81], v[158:161], v[174:177]
	v_mfma_f32_16x16x32_bf16 v[174:177], v[90:93], v[162:165], v[174:177]
	v_mfma_f32_16x16x32_bf16 v[170:173], v[114:117], v[162:165], v[170:173]
	v_mfma_f32_16x16x32_bf16 v[170:173], v[102:105], v[158:161], v[170:173]
	v_mfma_f32_16x16x32_bf16 v[150:153], v[126:129], v[158:161], v[150:153]
	v_mfma_f32_16x16x32_bf16 v[150:153], v[134:137], v[162:165], v[150:153]
	v_mfma_f32_16x16x32_bf16 v[146:149], v[154:157], v[162:165], v[146:149]
	v_mfma_f32_16x16x32_bf16 v[146:149], v[142:145], v[158:161], v[146:149]
	v_mfma_f32_16x16x32_bf16 v[118:121], v[142:145], v[166:169], v[118:121]
	v_mfma_f32_16x16x32_bf16 v[118:121], v[154:157], v[178:181], v[118:121]
	v_mfma_f32_16x16x32_bf16 v[122:125], v[134:137], v[178:181], v[122:125]
	v_mfma_f32_16x16x32_bf16 v[122:125], v[126:129], v[166:169], v[122:125]
	v_mfma_f32_16x16x32_bf16 v[130:133], v[102:105], v[166:169], v[130:133]
	v_mfma_f32_16x16x32_bf16 v[130:133], v[114:117], v[178:181], v[130:133]
	v_mfma_f32_16x16x32_bf16 v[138:141], v[90:93], v[178:181], v[138:141]
	v_mfma_f32_16x16x32_bf16 v[138:141], v[78:81], v[166:169], v[138:141]
	v_mfma_f32_16x16x32_bf16 v[110:113], v[78:81], v[182:185], v[110:113]
	v_mfma_f32_16x16x32_bf16 v[110:113], v[90:93], v[186:189], v[110:113]
	v_mfma_f32_16x16x32_bf16 v[106:109], v[114:117], v[186:189], v[106:109]
	v_mfma_f32_16x16x32_bf16 v[106:109], v[102:105], v[182:185], v[106:109]
	v_mfma_f32_16x16x32_bf16 v[98:101], v[126:129], v[182:185], v[98:101]
	v_mfma_f32_16x16x32_bf16 v[98:101], v[134:137], v[186:189], v[98:101]
	v_mfma_f32_16x16x32_bf16 v[94:97], v[154:157], v[186:189], v[94:97]
	v_mfma_f32_16x16x32_bf16 v[94:97], v[142:145], v[182:185], v[94:97]
	v_mfma_f32_16x16x32_bf16 v[66:69], v[142:145], v[190:193], v[66:69]
	v_mfma_f32_16x16x32_bf16 v[66:69], v[154:157], v[214:217], v[66:69]
	v_mfma_f32_16x16x32_bf16 v[74:77], v[134:137], v[214:217], v[74:77]
	v_mfma_f32_16x16x32_bf16 v[74:77], v[126:129], v[190:193], v[74:77]
	v_mfma_f32_16x16x32_bf16 v[82:85], v[102:105], v[190:193], v[82:85]
	v_mfma_f32_16x16x32_bf16 v[82:85], v[114:117], v[214:217], v[82:85]
	v_mfma_f32_16x16x32_bf16 v[86:89], v[90:93], v[214:217], v[86:89]
	v_mfma_f32_16x16x32_bf16 v[86:89], v[78:81], v[190:193], v[86:89]
	s_barrier
	s_add_u32 s98, s70, 0x80
	s_addc_u32 s99, s71, 0
	s_add_u32 s100, vcc_lo, 0x80
	s_addc_u32 s101, vcc_hi, 0
	s_add_i32 s0, s18, s28
	s_mov_b32 m0, s0
	ds_read_b128 v[158:161], v237 offset:49152
	ds_read_b128 v[162:165], v237 offset:50176
	ds_read_b128 v[166:169], v237 offset:51200
	ds_read_b128 v[178:181], v237 offset:52224
	ds_read_b128 v[182:185], v237 offset:53248
	ds_read_b128 v[186:189], v237 offset:54272
	ds_read_b128 v[190:193], v237 offset:55296
	ds_read_b128 v[214:217], v237 offset:56320
	global_load_lds_dwordx4 v194, s[98:99]
	s_add_i32 m0, s0, 0x2000
	s_add_u32 s0, s70, 0x80080
	s_addc_u32 s1, s71, 0
	s_add_i32 s18, s19, s28
	global_load_lds_dwordx4 v204, s[98:99]
	s_mov_b32 m0, s18
	s_nop 0
	global_load_lds_dwordx4 v194, s[0:1]
	s_add_i32 m0, s18, 0x2000
	s_nop 0
	global_load_lds_dwordx4 v204, s[0:1]
	s_mov_b32 m0, s68
	s_nop 0
	global_load_lds_dwordx4 v194, s[100:101]
	s_mov_b32 m0, s79
	s_nop 0
	global_load_lds_dwordx4 v204, s[100:101]
	s_waitcnt vmcnt(8)
	s_waitcnt lgkmcnt(0)
	s_barrier
	s_waitcnt lgkmcnt(0)
	v_mfma_f32_16x16x32_bf16 v[62:65], v[78:81], v[158:161], v[62:65]
	v_mfma_f32_16x16x32_bf16 v[62:65], v[90:93], v[162:165], v[62:65]
	v_mfma_f32_16x16x32_bf16 v[58:61], v[114:117], v[162:165], v[58:61]
	v_mfma_f32_16x16x32_bf16 v[58:61], v[102:105], v[158:161], v[58:61]
	v_mfma_f32_16x16x32_bf16 v[54:57], v[126:129], v[158:161], v[54:57]
	v_mfma_f32_16x16x32_bf16 v[54:57], v[134:137], v[162:165], v[54:57]
	v_mfma_f32_16x16x32_bf16 v[50:53], v[154:157], v[162:165], v[50:53]
	v_mfma_f32_16x16x32_bf16 v[50:53], v[142:145], v[158:161], v[50:53]
	v_mfma_f32_16x16x32_bf16 v[34:37], v[142:145], v[166:169], v[34:37]
	v_mfma_f32_16x16x32_bf16 v[34:37], v[154:157], v[178:181], v[34:37]
	v_mfma_f32_16x16x32_bf16 v[38:41], v[134:137], v[178:181], v[38:41]
	v_mfma_f32_16x16x32_bf16 v[38:41], v[126:129], v[166:169], v[38:41]
	v_mfma_f32_16x16x32_bf16 v[42:45], v[102:105], v[166:169], v[42:45]
	v_mfma_f32_16x16x32_bf16 v[42:45], v[114:117], v[178:181], v[42:45]
	v_mfma_f32_16x16x32_bf16 v[46:49], v[90:93], v[178:181], v[46:49]
	v_mfma_f32_16x16x32_bf16 v[46:49], v[78:81], v[166:169], v[46:49]
	v_mfma_f32_16x16x32_bf16 v[30:33], v[78:81], v[182:185], v[30:33]
	v_mfma_f32_16x16x32_bf16 v[30:33], v[90:93], v[186:189], v[30:33]
	v_mfma_f32_16x16x32_bf16 v[26:29], v[114:117], v[186:189], v[26:29]
	v_mfma_f32_16x16x32_bf16 v[26:29], v[102:105], v[182:185], v[26:29]
	v_mfma_f32_16x16x32_bf16 v[22:25], v[126:129], v[182:185], v[22:25]
	v_mfma_f32_16x16x32_bf16 v[22:25], v[134:137], v[186:189], v[22:25]
	v_mfma_f32_16x16x32_bf16 v[18:21], v[154:157], v[186:189], v[18:21]
	v_mfma_f32_16x16x32_bf16 v[18:21], v[142:145], v[182:185], v[18:21]
	v_mfma_f32_16x16x32_bf16 v[2:5], v[142:145], v[190:193], v[2:5]
	v_mfma_f32_16x16x32_bf16 v[2:5], v[154:157], v[214:217], v[2:5]
	v_mfma_f32_16x16x32_bf16 v[6:9], v[134:137], v[214:217], v[6:9]
	v_mfma_f32_16x16x32_bf16 v[6:9], v[126:129], v[190:193], v[6:9]
	v_mfma_f32_16x16x32_bf16 v[10:13], v[102:105], v[190:193], v[10:13]
	v_mfma_f32_16x16x32_bf16 v[10:13], v[114:117], v[214:217], v[10:13]
	v_mfma_f32_16x16x32_bf16 v[14:17], v[90:93], v[214:217], v[14:17]
	v_mfma_f32_16x16x32_bf16 v[14:17], v[78:81], v[190:193], v[14:17]
	s_barrier
	s_add_i32 s57, s57, 2
	s_add_u32 s51, s51, 0x100
	s_addc_u32 s53, s53, 0
	s_cmp_gt_u32 s57, 29
	s_mov_b64 s[76:77], s[90:91]
	s_cbranch_scc1 .LBB0_512

.Lpeel_disp_out:
	s_cmp_lg_u32 s57, -2
	s_cbranch_scc1 .LBB0_509
	s_add_u32 s90, s76, 0x100
	s_addc_u32 s91, s77, 0
	s_and_b64 s[0:1], s[70:71], exec
	s_cselect_b32 vcc_hi, s22, s91
	s_cselect_b32 vcc_lo, s23, s90
	s_cselect_b32 s71, s41, s53
	s_cselect_b32 s70, s44, s51
	s_add_i32 s0, 0, 0x10000
	s_add_i32 s18, 0, 0x14000
	ds_read_b128 v[78:81], v218
	ds_read_b128 v[90:93], v218 offset:1024
	ds_read_b128 v[102:105], v218 offset:2048
	ds_read_b128 v[114:117], v218 offset:3072
	ds_read_b128 v[126:129], v219
	ds_read_b128 v[134:137], v219 offset:1024
	ds_read_b128 v[142:145], v219 offset:2048
	ds_read_b128 v[154:157], v219 offset:3072
	s_add_i32 m0, s29, 0xc000
	ds_read_b128 v[158:161], v237
	ds_read_b128 v[162:165], v237 offset:1024
	ds_read_b128 v[166:169], v237 offset:2048
	ds_read_b128 v[178:181], v237 offset:3072
	ds_read_b128 v[182:185], v237 offset:4096
	ds_read_b128 v[186:189], v237 offset:5120
	ds_read_b128 v[190:193], v237 offset:6144
	ds_read_b128 v[214:217], v237 offset:7168
	global_load_lds_dwordx4 v210, s[76:77]
	s_add_i32 m0, s29, 0xe000
	s_nop 0
	global_load_lds_dwordx4 v212, s[76:77]
	s_waitcnt vmcnt(8)
	s_waitcnt lgkmcnt(0)
	s_barrier
	s_waitcnt lgkmcnt(0)
	v_mfma_f32_16x16x32_bf16 v[174:177], v[78:81], v[158:161], 0
	v_mfma_f32_16x16x32_bf16 v[174:177], v[90:93], v[162:165], v[174:177]
	v_mfma_f32_16x16x32_bf16 v[170:173], v[114:117], v[162:165], 0
	v_mfma_f32_16x16x32_bf16 v[170:173], v[102:105], v[158:161], v[170:173]
	v_mfma_f32_16x16x32_bf16 v[150:153], v[126:129], v[158:161], 0
	v_mfma_f32_16x16x32_bf16 v[150:153], v[134:137], v[162:165], v[150:153]
	v_mfma_f32_16x16x32_bf16 v[146:149], v[154:157], v[162:165], 0
	v_mfma_f32_16x16x32_bf16 v[146:149], v[142:145], v[158:161], v[146:149]
	v_mfma_f32_16x16x32_bf16 v[118:121], v[142:145], v[166:169], 0
	v_mfma_f32_16x16x32_bf16 v[118:121], v[154:157], v[178:181], v[118:121]
	v_mfma_f32_16x16x32_bf16 v[122:125], v[134:137], v[178:181], 0
	v_mfma_f32_16x16x32_bf16 v[122:125], v[126:129], v[166:169], v[122:125]
	v_mfma_f32_16x16x32_bf16 v[130:133], v[102:105], v[166:169], 0
	v_mfma_f32_16x16x32_bf16 v[130:133], v[114:117], v[178:181], v[130:133]
	v_mfma_f32_16x16x32_bf16 v[138:141], v[90:93], v[178:181], 0
	v_mfma_f32_16x16x32_bf16 v[138:141], v[78:81], v[166:169], v[138:141]
	v_mfma_f32_16x16x32_bf16 v[110:113], v[78:81], v[182:185], 0
	v_mfma_f32_16x16x32_bf16 v[110:113], v[90:93], v[186:189], v[110:113]
	v_mfma_f32_16x16x32_bf16 v[106:109], v[114:117], v[186:189], 0
	v_mfma_f32_16x16x32_bf16 v[106:109], v[102:105], v[182:185], v[106:109]
	v_mfma_f32_16x16x32_bf16 v[98:101], v[126:129], v[182:185], 0
	v_mfma_f32_16x16x32_bf16 v[98:101], v[134:137], v[186:189], v[98:101]
	v_mfma_f32_16x16x32_bf16 v[94:97], v[154:157], v[186:189], 0
	v_mfma_f32_16x16x32_bf16 v[94:97], v[142:145], v[182:185], v[94:97]
	v_mfma_f32_16x16x32_bf16 v[66:69], v[142:145], v[190:193], 0
	v_mfma_f32_16x16x32_bf16 v[66:69], v[154:157], v[214:217], v[66:69]
	v_mfma_f32_16x16x32_bf16 v[74:77], v[134:137], v[214:217], 0
	v_mfma_f32_16x16x32_bf16 v[74:77], v[126:129], v[190:193], v[74:77]
	v_mfma_f32_16x16x32_bf16 v[82:85], v[102:105], v[190:193], 0
	v_mfma_f32_16x16x32_bf16 v[82:85], v[114:117], v[214:217], v[82:85]
	v_mfma_f32_16x16x32_bf16 v[86:89], v[90:93], v[214:217], 0
	v_mfma_f32_16x16x32_bf16 v[86:89], v[78:81], v[190:193], v[86:89]
	s_barrier
	s_add_i32 s0, s0, s28
	s_mov_b32 m0, s0
	ds_read_b128 v[158:161], v237 offset:16384
	ds_read_b128 v[162:165], v237 offset:17408
	ds_read_b128 v[166:169], v237 offset:18432
	ds_read_b128 v[178:181], v237 offset:19456
	ds_read_b128 v[182:185], v237 offset:20480
	ds_read_b128 v[186:189], v237 offset:21504
	ds_read_b128 v[190:193], v237 offset:22528
	ds_read_b128 v[214:217], v237 offset:23552
	global_load_lds_dwordx4 v194, s[70:71]
	s_add_i32 m0, s0, 0x2000
	s_add_u32 s0, s70, 0x80000
	s_addc_u32 s1, s71, 0
	s_add_i32 s18, s18, s28
	global_load_lds_dwordx4 v204, s[70:71]
	s_mov_b32 m0, s18
	s_nop 0
	global_load_lds_dwordx4 v194, s[0:1]
	s_add_i32 m0, s18, 0x2000
	s_nop 0
	global_load_lds_dwordx4 v204, s[0:1]
	s_mov_b32 m0, s29
	s_nop 0
	global_load_lds_dwordx4 v194, vcc
	s_mov_b32 m0, s31
	s_nop 0
	global_load_lds_dwordx4 v204, vcc
	s_waitcnt vmcnt(8)
	s_waitcnt lgkmcnt(0)
	s_barrier
	s_waitcnt lgkmcnt(0)
	v_mfma_f32_16x16x32_bf16 v[62:65], v[78:81], v[158:161], 0
	v_mfma_f32_16x16x32_bf16 v[62:65], v[90:93], v[162:165], v[62:65]
	v_mfma_f32_16x16x32_bf16 v[58:61], v[114:117], v[162:165], 0
	v_mfma_f32_16x16x32_bf16 v[58:61], v[102:105], v[158:161], v[58:61]
	v_mfma_f32_16x16x32_bf16 v[54:57], v[126:129], v[158:161], 0
	v_mfma_f32_16x16x32_bf16 v[54:57], v[134:137], v[162:165], v[54:57]
	v_mfma_f32_16x16x32_bf16 v[50:53], v[154:157], v[162:165], 0
	v_mfma_f32_16x16x32_bf16 v[50:53], v[142:145], v[158:161], v[50:53]
	v_mfma_f32_16x16x32_bf16 v[34:37], v[142:145], v[166:169], 0
	v_mfma_f32_16x16x32_bf16 v[34:37], v[154:157], v[178:181], v[34:37]
	v_mfma_f32_16x16x32_bf16 v[38:41], v[134:137], v[178:181], 0
	v_mfma_f32_16x16x32_bf16 v[38:41], v[126:129], v[166:169], v[38:41]
	v_mfma_f32_16x16x32_bf16 v[42:45], v[102:105], v[166:169], 0
	v_mfma_f32_16x16x32_bf16 v[42:45], v[114:117], v[178:181], v[42:45]
	v_mfma_f32_16x16x32_bf16 v[46:49], v[90:93], v[178:181], 0
	v_mfma_f32_16x16x32_bf16 v[46:49], v[78:81], v[166:169], v[46:49]
	v_mfma_f32_16x16x32_bf16 v[30:33], v[78:81], v[182:185], 0
	v_mfma_f32_16x16x32_bf16 v[30:33], v[90:93], v[186:189], v[30:33]
	v_mfma_f32_16x16x32_bf16 v[26:29], v[114:117], v[186:189], 0
	v_mfma_f32_16x16x32_bf16 v[26:29], v[102:105], v[182:185], v[26:29]
	v_mfma_f32_16x16x32_bf16 v[22:25], v[126:129], v[182:185], 0
	v_mfma_f32_16x16x32_bf16 v[22:25], v[134:137], v[186:189], v[22:25]
	v_mfma_f32_16x16x32_bf16 v[18:21], v[154:157], v[186:189], 0
	v_mfma_f32_16x16x32_bf16 v[18:21], v[142:145], v[182:185], v[18:21]
	v_mfma_f32_16x16x32_bf16 v[2:5], v[142:145], v[190:193], 0
	v_mfma_f32_16x16x32_bf16 v[2:5], v[154:157], v[214:217], v[2:5]
	v_mfma_f32_16x16x32_bf16 v[6:9], v[134:137], v[214:217], 0
	v_mfma_f32_16x16x32_bf16 v[6:9], v[126:129], v[190:193], v[6:9]
	v_mfma_f32_16x16x32_bf16 v[10:13], v[102:105], v[190:193], 0
	v_mfma_f32_16x16x32_bf16 v[10:13], v[114:117], v[214:217], v[10:13]
	v_mfma_f32_16x16x32_bf16 v[14:17], v[90:93], v[214:217], 0
	v_mfma_f32_16x16x32_bf16 v[14:17], v[78:81], v[190:193], v[14:17]
	s_barrier
	s_add_i32 s18, 0, 0x18000
	s_add_i32 s19, 0, 0x1c000
	ds_read_b128 v[78:81], v220
	ds_read_b128 v[90:93], v220 offset:1024
	ds_read_b128 v[102:105], v220 offset:2048
	ds_read_b128 v[114:117], v220 offset:3072
	ds_read_b128 v[126:129], v221
	ds_read_b128 v[134:137], v221 offset:1024
	ds_read_b128 v[142:145], v221 offset:2048
	ds_read_b128 v[154:157], v221 offset:3072
	s_add_u32 s0, vcc_lo, 0x80000
	s_addc_u32 s1, vcc_hi, 0
	s_mov_b32 m0, s33
	ds_read_b128 v[158:161], v237 offset:32768
	ds_read_b128 v[162:165], v237 offset:33792
	ds_read_b128 v[166:169], v237 offset:34816
	ds_read_b128 v[178:181], v237 offset:35840
	ds_read_b128 v[182:185], v237 offset:36864
	ds_read_b128 v[186:189], v237 offset:37888
	ds_read_b128 v[190:193], v237 offset:38912
	ds_read_b128 v[214:217], v237 offset:39936
	global_load_lds_dwordx4 v194, s[0:1]
	s_mov_b32 m0, s43
	s_nop 0
	global_load_lds_dwordx4 v204, s[0:1]
	s_waitcnt vmcnt(8)
	s_waitcnt lgkmcnt(0)
	s_barrier
	s_waitcnt lgkmcnt(0)
	v_mfma_f32_16x16x32_bf16 v[174:177], v[78:81], v[158:161], v[174:177]
	v_mfma_f32_16x16x32_bf16 v[174:177], v[90:93], v[162:165], v[174:177]
	v_mfma_f32_16x16x32_bf16 v[170:173], v[114:117], v[162:165], v[170:173]
	v_mfma_f32_16x16x32_bf16 v[170:173], v[102:105], v[158:161], v[170:173]
	v_mfma_f32_16x16x32_bf16 v[150:153], v[126:129], v[158:161], v[150:153]
	v_mfma_f32_16x16x32_bf16 v[150:153], v[134:137], v[162:165], v[150:153]
	v_mfma_f32_16x16x32_bf16 v[146:149], v[154:157], v[162:165], v[146:149]
	v_mfma_f32_16x16x32_bf16 v[146:149], v[142:145], v[158:161], v[146:149]
	v_mfma_f32_16x16x32_bf16 v[118:121], v[142:145], v[166:169], v[118:121]
	v_mfma_f32_16x16x32_bf16 v[118:121], v[154:157], v[178:181], v[118:121]
	v_mfma_f32_16x16x32_bf16 v[122:125], v[134:137], v[178:181], v[122:125]
	v_mfma_f32_16x16x32_bf16 v[122:125], v[126:129], v[166:169], v[122:125]
	v_mfma_f32_16x16x32_bf16 v[130:133], v[102:105], v[166:169], v[130:133]
	v_mfma_f32_16x16x32_bf16 v[130:133], v[114:117], v[178:181], v[130:133]
	v_mfma_f32_16x16x32_bf16 v[138:141], v[90:93], v[178:181], v[138:141]
	v_mfma_f32_16x16x32_bf16 v[138:141], v[78:81], v[166:169], v[138:141]
	v_mfma_f32_16x16x32_bf16 v[110:113], v[78:81], v[182:185], v[110:113]
	v_mfma_f32_16x16x32_bf16 v[110:113], v[90:93], v[186:189], v[110:113]
	v_mfma_f32_16x16x32_bf16 v[106:109], v[114:117], v[186:189], v[106:109]
	v_mfma_f32_16x16x32_bf16 v[106:109], v[102:105], v[182:185], v[106:109]
	v_mfma_f32_16x16x32_bf16 v[98:101], v[126:129], v[182:185], v[98:101]
	v_mfma_f32_16x16x32_bf16 v[98:101], v[134:137], v[186:189], v[98:101]
	v_mfma_f32_16x16x32_bf16 v[94:97], v[154:157], v[186:189], v[94:97]
	v_mfma_f32_16x16x32_bf16 v[94:97], v[142:145], v[182:185], v[94:97]
	v_mfma_f32_16x16x32_bf16 v[66:69], v[142:145], v[190:193], v[66:69]
	v_mfma_f32_16x16x32_bf16 v[66:69], v[154:157], v[214:217], v[66:69]
	v_mfma_f32_16x16x32_bf16 v[74:77], v[134:137], v[214:217], v[74:77]
	v_mfma_f32_16x16x32_bf16 v[74:77], v[126:129], v[190:193], v[74:77]
	v_mfma_f32_16x16x32_bf16 v[82:85], v[102:105], v[190:193], v[82:85]
	v_mfma_f32_16x16x32_bf16 v[82:85], v[114:117], v[214:217], v[82:85]
	v_mfma_f32_16x16x32_bf16 v[86:89], v[90:93], v[214:217], v[86:89]
	v_mfma_f32_16x16x32_bf16 v[86:89], v[78:81], v[190:193], v[86:89]
	s_barrier
	s_add_u32 s98, s70, 0x80
	s_addc_u32 s99, s71, 0
	s_add_u32 s100, vcc_lo, 0x80
	s_addc_u32 s101, vcc_hi, 0
	s_add_i32 s0, s18, s28
	s_mov_b32 m0, s0
	ds_read_b128 v[158:161], v237 offset:49152
	ds_read_b128 v[162:165], v237 offset:50176
	ds_read_b128 v[166:169], v237 offset:51200
	ds_read_b128 v[178:181], v237 offset:52224
	ds_read_b128 v[182:185], v237 offset:53248
	ds_read_b128 v[186:189], v237 offset:54272
	ds_read_b128 v[190:193], v237 offset:55296
	ds_read_b128 v[214:217], v237 offset:56320
	global_load_lds_dwordx4 v194, s[98:99]
	s_add_i32 m0, s0, 0x2000
	s_add_u32 s0, s70, 0x80080
	s_addc_u32 s1, s71, 0
	s_add_i32 s18, s19, s28
	global_load_lds_dwordx4 v204, s[98:99]
	s_mov_b32 m0, s18
	s_nop 0
	global_load_lds_dwordx4 v194, s[0:1]
	s_add_i32 m0, s18, 0x2000
	s_nop 0
	global_load_lds_dwordx4 v204, s[0:1]
	s_mov_b32 m0, s68
	s_nop 0
	global_load_lds_dwordx4 v194, s[100:101]
	s_mov_b32 m0, s79
	s_nop 0
	global_load_lds_dwordx4 v204, s[100:101]
	s_waitcnt vmcnt(8)
	s_waitcnt lgkmcnt(0)
	s_barrier
	s_waitcnt lgkmcnt(0)
	v_mfma_f32_16x16x32_bf16 v[62:65], v[78:81], v[158:161], v[62:65]
	v_mfma_f32_16x16x32_bf16 v[62:65], v[90:93], v[162:165], v[62:65]
	v_mfma_f32_16x16x32_bf16 v[58:61], v[114:117], v[162:165], v[58:61]
	v_mfma_f32_16x16x32_bf16 v[58:61], v[102:105], v[158:161], v[58:61]
	v_mfma_f32_16x16x32_bf16 v[54:57], v[126:129], v[158:161], v[54:57]
	v_mfma_f32_16x16x32_bf16 v[54:57], v[134:137], v[162:165], v[54:57]
	v_mfma_f32_16x16x32_bf16 v[50:53], v[154:157], v[162:165], v[50:53]
	v_mfma_f32_16x16x32_bf16 v[50:53], v[142:145], v[158:161], v[50:53]
	v_mfma_f32_16x16x32_bf16 v[34:37], v[142:145], v[166:169], v[34:37]
	v_mfma_f32_16x16x32_bf16 v[34:37], v[154:157], v[178:181], v[34:37]
	v_mfma_f32_16x16x32_bf16 v[38:41], v[134:137], v[178:181], v[38:41]
	v_mfma_f32_16x16x32_bf16 v[38:41], v[126:129], v[166:169], v[38:41]
	v_mfma_f32_16x16x32_bf16 v[42:45], v[102:105], v[166:169], v[42:45]
	v_mfma_f32_16x16x32_bf16 v[42:45], v[114:117], v[178:181], v[42:45]
	v_mfma_f32_16x16x32_bf16 v[46:49], v[90:93], v[178:181], v[46:49]
	v_mfma_f32_16x16x32_bf16 v[46:49], v[78:81], v[166:169], v[46:49]
	v_mfma_f32_16x16x32_bf16 v[30:33], v[78:81], v[182:185], v[30:33]
	v_mfma_f32_16x16x32_bf16 v[30:33], v[90:93], v[186:189], v[30:33]
	v_mfma_f32_16x16x32_bf16 v[26:29], v[114:117], v[186:189], v[26:29]
	v_mfma_f32_16x16x32_bf16 v[26:29], v[102:105], v[182:185], v[26:29]
	v_mfma_f32_16x16x32_bf16 v[22:25], v[126:129], v[182:185], v[22:25]
	v_mfma_f32_16x16x32_bf16 v[22:25], v[134:137], v[186:189], v[22:25]
	v_mfma_f32_16x16x32_bf16 v[18:21], v[154:157], v[186:189], v[18:21]
	v_mfma_f32_16x16x32_bf16 v[18:21], v[142:145], v[182:185], v[18:21]
	v_mfma_f32_16x16x32_bf16 v[2:5], v[142:145], v[190:193], v[2:5]
	v_mfma_f32_16x16x32_bf16 v[2:5], v[154:157], v[214:217], v[2:5]
	v_mfma_f32_16x16x32_bf16 v[6:9], v[134:137], v[214:217], v[6:9]
	v_mfma_f32_16x16x32_bf16 v[6:9], v[126:129], v[190:193], v[6:9]
	v_mfma_f32_16x16x32_bf16 v[10:13], v[102:105], v[190:193], v[10:13]
	v_mfma_f32_16x16x32_bf16 v[10:13], v[114:117], v[214:217], v[10:13]
	v_mfma_f32_16x16x32_bf16 v[14:17], v[90:93], v[214:217], v[14:17]
	v_mfma_f32_16x16x32_bf16 v[14:17], v[78:81], v[190:193], v[14:17]
	s_barrier
	s_add_i32 s57, s57, 2
	s_add_u32 s51, s51, 0x100
	s_addc_u32 s53, s53, 0
	s_cmp_gt_u32 s57, 29
	s_mov_b64 s[76:77], s[90:91]
	s_cbranch_scc1 .LBB0_512
	s_branch .LBB0_510

.LBB0_580:
	s_ashr_i32 s47, s46, 31
	s_lshl_b64 s[0:1], s[46:47], 20
	s_add_u32 s48, s20, s0
	s_addc_u32 s49, s21, s1
	s_and_b64 s[0:1], s[6:7], exec
	s_cselect_b32 s22, s49, s63
	s_cselect_b32 s23, s48, s62
	s_ashr_i32 s39, s38, 31
	s_lshl_b64 s[0:1], s[38:39], 20
	s_add_u32 s50, s26, s0
	s_addc_u32 s51, s27, s1
	s_and_b64 s[0:1], s[6:7], exec
	s_cselect_b32 s39, s51, s65
	s_cselect_b32 s47, s50, s64
	s_ashr_i32 s53, s52, 31
	s_lshl_b32 s18, s44, 8
	s_lshl_b64 s[0:1], s[52:53], 10
	s_ashr_i32 s24, s52, 5
	s_ashr_i32 s19, s18, 31
	s_add_u32 s62, s62, 0x80080
	v_lshl_add_u64 v[2:3], s[18:19], 2, v[132:133]
	s_addc_u32 s63, s63, 0
	v_lshl_add_u64 v[140:141], v[134:135], 0, s[0:1]
	v_mad_i64_i32 v[142:143], s[0:1], s24, v236, v[2:3]
	s_add_u32 s53, s64, 0x100
	s_addc_u32 s58, s65, 0
	s_mov_b32 s76, -2
	v_add_u32_e32 v220, 0x10000, v1
	v_add_u32_e32 v221, 0x14000, v1
	v_add_u32_e32 v222, 0x18000, v1
	v_add_u32_e32 v223, 0x1c000, v1
	s_branch .LBB0_582
.LBB0_581:
	s_add_u32 s18, s62, 0xfff80080
	s_addc_u32 s19, s63, -1
	s_and_b64 s[0:1], s[64:65], exec
	s_cselect_b32 s71, s22, s19
	s_cselect_b32 s70, s23, s18
	s_cselect_b32 s65, s39, s58
	s_cselect_b32 s64, s47, s53
	s_add_i32 s0, 0, 0x10000
	s_add_i32 s18, 0, 0x14000
	ds_read_b128 v[144:147], v220
	ds_read_b128 v[148:151], v220 offset:1024
	ds_read_b128 v[154:157], v220 offset:2048
	ds_read_b128 v[158:161], v220 offset:3072
	ds_read_b128 v[162:165], v221
	ds_read_b128 v[166:169], v221 offset:1024
	ds_read_b128 v[170:173], v221 offset:2048
	ds_read_b128 v[174:177], v221 offset:3072
	s_add_i32 m0, s29, 0xc000
	ds_read_b128 v[178:181], v152
	ds_read_b128 v[182:185], v152 offset:1024
	ds_read_b128 v[186:189], v152 offset:2048
	ds_read_b128 v[190:193], v152 offset:3072
	ds_read_b128 v[204:207], v152 offset:4096
	ds_read_b128 v[208:211], v152 offset:5120
	ds_read_b128 v[212:215], v152 offset:6144
	ds_read_b128 v[216:219], v152 offset:7168
	global_load_lds_dwordx4 v136, s[62:63]
	s_add_i32 m0, s29, 0xe000
	s_nop 0
	global_load_lds_dwordx4 v138, s[62:63]
	s_waitcnt vmcnt(8)
	s_waitcnt lgkmcnt(0)
	s_barrier
	s_waitcnt lgkmcnt(0)
	v_mfma_f32_16x16x32_bf16 v[126:129], v[144:147], v[178:181], v[126:129]
	v_mfma_f32_16x16x32_bf16 v[126:129], v[148:151], v[182:185], v[126:129]
	v_mfma_f32_16x16x32_bf16 v[122:125], v[158:161], v[182:185], v[122:125]
	v_mfma_f32_16x16x32_bf16 v[122:125], v[154:157], v[178:181], v[122:125]
	v_mfma_f32_16x16x32_bf16 v[118:121], v[162:165], v[178:181], v[118:121]
	v_mfma_f32_16x16x32_bf16 v[118:121], v[166:169], v[182:185], v[118:121]
	v_mfma_f32_16x16x32_bf16 v[114:117], v[174:177], v[182:185], v[114:117]
	v_mfma_f32_16x16x32_bf16 v[114:117], v[170:173], v[178:181], v[114:117]
	v_mfma_f32_16x16x32_bf16 v[98:101], v[170:173], v[186:189], v[98:101]
	v_mfma_f32_16x16x32_bf16 v[98:101], v[174:177], v[190:193], v[98:101]
	v_mfma_f32_16x16x32_bf16 v[102:105], v[166:169], v[190:193], v[102:105]
	v_mfma_f32_16x16x32_bf16 v[102:105], v[162:165], v[186:189], v[102:105]
	v_mfma_f32_16x16x32_bf16 v[106:109], v[154:157], v[186:189], v[106:109]
	v_mfma_f32_16x16x32_bf16 v[106:109], v[158:161], v[190:193], v[106:109]
	v_mfma_f32_16x16x32_bf16 v[110:113], v[148:151], v[190:193], v[110:113]
	v_mfma_f32_16x16x32_bf16 v[110:113], v[144:147], v[186:189], v[110:113]
	v_mfma_f32_16x16x32_bf16 v[94:97], v[144:147], v[204:207], v[94:97]
	v_mfma_f32_16x16x32_bf16 v[94:97], v[148:151], v[208:211], v[94:97]
	v_mfma_f32_16x16x32_bf16 v[90:93], v[158:161], v[208:211], v[90:93]
	v_mfma_f32_16x16x32_bf16 v[90:93], v[154:157], v[204:207], v[90:93]
	v_mfma_f32_16x16x32_bf16 v[86:89], v[162:165], v[204:207], v[86:89]
	v_mfma_f32_16x16x32_bf16 v[86:89], v[166:169], v[208:211], v[86:89]
	v_mfma_f32_16x16x32_bf16 v[82:85], v[174:177], v[208:211], v[82:85]
	v_mfma_f32_16x16x32_bf16 v[82:85], v[170:173], v[204:207], v[82:85]
	v_mfma_f32_16x16x32_bf16 v[66:69], v[170:173], v[212:215], v[66:69]
	v_mfma_f32_16x16x32_bf16 v[66:69], v[174:177], v[216:219], v[66:69]
	v_mfma_f32_16x16x32_bf16 v[70:73], v[166:169], v[216:219], v[70:73]
	v_mfma_f32_16x16x32_bf16 v[70:73], v[162:165], v[212:215], v[70:73]
	v_mfma_f32_16x16x32_bf16 v[74:77], v[154:157], v[212:215], v[74:77]
	v_mfma_f32_16x16x32_bf16 v[74:77], v[158:161], v[216:219], v[74:77]
	v_mfma_f32_16x16x32_bf16 v[78:81], v[148:151], v[216:219], v[78:81]
	v_mfma_f32_16x16x32_bf16 v[78:81], v[144:147], v[212:215], v[78:81]
	s_barrier
	s_add_i32 s0, s0, s28
	s_mov_b32 m0, s0
	ds_read_b128 v[178:181], v152 offset:16384
	ds_read_b128 v[182:185], v152 offset:17408
	ds_read_b128 v[186:189], v152 offset:18432
	ds_read_b128 v[190:193], v152 offset:19456
	ds_read_b128 v[204:207], v152 offset:20480
	ds_read_b128 v[208:211], v152 offset:21504
	ds_read_b128 v[212:215], v152 offset:22528
	ds_read_b128 v[216:219], v152 offset:23552
	global_load_lds_dwordx4 v194, s[64:65]
	s_add_i32 m0, s0, 0x2000
	s_add_u32 s0, s64, 0x80000
	s_addc_u32 s1, s65, 0
	s_add_i32 s18, s18, s28
	global_load_lds_dwordx4 v130, s[64:65]
	s_mov_b32 m0, s18
	s_nop 0
	global_load_lds_dwordx4 v194, s[0:1]
	s_add_i32 m0, s18, 0x2000
	s_nop 0
	global_load_lds_dwordx4 v130, s[0:1]
	s_mov_b32 m0, s29
	s_nop 0
	global_load_lds_dwordx4 v194, s[70:71]
	s_mov_b32 m0, s31
	s_nop 0
	global_load_lds_dwordx4 v130, s[70:71]
	s_waitcnt vmcnt(8)
	s_waitcnt lgkmcnt(0)
	s_barrier
	s_waitcnt lgkmcnt(0)
	v_mfma_f32_16x16x32_bf16 v[62:65], v[144:147], v[178:181], v[62:65]
	v_mfma_f32_16x16x32_bf16 v[62:65], v[148:151], v[182:185], v[62:65]
	v_mfma_f32_16x16x32_bf16 v[58:61], v[158:161], v[182:185], v[58:61]
	v_mfma_f32_16x16x32_bf16 v[58:61], v[154:157], v[178:181], v[58:61]
	v_mfma_f32_16x16x32_bf16 v[54:57], v[162:165], v[178:181], v[54:57]
	v_mfma_f32_16x16x32_bf16 v[54:57], v[166:169], v[182:185], v[54:57]
	v_mfma_f32_16x16x32_bf16 v[50:53], v[174:177], v[182:185], v[50:53]
	v_mfma_f32_16x16x32_bf16 v[50:53], v[170:173], v[178:181], v[50:53]
	v_mfma_f32_16x16x32_bf16 v[34:37], v[170:173], v[186:189], v[34:37]
	v_mfma_f32_16x16x32_bf16 v[34:37], v[174:177], v[190:193], v[34:37]
	v_mfma_f32_16x16x32_bf16 v[38:41], v[166:169], v[190:193], v[38:41]
	v_mfma_f32_16x16x32_bf16 v[38:41], v[162:165], v[186:189], v[38:41]
	v_mfma_f32_16x16x32_bf16 v[42:45], v[154:157], v[186:189], v[42:45]
	v_mfma_f32_16x16x32_bf16 v[42:45], v[158:161], v[190:193], v[42:45]
	v_mfma_f32_16x16x32_bf16 v[46:49], v[148:151], v[190:193], v[46:49]
	v_mfma_f32_16x16x32_bf16 v[46:49], v[144:147], v[186:189], v[46:49]
	v_mfma_f32_16x16x32_bf16 v[30:33], v[144:147], v[204:207], v[30:33]
	v_mfma_f32_16x16x32_bf16 v[30:33], v[148:151], v[208:211], v[30:33]
	v_mfma_f32_16x16x32_bf16 v[26:29], v[158:161], v[208:211], v[26:29]
	v_mfma_f32_16x16x32_bf16 v[26:29], v[154:157], v[204:207], v[26:29]
	v_mfma_f32_16x16x32_bf16 v[22:25], v[162:165], v[204:207], v[22:25]
	v_mfma_f32_16x16x32_bf16 v[22:25], v[166:169], v[208:211], v[22:25]
	v_mfma_f32_16x16x32_bf16 v[18:21], v[174:177], v[208:211], v[18:21]
	v_mfma_f32_16x16x32_bf16 v[18:21], v[170:173], v[204:207], v[18:21]
	v_mfma_f32_16x16x32_bf16 v[2:5], v[170:173], v[212:215], v[2:5]
	v_mfma_f32_16x16x32_bf16 v[2:5], v[174:177], v[216:219], v[2:5]
	v_mfma_f32_16x16x32_bf16 v[6:9], v[166:169], v[216:219], v[6:9]
	v_mfma_f32_16x16x32_bf16 v[6:9], v[162:165], v[212:215], v[6:9]
	v_mfma_f32_16x16x32_bf16 v[10:13], v[154:157], v[212:215], v[10:13]
	v_mfma_f32_16x16x32_bf16 v[10:13], v[158:161], v[216:219], v[10:13]
	v_mfma_f32_16x16x32_bf16 v[14:17], v[148:151], v[216:219], v[14:17]
	v_mfma_f32_16x16x32_bf16 v[14:17], v[144:147], v[212:215], v[14:17]
	s_barrier
	s_add_i32 s18, 0, 0x18000
	s_add_i32 s19, 0, 0x1c000
	ds_read_b128 v[144:147], v222
	ds_read_b128 v[148:151], v222 offset:1024
	ds_read_b128 v[154:157], v222 offset:2048
	ds_read_b128 v[158:161], v222 offset:3072
	ds_read_b128 v[162:165], v223
	ds_read_b128 v[166:169], v223 offset:1024
	ds_read_b128 v[170:173], v223 offset:2048
	ds_read_b128 v[174:177], v223 offset:3072
	s_add_u32 s0, s70, 0x80000
	s_addc_u32 s1, s71, 0
	s_mov_b32 m0, s33
	ds_read_b128 v[178:181], v152 offset:32768
	ds_read_b128 v[182:185], v152 offset:33792
	ds_read_b128 v[186:189], v152 offset:34816
	ds_read_b128 v[190:193], v152 offset:35840
	ds_read_b128 v[204:207], v152 offset:36864
	ds_read_b128 v[208:211], v152 offset:37888
	ds_read_b128 v[212:215], v152 offset:38912
	ds_read_b128 v[216:219], v152 offset:39936
	global_load_lds_dwordx4 v194, s[0:1]
	s_mov_b32 m0, s40
	s_nop 0
	global_load_lds_dwordx4 v130, s[0:1]
	s_waitcnt vmcnt(8)
	s_waitcnt lgkmcnt(0)
	s_barrier
	s_waitcnt lgkmcnt(0)
	v_mfma_f32_16x16x32_bf16 v[126:129], v[144:147], v[178:181], v[126:129]
	v_mfma_f32_16x16x32_bf16 v[126:129], v[148:151], v[182:185], v[126:129]
	v_mfma_f32_16x16x32_bf16 v[122:125], v[158:161], v[182:185], v[122:125]
	v_mfma_f32_16x16x32_bf16 v[122:125], v[154:157], v[178:181], v[122:125]
	v_mfma_f32_16x16x32_bf16 v[118:121], v[162:165], v[178:181], v[118:121]
	v_mfma_f32_16x16x32_bf16 v[118:121], v[166:169], v[182:185], v[118:121]
	v_mfma_f32_16x16x32_bf16 v[114:117], v[174:177], v[182:185], v[114:117]
	v_mfma_f32_16x16x32_bf16 v[114:117], v[170:173], v[178:181], v[114:117]
	v_mfma_f32_16x16x32_bf16 v[98:101], v[170:173], v[186:189], v[98:101]
	v_mfma_f32_16x16x32_bf16 v[98:101], v[174:177], v[190:193], v[98:101]
	v_mfma_f32_16x16x32_bf16 v[102:105], v[166:169], v[190:193], v[102:105]
	v_mfma_f32_16x16x32_bf16 v[102:105], v[162:165], v[186:189], v[102:105]
	v_mfma_f32_16x16x32_bf16 v[106:109], v[154:157], v[186:189], v[106:109]
	v_mfma_f32_16x16x32_bf16 v[106:109], v[158:161], v[190:193], v[106:109]
	v_mfma_f32_16x16x32_bf16 v[110:113], v[148:151], v[190:193], v[110:113]
	v_mfma_f32_16x16x32_bf16 v[110:113], v[144:147], v[186:189], v[110:113]
	v_mfma_f32_16x16x32_bf16 v[94:97], v[144:147], v[204:207], v[94:97]
	v_mfma_f32_16x16x32_bf16 v[94:97], v[148:151], v[208:211], v[94:97]
	v_mfma_f32_16x16x32_bf16 v[90:93], v[158:161], v[208:211], v[90:93]
	v_mfma_f32_16x16x32_bf16 v[90:93], v[154:157], v[204:207], v[90:93]
	v_mfma_f32_16x16x32_bf16 v[86:89], v[162:165], v[204:207], v[86:89]
	v_mfma_f32_16x16x32_bf16 v[86:89], v[166:169], v[208:211], v[86:89]
	v_mfma_f32_16x16x32_bf16 v[82:85], v[174:177], v[208:211], v[82:85]
	v_mfma_f32_16x16x32_bf16 v[82:85], v[170:173], v[204:207], v[82:85]
	v_mfma_f32_16x16x32_bf16 v[66:69], v[170:173], v[212:215], v[66:69]
	v_mfma_f32_16x16x32_bf16 v[66:69], v[174:177], v[216:219], v[66:69]
	v_mfma_f32_16x16x32_bf16 v[70:73], v[166:169], v[216:219], v[70:73]
	v_mfma_f32_16x16x32_bf16 v[70:73], v[162:165], v[212:215], v[70:73]
	v_mfma_f32_16x16x32_bf16 v[74:77], v[154:157], v[212:215], v[74:77]
	v_mfma_f32_16x16x32_bf16 v[74:77], v[158:161], v[216:219], v[74:77]
	v_mfma_f32_16x16x32_bf16 v[78:81], v[148:151], v[216:219], v[78:81]
	v_mfma_f32_16x16x32_bf16 v[78:81], v[144:147], v[212:215], v[78:81]
	s_barrier
	s_add_u32 s98, s64, 0x80
	s_addc_u32 s99, s65, 0
	s_add_u32 s100, s70, 0x80
	s_addc_u32 s101, s71, 0
	s_add_i32 s0, s18, s28
	s_mov_b32 m0, s0
	ds_read_b128 v[178:181], v152 offset:49152
	ds_read_b128 v[182:185], v152 offset:50176
	ds_read_b128 v[186:189], v152 offset:51200
	ds_read_b128 v[190:193], v152 offset:52224
	ds_read_b128 v[204:207], v152 offset:53248
	ds_read_b128 v[208:211], v152 offset:54272
	ds_read_b128 v[212:215], v152 offset:55296
	ds_read_b128 v[216:219], v152 offset:56320
	global_load_lds_dwordx4 v194, s[98:99]
	s_add_i32 m0, s0, 0x2000
	s_add_u32 s0, s64, 0x80080
	s_addc_u32 s1, s65, 0
	s_add_i32 s18, s19, s28
	global_load_lds_dwordx4 v130, s[98:99]
	s_mov_b32 m0, s18
	s_nop 0
	global_load_lds_dwordx4 v194, s[0:1]
	s_add_i32 m0, s18, 0x2000
	s_nop 0
	global_load_lds_dwordx4 v130, s[0:1]
	s_mov_b32 m0, s54
	s_nop 0
	global_load_lds_dwordx4 v194, s[100:101]
	s_mov_b32 m0, s57
	s_nop 0
	global_load_lds_dwordx4 v130, s[100:101]
	s_waitcnt vmcnt(8)
	s_waitcnt lgkmcnt(0)
	s_barrier
	s_waitcnt lgkmcnt(0)
	v_mfma_f32_16x16x32_bf16 v[62:65], v[144:147], v[178:181], v[62:65]
	v_mfma_f32_16x16x32_bf16 v[62:65], v[148:151], v[182:185], v[62:65]
	v_mfma_f32_16x16x32_bf16 v[58:61], v[158:161], v[182:185], v[58:61]
	v_mfma_f32_16x16x32_bf16 v[58:61], v[154:157], v[178:181], v[58:61]
	v_mfma_f32_16x16x32_bf16 v[54:57], v[162:165], v[178:181], v[54:57]
	v_mfma_f32_16x16x32_bf16 v[54:57], v[166:169], v[182:185], v[54:57]
	v_mfma_f32_16x16x32_bf16 v[50:53], v[174:177], v[182:185], v[50:53]
	v_mfma_f32_16x16x32_bf16 v[50:53], v[170:173], v[178:181], v[50:53]
	v_mfma_f32_16x16x32_bf16 v[34:37], v[170:173], v[186:189], v[34:37]
	v_mfma_f32_16x16x32_bf16 v[34:37], v[174:177], v[190:193], v[34:37]
	v_mfma_f32_16x16x32_bf16 v[38:41], v[166:169], v[190:193], v[38:41]
	v_mfma_f32_16x16x32_bf16 v[38:41], v[162:165], v[186:189], v[38:41]
	v_mfma_f32_16x16x32_bf16 v[42:45], v[154:157], v[186:189], v[42:45]
	v_mfma_f32_16x16x32_bf16 v[42:45], v[158:161], v[190:193], v[42:45]
	v_mfma_f32_16x16x32_bf16 v[46:49], v[148:151], v[190:193], v[46:49]
	v_mfma_f32_16x16x32_bf16 v[46:49], v[144:147], v[186:189], v[46:49]
	v_mfma_f32_16x16x32_bf16 v[30:33], v[144:147], v[204:207], v[30:33]
	v_mfma_f32_16x16x32_bf16 v[30:33], v[148:151], v[208:211], v[30:33]
	v_mfma_f32_16x16x32_bf16 v[26:29], v[158:161], v[208:211], v[26:29]
	v_mfma_f32_16x16x32_bf16 v[26:29], v[154:157], v[204:207], v[26:29]
	v_mfma_f32_16x16x32_bf16 v[22:25], v[162:165], v[204:207], v[22:25]
	v_mfma_f32_16x16x32_bf16 v[22:25], v[166:169], v[208:211], v[22:25]
	v_mfma_f32_16x16x32_bf16 v[18:21], v[174:177], v[208:211], v[18:21]
	v_mfma_f32_16x16x32_bf16 v[18:21], v[170:173], v[204:207], v[18:21]
	v_mfma_f32_16x16x32_bf16 v[2:5], v[170:173], v[212:215], v[2:5]
	v_mfma_f32_16x16x32_bf16 v[2:5], v[174:177], v[216:219], v[2:5]
	v_mfma_f32_16x16x32_bf16 v[6:9], v[166:169], v[216:219], v[6:9]
	v_mfma_f32_16x16x32_bf16 v[6:9], v[162:165], v[212:215], v[6:9]
	v_mfma_f32_16x16x32_bf16 v[10:13], v[154:157], v[212:215], v[10:13]
	v_mfma_f32_16x16x32_bf16 v[10:13], v[158:161], v[216:219], v[10:13]
	v_mfma_f32_16x16x32_bf16 v[14:17], v[148:151], v[216:219], v[14:17]
	v_mfma_f32_16x16x32_bf16 v[14:17], v[144:147], v[212:215], v[14:17]
	s_barrier
	s_add_i32 s76, s76, 2
	s_add_u32 s62, s62, 0x100
	s_addc_u32 s63, s63, 0
	s_add_u32 s53, s53, 0x100
	s_addc_u32 s58, s58, 0
	s_cmp_gt_u32 s76, 29
	s_cbranch_scc1 .LBB0_584

.Lpeel_disp_gu:
	s_cmp_lg_u32 s76, -2
	s_cbranch_scc1 .LBB0_581
	s_add_u32 s18, s62, 0xfff80080
	s_addc_u32 s19, s63, -1
	s_and_b64 s[0:1], s[64:65], exec
	s_cselect_b32 s71, s22, s19
	s_cselect_b32 s70, s23, s18
	s_cselect_b32 s65, s39, s58
	s_cselect_b32 s64, s47, s53
	s_add_i32 s0, 0, 0x10000
	s_add_i32 s18, 0, 0x14000
	ds_read_b128 v[144:147], v220
	ds_read_b128 v[148:151], v220 offset:1024
	ds_read_b128 v[154:157], v220 offset:2048
	ds_read_b128 v[158:161], v220 offset:3072
	ds_read_b128 v[162:165], v221
	ds_read_b128 v[166:169], v221 offset:1024
	ds_read_b128 v[170:173], v221 offset:2048
	ds_read_b128 v[174:177], v221 offset:3072
	s_add_i32 m0, s29, 0xc000
	ds_read_b128 v[178:181], v152
	ds_read_b128 v[182:185], v152 offset:1024
	ds_read_b128 v[186:189], v152 offset:2048
	ds_read_b128 v[190:193], v152 offset:3072
	ds_read_b128 v[204:207], v152 offset:4096
	ds_read_b128 v[208:211], v152 offset:5120
	ds_read_b128 v[212:215], v152 offset:6144
	ds_read_b128 v[216:219], v152 offset:7168
	global_load_lds_dwordx4 v136, s[62:63]
	s_add_i32 m0, s29, 0xe000
	s_nop 0
	global_load_lds_dwordx4 v138, s[62:63]
	s_waitcnt vmcnt(8)
	s_waitcnt lgkmcnt(0)
	s_barrier
	s_waitcnt lgkmcnt(0)
	v_mfma_f32_16x16x32_bf16 v[126:129], v[144:147], v[178:181], 0
	v_mfma_f32_16x16x32_bf16 v[126:129], v[148:151], v[182:185], v[126:129]
	v_mfma_f32_16x16x32_bf16 v[122:125], v[158:161], v[182:185], 0
	v_mfma_f32_16x16x32_bf16 v[122:125], v[154:157], v[178:181], v[122:125]
	v_mfma_f32_16x16x32_bf16 v[118:121], v[162:165], v[178:181], 0
	v_mfma_f32_16x16x32_bf16 v[118:121], v[166:169], v[182:185], v[118:121]
	v_mfma_f32_16x16x32_bf16 v[114:117], v[174:177], v[182:185], 0
	v_mfma_f32_16x16x32_bf16 v[114:117], v[170:173], v[178:181], v[114:117]
	v_mfma_f32_16x16x32_bf16 v[98:101], v[170:173], v[186:189], 0
	v_mfma_f32_16x16x32_bf16 v[98:101], v[174:177], v[190:193], v[98:101]
	v_mfma_f32_16x16x32_bf16 v[102:105], v[166:169], v[190:193], 0
	v_mfma_f32_16x16x32_bf16 v[102:105], v[162:165], v[186:189], v[102:105]
	v_mfma_f32_16x16x32_bf16 v[106:109], v[154:157], v[186:189], 0
	v_mfma_f32_16x16x32_bf16 v[106:109], v[158:161], v[190:193], v[106:109]
	v_mfma_f32_16x16x32_bf16 v[110:113], v[148:151], v[190:193], 0
	v_mfma_f32_16x16x32_bf16 v[110:113], v[144:147], v[186:189], v[110:113]
	v_mfma_f32_16x16x32_bf16 v[94:97], v[144:147], v[204:207], 0
	v_mfma_f32_16x16x32_bf16 v[94:97], v[148:151], v[208:211], v[94:97]
	v_mfma_f32_16x16x32_bf16 v[90:93], v[158:161], v[208:211], 0
	v_mfma_f32_16x16x32_bf16 v[90:93], v[154:157], v[204:207], v[90:93]
	v_mfma_f32_16x16x32_bf16 v[86:89], v[162:165], v[204:207], 0
	v_mfma_f32_16x16x32_bf16 v[86:89], v[166:169], v[208:211], v[86:89]
	v_mfma_f32_16x16x32_bf16 v[82:85], v[174:177], v[208:211], 0
	v_mfma_f32_16x16x32_bf16 v[82:85], v[170:173], v[204:207], v[82:85]
	v_mfma_f32_16x16x32_bf16 v[66:69], v[170:173], v[212:215], 0
	v_mfma_f32_16x16x32_bf16 v[66:69], v[174:177], v[216:219], v[66:69]
	v_mfma_f32_16x16x32_bf16 v[70:73], v[166:169], v[216:219], 0
	v_mfma_f32_16x16x32_bf16 v[70:73], v[162:165], v[212:215], v[70:73]
	v_mfma_f32_16x16x32_bf16 v[74:77], v[154:157], v[212:215], 0
	v_mfma_f32_16x16x32_bf16 v[74:77], v[158:161], v[216:219], v[74:77]
	v_mfma_f32_16x16x32_bf16 v[78:81], v[148:151], v[216:219], 0
	v_mfma_f32_16x16x32_bf16 v[78:81], v[144:147], v[212:215], v[78:81]
	s_barrier
	s_add_i32 s0, s0, s28
	s_mov_b32 m0, s0
	ds_read_b128 v[178:181], v152 offset:16384
	ds_read_b128 v[182:185], v152 offset:17408
	ds_read_b128 v[186:189], v152 offset:18432
	ds_read_b128 v[190:193], v152 offset:19456
	ds_read_b128 v[204:207], v152 offset:20480
	ds_read_b128 v[208:211], v152 offset:21504
	ds_read_b128 v[212:215], v152 offset:22528
	ds_read_b128 v[216:219], v152 offset:23552
	global_load_lds_dwordx4 v194, s[64:65]
	s_add_i32 m0, s0, 0x2000
	s_add_u32 s0, s64, 0x80000
	s_addc_u32 s1, s65, 0
	s_add_i32 s18, s18, s28
	global_load_lds_dwordx4 v130, s[64:65]
	s_mov_b32 m0, s18
	s_nop 0
	global_load_lds_dwordx4 v194, s[0:1]
	s_add_i32 m0, s18, 0x2000
	s_nop 0
	global_load_lds_dwordx4 v130, s[0:1]
	s_mov_b32 m0, s29
	s_nop 0
	global_load_lds_dwordx4 v194, s[70:71]
	s_mov_b32 m0, s31
	s_nop 0
	global_load_lds_dwordx4 v130, s[70:71]
	s_waitcnt vmcnt(8)
	s_waitcnt lgkmcnt(0)
	s_barrier
	s_waitcnt lgkmcnt(0)
	v_mfma_f32_16x16x32_bf16 v[62:65], v[144:147], v[178:181], 0
	v_mfma_f32_16x16x32_bf16 v[62:65], v[148:151], v[182:185], v[62:65]
	v_mfma_f32_16x16x32_bf16 v[58:61], v[158:161], v[182:185], 0
	v_mfma_f32_16x16x32_bf16 v[58:61], v[154:157], v[178:181], v[58:61]
	v_mfma_f32_16x16x32_bf16 v[54:57], v[162:165], v[178:181], 0
	v_mfma_f32_16x16x32_bf16 v[54:57], v[166:169], v[182:185], v[54:57]
	v_mfma_f32_16x16x32_bf16 v[50:53], v[174:177], v[182:185], 0
	v_mfma_f32_16x16x32_bf16 v[50:53], v[170:173], v[178:181], v[50:53]
	v_mfma_f32_16x16x32_bf16 v[34:37], v[170:173], v[186:189], 0
	v_mfma_f32_16x16x32_bf16 v[34:37], v[174:177], v[190:193], v[34:37]
	v_mfma_f32_16x16x32_bf16 v[38:41], v[166:169], v[190:193], 0
	v_mfma_f32_16x16x32_bf16 v[38:41], v[162:165], v[186:189], v[38:41]
	v_mfma_f32_16x16x32_bf16 v[42:45], v[154:157], v[186:189], 0
	v_mfma_f32_16x16x32_bf16 v[42:45], v[158:161], v[190:193], v[42:45]
	v_mfma_f32_16x16x32_bf16 v[46:49], v[148:151], v[190:193], 0
	v_mfma_f32_16x16x32_bf16 v[46:49], v[144:147], v[186:189], v[46:49]
	v_mfma_f32_16x16x32_bf16 v[30:33], v[144:147], v[204:207], 0
	v_mfma_f32_16x16x32_bf16 v[30:33], v[148:151], v[208:211], v[30:33]
	v_mfma_f32_16x16x32_bf16 v[26:29], v[158:161], v[208:211], 0
	v_mfma_f32_16x16x32_bf16 v[26:29], v[154:157], v[204:207], v[26:29]
	v_mfma_f32_16x16x32_bf16 v[22:25], v[162:165], v[204:207], 0
	v_mfma_f32_16x16x32_bf16 v[22:25], v[166:169], v[208:211], v[22:25]
	v_mfma_f32_16x16x32_bf16 v[18:21], v[174:177], v[208:211], 0
	v_mfma_f32_16x16x32_bf16 v[18:21], v[170:173], v[204:207], v[18:21]
	v_mfma_f32_16x16x32_bf16 v[2:5], v[170:173], v[212:215], 0
	v_mfma_f32_16x16x32_bf16 v[2:5], v[174:177], v[216:219], v[2:5]
	v_mfma_f32_16x16x32_bf16 v[6:9], v[166:169], v[216:219], 0
	v_mfma_f32_16x16x32_bf16 v[6:9], v[162:165], v[212:215], v[6:9]
	v_mfma_f32_16x16x32_bf16 v[10:13], v[154:157], v[212:215], 0
	v_mfma_f32_16x16x32_bf16 v[10:13], v[158:161], v[216:219], v[10:13]
	v_mfma_f32_16x16x32_bf16 v[14:17], v[148:151], v[216:219], 0
	v_mfma_f32_16x16x32_bf16 v[14:17], v[144:147], v[212:215], v[14:17]
	s_barrier
	s_add_i32 s18, 0, 0x18000
	s_add_i32 s19, 0, 0x1c000
	ds_read_b128 v[144:147], v222
	ds_read_b128 v[148:151], v222 offset:1024
	ds_read_b128 v[154:157], v222 offset:2048
	ds_read_b128 v[158:161], v222 offset:3072
	ds_read_b128 v[162:165], v223
	ds_read_b128 v[166:169], v223 offset:1024
	ds_read_b128 v[170:173], v223 offset:2048
	ds_read_b128 v[174:177], v223 offset:3072
	s_add_u32 s0, s70, 0x80000
	s_addc_u32 s1, s71, 0
	s_mov_b32 m0, s33
	ds_read_b128 v[178:181], v152 offset:32768
	ds_read_b128 v[182:185], v152 offset:33792
	ds_read_b128 v[186:189], v152 offset:34816
	ds_read_b128 v[190:193], v152 offset:35840
	ds_read_b128 v[204:207], v152 offset:36864
	ds_read_b128 v[208:211], v152 offset:37888
	ds_read_b128 v[212:215], v152 offset:38912
	ds_read_b128 v[216:219], v152 offset:39936
	global_load_lds_dwordx4 v194, s[0:1]
	s_mov_b32 m0, s40
	s_nop 0
	global_load_lds_dwordx4 v130, s[0:1]
	s_waitcnt vmcnt(8)
	s_waitcnt lgkmcnt(0)
	s_barrier
	s_waitcnt lgkmcnt(0)
	v_mfma_f32_16x16x32_bf16 v[126:129], v[144:147], v[178:181], v[126:129]
	v_mfma_f32_16x16x32_bf16 v[126:129], v[148:151], v[182:185], v[126:129]
	v_mfma_f32_16x16x32_bf16 v[122:125], v[158:161], v[182:185], v[122:125]
	v_mfma_f32_16x16x32_bf16 v[122:125], v[154:157], v[178:181], v[122:125]
	v_mfma_f32_16x16x32_bf16 v[118:121], v[162:165], v[178:181], v[118:121]
	v_mfma_f32_16x16x32_bf16 v[118:121], v[166:169], v[182:185], v[118:121]
	v_mfma_f32_16x16x32_bf16 v[114:117], v[174:177], v[182:185], v[114:117]
	v_mfma_f32_16x16x32_bf16 v[114:117], v[170:173], v[178:181], v[114:117]
	v_mfma_f32_16x16x32_bf16 v[98:101], v[170:173], v[186:189], v[98:101]
	v_mfma_f32_16x16x32_bf16 v[98:101], v[174:177], v[190:193], v[98:101]
	v_mfma_f32_16x16x32_bf16 v[102:105], v[166:169], v[190:193], v[102:105]
	v_mfma_f32_16x16x32_bf16 v[102:105], v[162:165], v[186:189], v[102:105]
	v_mfma_f32_16x16x32_bf16 v[106:109], v[154:157], v[186:189], v[106:109]
	v_mfma_f32_16x16x32_bf16 v[106:109], v[158:161], v[190:193], v[106:109]
	v_mfma_f32_16x16x32_bf16 v[110:113], v[148:151], v[190:193], v[110:113]
	v_mfma_f32_16x16x32_bf16 v[110:113], v[144:147], v[186:189], v[110:113]
	v_mfma_f32_16x16x32_bf16 v[94:97], v[144:147], v[204:207], v[94:97]
	v_mfma_f32_16x16x32_bf16 v[94:97], v[148:151], v[208:211], v[94:97]
	v_mfma_f32_16x16x32_bf16 v[90:93], v[158:161], v[208:211], v[90:93]
	v_mfma_f32_16x16x32_bf16 v[90:93], v[154:157], v[204:207], v[90:93]
	v_mfma_f32_16x16x32_bf16 v[86:89], v[162:165], v[204:207], v[86:89]
	v_mfma_f32_16x16x32_bf16 v[86:89], v[166:169], v[208:211], v[86:89]
	v_mfma_f32_16x16x32_bf16 v[82:85], v[174:177], v[208:211], v[82:85]
	v_mfma_f32_16x16x32_bf16 v[82:85], v[170:173], v[204:207], v[82:85]
	v_mfma_f32_16x16x32_bf16 v[66:69], v[170:173], v[212:215], v[66:69]
	v_mfma_f32_16x16x32_bf16 v[66:69], v[174:177], v[216:219], v[66:69]
	v_mfma_f32_16x16x32_bf16 v[70:73], v[166:169], v[216:219], v[70:73]
	v_mfma_f32_16x16x32_bf16 v[70:73], v[162:165], v[212:215], v[70:73]
	v_mfma_f32_16x16x32_bf16 v[74:77], v[154:157], v[212:215], v[74:77]
	v_mfma_f32_16x16x32_bf16 v[74:77], v[158:161], v[216:219], v[74:77]
	v_mfma_f32_16x16x32_bf16 v[78:81], v[148:151], v[216:219], v[78:81]
	v_mfma_f32_16x16x32_bf16 v[78:81], v[144:147], v[212:215], v[78:81]
	s_barrier
	s_add_u32 s98, s64, 0x80
	s_addc_u32 s99, s65, 0
	s_add_u32 s100, s70, 0x80
	s_addc_u32 s101, s71, 0
	s_add_i32 s0, s18, s28
	s_mov_b32 m0, s0
	ds_read_b128 v[178:181], v152 offset:49152
	ds_read_b128 v[182:185], v152 offset:50176
	ds_read_b128 v[186:189], v152 offset:51200
	ds_read_b128 v[190:193], v152 offset:52224
	ds_read_b128 v[204:207], v152 offset:53248
	ds_read_b128 v[208:211], v152 offset:54272
	ds_read_b128 v[212:215], v152 offset:55296
	ds_read_b128 v[216:219], v152 offset:56320
	global_load_lds_dwordx4 v194, s[98:99]
	s_add_i32 m0, s0, 0x2000
	s_add_u32 s0, s64, 0x80080
	s_addc_u32 s1, s65, 0
	s_add_i32 s18, s19, s28
	global_load_lds_dwordx4 v130, s[98:99]
	s_mov_b32 m0, s18
	s_nop 0
	global_load_lds_dwordx4 v194, s[0:1]
	s_add_i32 m0, s18, 0x2000
	s_nop 0
	global_load_lds_dwordx4 v130, s[0:1]
	s_mov_b32 m0, s54
	s_nop 0
	global_load_lds_dwordx4 v194, s[100:101]
	s_mov_b32 m0, s57
	s_nop 0
	global_load_lds_dwordx4 v130, s[100:101]
	s_waitcnt vmcnt(8)
	s_waitcnt lgkmcnt(0)
	s_barrier
	s_waitcnt lgkmcnt(0)
	v_mfma_f32_16x16x32_bf16 v[62:65], v[144:147], v[178:181], v[62:65]
	v_mfma_f32_16x16x32_bf16 v[62:65], v[148:151], v[182:185], v[62:65]
	v_mfma_f32_16x16x32_bf16 v[58:61], v[158:161], v[182:185], v[58:61]
	v_mfma_f32_16x16x32_bf16 v[58:61], v[154:157], v[178:181], v[58:61]
	v_mfma_f32_16x16x32_bf16 v[54:57], v[162:165], v[178:181], v[54:57]
	v_mfma_f32_16x16x32_bf16 v[54:57], v[166:169], v[182:185], v[54:57]
	v_mfma_f32_16x16x32_bf16 v[50:53], v[174:177], v[182:185], v[50:53]
	v_mfma_f32_16x16x32_bf16 v[50:53], v[170:173], v[178:181], v[50:53]
	v_mfma_f32_16x16x32_bf16 v[34:37], v[170:173], v[186:189], v[34:37]
	v_mfma_f32_16x16x32_bf16 v[34:37], v[174:177], v[190:193], v[34:37]
	v_mfma_f32_16x16x32_bf16 v[38:41], v[166:169], v[190:193], v[38:41]
	v_mfma_f32_16x16x32_bf16 v[38:41], v[162:165], v[186:189], v[38:41]
	v_mfma_f32_16x16x32_bf16 v[42:45], v[154:157], v[186:189], v[42:45]
	v_mfma_f32_16x16x32_bf16 v[42:45], v[158:161], v[190:193], v[42:45]
	v_mfma_f32_16x16x32_bf16 v[46:49], v[148:151], v[190:193], v[46:49]
	v_mfma_f32_16x16x32_bf16 v[46:49], v[144:147], v[186:189], v[46:49]
	v_mfma_f32_16x16x32_bf16 v[30:33], v[144:147], v[204:207], v[30:33]
	v_mfma_f32_16x16x32_bf16 v[30:33], v[148:151], v[208:211], v[30:33]
	v_mfma_f32_16x16x32_bf16 v[26:29], v[158:161], v[208:211], v[26:29]
	v_mfma_f32_16x16x32_bf16 v[26:29], v[154:157], v[204:207], v[26:29]
	v_mfma_f32_16x16x32_bf16 v[22:25], v[162:165], v[204:207], v[22:25]
	v_mfma_f32_16x16x32_bf16 v[22:25], v[166:169], v[208:211], v[22:25]
	v_mfma_f32_16x16x32_bf16 v[18:21], v[174:177], v[208:211], v[18:21]
	v_mfma_f32_16x16x32_bf16 v[18:21], v[170:173], v[204:207], v[18:21]
	v_mfma_f32_16x16x32_bf16 v[2:5], v[170:173], v[212:215], v[2:5]
	v_mfma_f32_16x16x32_bf16 v[2:5], v[174:177], v[216:219], v[2:5]
	v_mfma_f32_16x16x32_bf16 v[6:9], v[166:169], v[216:219], v[6:9]
	v_mfma_f32_16x16x32_bf16 v[6:9], v[162:165], v[212:215], v[6:9]
	v_mfma_f32_16x16x32_bf16 v[10:13], v[154:157], v[212:215], v[10:13]
	v_mfma_f32_16x16x32_bf16 v[10:13], v[158:161], v[216:219], v[10:13]
	v_mfma_f32_16x16x32_bf16 v[14:17], v[148:151], v[216:219], v[14:17]
	v_mfma_f32_16x16x32_bf16 v[14:17], v[144:147], v[212:215], v[14:17]
	s_barrier
	s_add_i32 s76, s76, 2
	s_add_u32 s62, s62, 0x100
	s_addc_u32 s63, s63, 0
	s_add_u32 s53, s53, 0x100
	s_addc_u32 s58, s58, 0
	s_cmp_gt_u32 s76, 29
	s_cbranch_scc1 .LBB0_584
	s_branch .LBB0_582

.LBB0_644:
	s_lshl_b32 s6, s23, 8
	s_ashr_i32 s7, s6, 31
	s_lshl_b64 s[0:1], s[6:7], 2
	s_ashr_i32 s24, s22, 5
	v_lshl_add_u64 v[2:3], v[204:205], 0, s[0:1]
	v_mad_i64_i32 v[66:67], s[18:19], s24, v235, v[2:3]
	s_mul_hi_i32 s7, s24, 0xc000
	s_mul_i32 s24, s24, 0xc000
	s_add_u32 s18, s90, s24
	s_addc_u32 s7, s80, s7
	s_add_u32 s0, s18, s0
	s_addc_u32 s1, s7, s1
	s_add_u32 s7, s64, 0x100
	v_lshl_add_u64 v[68:69], s[0:1], 0, v[194:195]
	s_addc_u32 s23, s65, 0
	s_mov_b32 s41, -2
	v_add_u32_e32 v218, 0x10000, v1
	v_add_u32_e32 v219, 0x14000, v1
	v_add_u32_e32 v220, 0x18000, v1
	v_add_u32_e32 v221, 0x1c000, v1
	s_branch .LBB0_646
.LBB0_645:
	s_add_u32 s64, s8, 0x100
	s_addc_u32 s65, s9, 0
	s_and_b64 s[0:1], s[70:71], exec
	s_cselect_b32 s77, s63, s65
	s_cselect_b32 s76, s62, s64
	s_cselect_b32 s71, s85, s23
	s_cselect_b32 s70, s84, s7
	s_add_i32 s0, 0, 0x10000
	s_add_i32 s18, 0, 0x14000
	ds_read_b128 v[70:73], v218
	ds_read_b128 v[82:85], v218 offset:1024
	ds_read_b128 v[94:97], v218 offset:2048
	ds_read_b128 v[106:109], v218 offset:3072
	ds_read_b128 v[118:121], v219
	ds_read_b128 v[130:133], v219 offset:1024
	ds_read_b128 v[142:145], v219 offset:2048
	ds_read_b128 v[154:157], v219 offset:3072
	s_add_i32 m0, s29, 0xc000
	ds_read_b128 v[158:161], v237
	ds_read_b128 v[170:173], v237 offset:1024
	ds_read_b128 v[174:177], v237 offset:2048
	ds_read_b128 v[178:181], v237 offset:3072
	ds_read_b128 v[182:185], v237 offset:4096
	ds_read_b128 v[186:189], v237 offset:5120
	ds_read_b128 v[210:213], v237 offset:6144
	ds_read_b128 v[214:217], v237 offset:7168
	global_load_lds_dwordx4 v206, s[8:9]
	s_add_i32 m0, s29, 0xe000
	s_nop 0
	global_load_lds_dwordx4 v208, s[8:9]
	s_waitcnt vmcnt(8)
	s_waitcnt lgkmcnt(0)
	s_barrier
	s_waitcnt lgkmcnt(0)
	v_mfma_f32_16x16x32_bf16 v[166:169], v[70:73], v[158:161], v[166:169]
	v_mfma_f32_16x16x32_bf16 v[166:169], v[82:85], v[170:173], v[166:169]
	v_mfma_f32_16x16x32_bf16 v[162:165], v[106:109], v[170:173], v[162:165]
	v_mfma_f32_16x16x32_bf16 v[162:165], v[94:97], v[158:161], v[162:165]
	v_mfma_f32_16x16x32_bf16 v[150:153], v[118:121], v[158:161], v[150:153]
	v_mfma_f32_16x16x32_bf16 v[150:153], v[130:133], v[170:173], v[150:153]
	v_mfma_f32_16x16x32_bf16 v[146:149], v[154:157], v[170:173], v[146:149]
	v_mfma_f32_16x16x32_bf16 v[146:149], v[142:145], v[158:161], v[146:149]
	v_mfma_f32_16x16x32_bf16 v[122:125], v[142:145], v[174:177], v[122:125]
	v_mfma_f32_16x16x32_bf16 v[122:125], v[154:157], v[178:181], v[122:125]
	v_mfma_f32_16x16x32_bf16 v[126:129], v[130:133], v[178:181], v[126:129]
	v_mfma_f32_16x16x32_bf16 v[126:129], v[118:121], v[174:177], v[126:129]
	v_mfma_f32_16x16x32_bf16 v[134:137], v[94:97], v[174:177], v[134:137]
	v_mfma_f32_16x16x32_bf16 v[134:137], v[106:109], v[178:181], v[134:137]
	v_mfma_f32_16x16x32_bf16 v[138:141], v[82:85], v[178:181], v[138:141]
	v_mfma_f32_16x16x32_bf16 v[138:141], v[70:73], v[174:177], v[138:141]
	v_mfma_f32_16x16x32_bf16 v[114:117], v[70:73], v[182:185], v[114:117]
	v_mfma_f32_16x16x32_bf16 v[114:117], v[82:85], v[186:189], v[114:117]
	v_mfma_f32_16x16x32_bf16 v[110:113], v[106:109], v[186:189], v[110:113]
	v_mfma_f32_16x16x32_bf16 v[110:113], v[94:97], v[182:185], v[110:113]
	v_mfma_f32_16x16x32_bf16 v[102:105], v[118:121], v[182:185], v[102:105]
	v_mfma_f32_16x16x32_bf16 v[102:105], v[130:133], v[186:189], v[102:105]
	v_mfma_f32_16x16x32_bf16 v[98:101], v[154:157], v[186:189], v[98:101]
	v_mfma_f32_16x16x32_bf16 v[98:101], v[142:145], v[182:185], v[98:101]
	v_mfma_f32_16x16x32_bf16 v[74:77], v[142:145], v[210:213], v[74:77]
	v_mfma_f32_16x16x32_bf16 v[74:77], v[154:157], v[214:217], v[74:77]
	v_mfma_f32_16x16x32_bf16 v[78:81], v[130:133], v[214:217], v[78:81]
	v_mfma_f32_16x16x32_bf16 v[78:81], v[118:121], v[210:213], v[78:81]
	v_mfma_f32_16x16x32_bf16 v[86:89], v[94:97], v[210:213], v[86:89]
	v_mfma_f32_16x16x32_bf16 v[86:89], v[106:109], v[214:217], v[86:89]
	v_mfma_f32_16x16x32_bf16 v[90:93], v[82:85], v[214:217], v[90:93]
	v_mfma_f32_16x16x32_bf16 v[90:93], v[70:73], v[210:213], v[90:93]
	s_barrier
	s_add_i32 s0, s0, s28
	s_mov_b32 m0, s0
	ds_read_b128 v[158:161], v237 offset:16384
	ds_read_b128 v[170:173], v237 offset:17408
	ds_read_b128 v[174:177], v237 offset:18432
	ds_read_b128 v[178:181], v237 offset:19456
	ds_read_b128 v[182:185], v237 offset:20480
	ds_read_b128 v[186:189], v237 offset:21504
	ds_read_b128 v[210:213], v237 offset:22528
	ds_read_b128 v[214:217], v237 offset:23552
	global_load_lds_dwordx4 v192, s[70:71]
	s_add_i32 m0, s0, 0x2000
	s_add_u32 s0, s70, 0x160000
	s_addc_u32 s1, s71, 0
	s_add_i32 s8, s18, s28
	global_load_lds_dwordx4 v190, s[70:71]
	s_mov_b32 m0, s8
	s_nop 0
	global_load_lds_dwordx4 v192, s[0:1]
	s_add_i32 m0, s8, 0x2000
	s_nop 0
	global_load_lds_dwordx4 v190, s[0:1]
	s_mov_b32 m0, s29
	s_nop 0
	global_load_lds_dwordx4 v192, s[76:77]
	s_mov_b32 m0, s31
	s_nop 0
	global_load_lds_dwordx4 v190, s[76:77]
	s_waitcnt vmcnt(8)
	s_waitcnt lgkmcnt(0)
	s_barrier
	s_waitcnt lgkmcnt(0)
	v_mfma_f32_16x16x32_bf16 v[62:65], v[70:73], v[158:161], v[62:65]
	v_mfma_f32_16x16x32_bf16 v[62:65], v[82:85], v[170:173], v[62:65]
	v_mfma_f32_16x16x32_bf16 v[58:61], v[106:109], v[170:173], v[58:61]
	v_mfma_f32_16x16x32_bf16 v[58:61], v[94:97], v[158:161], v[58:61]
	v_mfma_f32_16x16x32_bf16 v[54:57], v[118:121], v[158:161], v[54:57]
	v_mfma_f32_16x16x32_bf16 v[54:57], v[130:133], v[170:173], v[54:57]
	v_mfma_f32_16x16x32_bf16 v[50:53], v[154:157], v[170:173], v[50:53]
	v_mfma_f32_16x16x32_bf16 v[50:53], v[142:145], v[158:161], v[50:53]
	v_mfma_f32_16x16x32_bf16 v[34:37], v[142:145], v[174:177], v[34:37]
	v_mfma_f32_16x16x32_bf16 v[34:37], v[154:157], v[178:181], v[34:37]
	v_mfma_f32_16x16x32_bf16 v[38:41], v[130:133], v[178:181], v[38:41]
	v_mfma_f32_16x16x32_bf16 v[38:41], v[118:121], v[174:177], v[38:41]
	v_mfma_f32_16x16x32_bf16 v[42:45], v[94:97], v[174:177], v[42:45]
	v_mfma_f32_16x16x32_bf16 v[42:45], v[106:109], v[178:181], v[42:45]
	v_mfma_f32_16x16x32_bf16 v[46:49], v[82:85], v[178:181], v[46:49]
	v_mfma_f32_16x16x32_bf16 v[46:49], v[70:73], v[174:177], v[46:49]
	v_mfma_f32_16x16x32_bf16 v[30:33], v[70:73], v[182:185], v[30:33]
	v_mfma_f32_16x16x32_bf16 v[30:33], v[82:85], v[186:189], v[30:33]
	v_mfma_f32_16x16x32_bf16 v[26:29], v[106:109], v[186:189], v[26:29]
	v_mfma_f32_16x16x32_bf16 v[26:29], v[94:97], v[182:185], v[26:29]
	v_mfma_f32_16x16x32_bf16 v[22:25], v[118:121], v[182:185], v[22:25]
	v_mfma_f32_16x16x32_bf16 v[22:25], v[130:133], v[186:189], v[22:25]
	v_mfma_f32_16x16x32_bf16 v[18:21], v[154:157], v[186:189], v[18:21]
	v_mfma_f32_16x16x32_bf16 v[18:21], v[142:145], v[182:185], v[18:21]
	v_mfma_f32_16x16x32_bf16 v[2:5], v[142:145], v[210:213], v[2:5]
	v_mfma_f32_16x16x32_bf16 v[2:5], v[154:157], v[214:217], v[2:5]
	v_mfma_f32_16x16x32_bf16 v[6:9], v[130:133], v[214:217], v[6:9]
	v_mfma_f32_16x16x32_bf16 v[6:9], v[118:121], v[210:213], v[6:9]
	v_mfma_f32_16x16x32_bf16 v[10:13], v[94:97], v[210:213], v[10:13]
	v_mfma_f32_16x16x32_bf16 v[10:13], v[106:109], v[214:217], v[10:13]
	v_mfma_f32_16x16x32_bf16 v[14:17], v[82:85], v[214:217], v[14:17]
	v_mfma_f32_16x16x32_bf16 v[14:17], v[70:73], v[210:213], v[14:17]
	s_barrier
	s_add_i32 s8, 0, 0x18000
	s_add_i32 s9, 0, 0x1c000
	ds_read_b128 v[70:73], v220
	ds_read_b128 v[82:85], v220 offset:1024
	ds_read_b128 v[94:97], v220 offset:2048
	ds_read_b128 v[106:109], v220 offset:3072
	ds_read_b128 v[118:121], v221
	ds_read_b128 v[130:133], v221 offset:1024
	ds_read_b128 v[142:145], v221 offset:2048
	ds_read_b128 v[154:157], v221 offset:3072
	s_add_u32 s0, s76, 0x160000
	s_addc_u32 s1, s77, 0
	s_mov_b32 m0, s33
	ds_read_b128 v[158:161], v237 offset:32768
	ds_read_b128 v[170:173], v237 offset:33792
	ds_read_b128 v[174:177], v237 offset:34816
	ds_read_b128 v[178:181], v237 offset:35840
	ds_read_b128 v[182:185], v237 offset:36864
	ds_read_b128 v[186:189], v237 offset:37888
	ds_read_b128 v[210:213], v237 offset:38912
	ds_read_b128 v[214:217], v237 offset:39936
	global_load_lds_dwordx4 v192, s[0:1]
	s_mov_b32 m0, s43
	s_nop 0
	global_load_lds_dwordx4 v190, s[0:1]
	s_waitcnt vmcnt(8)
	s_waitcnt lgkmcnt(0)
	s_barrier
	s_waitcnt lgkmcnt(0)
	v_mfma_f32_16x16x32_bf16 v[166:169], v[70:73], v[158:161], v[166:169]
	v_mfma_f32_16x16x32_bf16 v[166:169], v[82:85], v[170:173], v[166:169]
	v_mfma_f32_16x16x32_bf16 v[162:165], v[106:109], v[170:173], v[162:165]
	v_mfma_f32_16x16x32_bf16 v[162:165], v[94:97], v[158:161], v[162:165]
	v_mfma_f32_16x16x32_bf16 v[150:153], v[118:121], v[158:161], v[150:153]
	v_mfma_f32_16x16x32_bf16 v[150:153], v[130:133], v[170:173], v[150:153]
	v_mfma_f32_16x16x32_bf16 v[146:149], v[154:157], v[170:173], v[146:149]
	v_mfma_f32_16x16x32_bf16 v[146:149], v[142:145], v[158:161], v[146:149]
	v_mfma_f32_16x16x32_bf16 v[122:125], v[142:145], v[174:177], v[122:125]
	v_mfma_f32_16x16x32_bf16 v[122:125], v[154:157], v[178:181], v[122:125]
	v_mfma_f32_16x16x32_bf16 v[126:129], v[130:133], v[178:181], v[126:129]
	v_mfma_f32_16x16x32_bf16 v[126:129], v[118:121], v[174:177], v[126:129]
	v_mfma_f32_16x16x32_bf16 v[134:137], v[94:97], v[174:177], v[134:137]
	v_mfma_f32_16x16x32_bf16 v[134:137], v[106:109], v[178:181], v[134:137]
	v_mfma_f32_16x16x32_bf16 v[138:141], v[82:85], v[178:181], v[138:141]
	v_mfma_f32_16x16x32_bf16 v[138:141], v[70:73], v[174:177], v[138:141]
	v_mfma_f32_16x16x32_bf16 v[114:117], v[70:73], v[182:185], v[114:117]
	v_mfma_f32_16x16x32_bf16 v[114:117], v[82:85], v[186:189], v[114:117]
	v_mfma_f32_16x16x32_bf16 v[110:113], v[106:109], v[186:189], v[110:113]
	v_mfma_f32_16x16x32_bf16 v[110:113], v[94:97], v[182:185], v[110:113]
	v_mfma_f32_16x16x32_bf16 v[102:105], v[118:121], v[182:185], v[102:105]
	v_mfma_f32_16x16x32_bf16 v[102:105], v[130:133], v[186:189], v[102:105]
	v_mfma_f32_16x16x32_bf16 v[98:101], v[154:157], v[186:189], v[98:101]
	v_mfma_f32_16x16x32_bf16 v[98:101], v[142:145], v[182:185], v[98:101]
	v_mfma_f32_16x16x32_bf16 v[74:77], v[142:145], v[210:213], v[74:77]
	v_mfma_f32_16x16x32_bf16 v[74:77], v[154:157], v[214:217], v[74:77]
	v_mfma_f32_16x16x32_bf16 v[78:81], v[130:133], v[214:217], v[78:81]
	v_mfma_f32_16x16x32_bf16 v[78:81], v[118:121], v[210:213], v[78:81]
	v_mfma_f32_16x16x32_bf16 v[86:89], v[94:97], v[210:213], v[86:89]
	v_mfma_f32_16x16x32_bf16 v[86:89], v[106:109], v[214:217], v[86:89]
	v_mfma_f32_16x16x32_bf16 v[90:93], v[82:85], v[214:217], v[90:93]
	v_mfma_f32_16x16x32_bf16 v[90:93], v[70:73], v[210:213], v[90:93]
	s_barrier
	s_add_u32 s98, s70, 0x80
	s_addc_u32 s99, s71, 0
	s_add_u32 s100, s76, 0x80
	s_addc_u32 s101, s77, 0
	s_add_i32 s0, s8, s28
	s_mov_b32 m0, s0
	ds_read_b128 v[158:161], v237 offset:49152
	ds_read_b128 v[170:173], v237 offset:50176
	ds_read_b128 v[174:177], v237 offset:51200
	ds_read_b128 v[178:181], v237 offset:52224
	ds_read_b128 v[182:185], v237 offset:53248
	ds_read_b128 v[186:189], v237 offset:54272
	ds_read_b128 v[210:213], v237 offset:55296
	ds_read_b128 v[214:217], v237 offset:56320
	global_load_lds_dwordx4 v192, s[98:99]
	s_add_i32 m0, s0, 0x2000
	s_add_u32 s0, s70, 0x160080
	s_addc_u32 s1, s71, 0
	s_add_i32 s8, s9, s28
	global_load_lds_dwordx4 v190, s[98:99]
	s_mov_b32 m0, s8
	s_nop 0
	global_load_lds_dwordx4 v192, s[0:1]
	s_add_i32 m0, s8, 0x2000
	s_nop 0
	global_load_lds_dwordx4 v190, s[0:1]
	s_mov_b32 m0, s68
	s_nop 0
	global_load_lds_dwordx4 v192, s[100:101]
	s_mov_b32 m0, s79
	s_nop 0
	global_load_lds_dwordx4 v190, s[100:101]
	s_waitcnt vmcnt(8)
	s_waitcnt lgkmcnt(0)
	s_barrier
	s_waitcnt lgkmcnt(0)
	v_mfma_f32_16x16x32_bf16 v[62:65], v[70:73], v[158:161], v[62:65]
	v_mfma_f32_16x16x32_bf16 v[62:65], v[82:85], v[170:173], v[62:65]
	v_mfma_f32_16x16x32_bf16 v[58:61], v[106:109], v[170:173], v[58:61]
	v_mfma_f32_16x16x32_bf16 v[58:61], v[94:97], v[158:161], v[58:61]
	v_mfma_f32_16x16x32_bf16 v[54:57], v[118:121], v[158:161], v[54:57]
	v_mfma_f32_16x16x32_bf16 v[54:57], v[130:133], v[170:173], v[54:57]
	v_mfma_f32_16x16x32_bf16 v[50:53], v[154:157], v[170:173], v[50:53]
	v_mfma_f32_16x16x32_bf16 v[50:53], v[142:145], v[158:161], v[50:53]
	v_mfma_f32_16x16x32_bf16 v[34:37], v[142:145], v[174:177], v[34:37]
	v_mfma_f32_16x16x32_bf16 v[34:37], v[154:157], v[178:181], v[34:37]
	v_mfma_f32_16x16x32_bf16 v[38:41], v[130:133], v[178:181], v[38:41]
	v_mfma_f32_16x16x32_bf16 v[38:41], v[118:121], v[174:177], v[38:41]
	v_mfma_f32_16x16x32_bf16 v[42:45], v[94:97], v[174:177], v[42:45]
	v_mfma_f32_16x16x32_bf16 v[42:45], v[106:109], v[178:181], v[42:45]
	v_mfma_f32_16x16x32_bf16 v[46:49], v[82:85], v[178:181], v[46:49]
	v_mfma_f32_16x16x32_bf16 v[46:49], v[70:73], v[174:177], v[46:49]
	v_mfma_f32_16x16x32_bf16 v[30:33], v[70:73], v[182:185], v[30:33]
	v_mfma_f32_16x16x32_bf16 v[30:33], v[82:85], v[186:189], v[30:33]
	v_mfma_f32_16x16x32_bf16 v[26:29], v[106:109], v[186:189], v[26:29]
	v_mfma_f32_16x16x32_bf16 v[26:29], v[94:97], v[182:185], v[26:29]
	v_mfma_f32_16x16x32_bf16 v[22:25], v[118:121], v[182:185], v[22:25]
	v_mfma_f32_16x16x32_bf16 v[22:25], v[130:133], v[186:189], v[22:25]
	v_mfma_f32_16x16x32_bf16 v[18:21], v[154:157], v[186:189], v[18:21]
	v_mfma_f32_16x16x32_bf16 v[18:21], v[142:145], v[182:185], v[18:21]
	v_mfma_f32_16x16x32_bf16 v[2:5], v[142:145], v[210:213], v[2:5]
	v_mfma_f32_16x16x32_bf16 v[2:5], v[154:157], v[214:217], v[2:5]
	v_mfma_f32_16x16x32_bf16 v[6:9], v[130:133], v[214:217], v[6:9]
	v_mfma_f32_16x16x32_bf16 v[6:9], v[118:121], v[210:213], v[6:9]
	v_mfma_f32_16x16x32_bf16 v[10:13], v[94:97], v[210:213], v[10:13]
	v_mfma_f32_16x16x32_bf16 v[10:13], v[106:109], v[214:217], v[10:13]
	v_mfma_f32_16x16x32_bf16 v[14:17], v[82:85], v[214:217], v[14:17]
	v_mfma_f32_16x16x32_bf16 v[14:17], v[70:73], v[210:213], v[14:17]
	s_barrier
	s_add_i32 s41, s41, 2
	s_add_u32 s7, s7, 0x100
	s_addc_u32 s23, s23, 0
	s_cmpk_gt_u32 s41, 0x55
	s_mov_b64 s[8:9], s[64:65]
	s_cbranch_scc1 .LBB0_648

.Lpeel_disp_down:
	s_cmp_lg_u32 s41, -2
	s_cbranch_scc1 .LBB0_645
	s_add_u32 s64, s8, 0x100
	s_addc_u32 s65, s9, 0
	s_and_b64 s[0:1], s[70:71], exec
	s_cselect_b32 s77, s63, s65
	s_cselect_b32 s76, s62, s64
	s_cselect_b32 s71, s85, s23
	s_cselect_b32 s70, s84, s7
	s_add_i32 s0, 0, 0x10000
	s_add_i32 s18, 0, 0x14000
	ds_read_b128 v[70:73], v218
	ds_read_b128 v[82:85], v218 offset:1024
	ds_read_b128 v[94:97], v218 offset:2048
	ds_read_b128 v[106:109], v218 offset:3072
	ds_read_b128 v[118:121], v219
	ds_read_b128 v[130:133], v219 offset:1024
	ds_read_b128 v[142:145], v219 offset:2048
	ds_read_b128 v[154:157], v219 offset:3072
	s_add_i32 m0, s29, 0xc000
	ds_read_b128 v[158:161], v237
	ds_read_b128 v[170:173], v237 offset:1024
	ds_read_b128 v[174:177], v237 offset:2048
	ds_read_b128 v[178:181], v237 offset:3072
	ds_read_b128 v[182:185], v237 offset:4096
	ds_read_b128 v[186:189], v237 offset:5120
	ds_read_b128 v[210:213], v237 offset:6144
	ds_read_b128 v[214:217], v237 offset:7168
	global_load_lds_dwordx4 v206, s[8:9]
	s_add_i32 m0, s29, 0xe000
	s_nop 0
	global_load_lds_dwordx4 v208, s[8:9]
	s_waitcnt vmcnt(8)
	s_waitcnt lgkmcnt(0)
	s_barrier
	s_waitcnt lgkmcnt(0)
	v_mfma_f32_16x16x32_bf16 v[166:169], v[70:73], v[158:161], 0
	v_mfma_f32_16x16x32_bf16 v[166:169], v[82:85], v[170:173], v[166:169]
	v_mfma_f32_16x16x32_bf16 v[162:165], v[106:109], v[170:173], 0
	v_mfma_f32_16x16x32_bf16 v[162:165], v[94:97], v[158:161], v[162:165]
	v_mfma_f32_16x16x32_bf16 v[150:153], v[118:121], v[158:161], 0
	v_mfma_f32_16x16x32_bf16 v[150:153], v[130:133], v[170:173], v[150:153]
	v_mfma_f32_16x16x32_bf16 v[146:149], v[154:157], v[170:173], 0
	v_mfma_f32_16x16x32_bf16 v[146:149], v[142:145], v[158:161], v[146:149]
	v_mfma_f32_16x16x32_bf16 v[122:125], v[142:145], v[174:177], 0
	v_mfma_f32_16x16x32_bf16 v[122:125], v[154:157], v[178:181], v[122:125]
	v_mfma_f32_16x16x32_bf16 v[126:129], v[130:133], v[178:181], 0
	v_mfma_f32_16x16x32_bf16 v[126:129], v[118:121], v[174:177], v[126:129]
	v_mfma_f32_16x16x32_bf16 v[134:137], v[94:97], v[174:177], 0
	v_mfma_f32_16x16x32_bf16 v[134:137], v[106:109], v[178:181], v[134:137]
	v_mfma_f32_16x16x32_bf16 v[138:141], v[82:85], v[178:181], 0
	v_mfma_f32_16x16x32_bf16 v[138:141], v[70:73], v[174:177], v[138:141]
	v_mfma_f32_16x16x32_bf16 v[114:117], v[70:73], v[182:185], 0
	v_mfma_f32_16x16x32_bf16 v[114:117], v[82:85], v[186:189], v[114:117]
	v_mfma_f32_16x16x32_bf16 v[110:113], v[106:109], v[186:189], 0
	v_mfma_f32_16x16x32_bf16 v[110:113], v[94:97], v[182:185], v[110:113]
	v_mfma_f32_16x16x32_bf16 v[102:105], v[118:121], v[182:185], 0
	v_mfma_f32_16x16x32_bf16 v[102:105], v[130:133], v[186:189], v[102:105]
	v_mfma_f32_16x16x32_bf16 v[98:101], v[154:157], v[186:189], 0
	v_mfma_f32_16x16x32_bf16 v[98:101], v[142:145], v[182:185], v[98:101]
	v_mfma_f32_16x16x32_bf16 v[74:77], v[142:145], v[210:213], 0
	v_mfma_f32_16x16x32_bf16 v[74:77], v[154:157], v[214:217], v[74:77]
	v_mfma_f32_16x16x32_bf16 v[78:81], v[130:133], v[214:217], 0
	v_mfma_f32_16x16x32_bf16 v[78:81], v[118:121], v[210:213], v[78:81]
	v_mfma_f32_16x16x32_bf16 v[86:89], v[94:97], v[210:213], 0
	v_mfma_f32_16x16x32_bf16 v[86:89], v[106:109], v[214:217], v[86:89]
	v_mfma_f32_16x16x32_bf16 v[90:93], v[82:85], v[214:217], 0
	v_mfma_f32_16x16x32_bf16 v[90:93], v[70:73], v[210:213], v[90:93]
	s_barrier
	s_add_i32 s0, s0, s28
	s_mov_b32 m0, s0
	ds_read_b128 v[158:161], v237 offset:16384
	ds_read_b128 v[170:173], v237 offset:17408
	ds_read_b128 v[174:177], v237 offset:18432
	ds_read_b128 v[178:181], v237 offset:19456
	ds_read_b128 v[182:185], v237 offset:20480
	ds_read_b128 v[186:189], v237 offset:21504
	ds_read_b128 v[210:213], v237 offset:22528
	ds_read_b128 v[214:217], v237 offset:23552
	global_load_lds_dwordx4 v192, s[70:71]
	s_add_i32 m0, s0, 0x2000
	s_add_u32 s0, s70, 0x160000
	s_addc_u32 s1, s71, 0
	s_add_i32 s8, s18, s28
	global_load_lds_dwordx4 v190, s[70:71]
	s_mov_b32 m0, s8
	s_nop 0
	global_load_lds_dwordx4 v192, s[0:1]
	s_add_i32 m0, s8, 0x2000
	s_nop 0
	global_load_lds_dwordx4 v190, s[0:1]
	s_mov_b32 m0, s29
	s_nop 0
	global_load_lds_dwordx4 v192, s[76:77]
	s_mov_b32 m0, s31
	s_nop 0
	global_load_lds_dwordx4 v190, s[76:77]
	s_waitcnt vmcnt(8)
	s_waitcnt lgkmcnt(0)
	s_barrier
	s_waitcnt lgkmcnt(0)
	v_mfma_f32_16x16x32_bf16 v[62:65], v[70:73], v[158:161], 0
	v_mfma_f32_16x16x32_bf16 v[62:65], v[82:85], v[170:173], v[62:65]
	v_mfma_f32_16x16x32_bf16 v[58:61], v[106:109], v[170:173], 0
	v_mfma_f32_16x16x32_bf16 v[58:61], v[94:97], v[158:161], v[58:61]
	v_mfma_f32_16x16x32_bf16 v[54:57], v[118:121], v[158:161], 0
	v_mfma_f32_16x16x32_bf16 v[54:57], v[130:133], v[170:173], v[54:57]
	v_mfma_f32_16x16x32_bf16 v[50:53], v[154:157], v[170:173], 0
	v_mfma_f32_16x16x32_bf16 v[50:53], v[142:145], v[158:161], v[50:53]
	v_mfma_f32_16x16x32_bf16 v[34:37], v[142:145], v[174:177], 0
	v_mfma_f32_16x16x32_bf16 v[34:37], v[154:157], v[178:181], v[34:37]
	v_mfma_f32_16x16x32_bf16 v[38:41], v[130:133], v[178:181], 0
	v_mfma_f32_16x16x32_bf16 v[38:41], v[118:121], v[174:177], v[38:41]
	v_mfma_f32_16x16x32_bf16 v[42:45], v[94:97], v[174:177], 0
	v_mfma_f32_16x16x32_bf16 v[42:45], v[106:109], v[178:181], v[42:45]
	v_mfma_f32_16x16x32_bf16 v[46:49], v[82:85], v[178:181], 0
	v_mfma_f32_16x16x32_bf16 v[46:49], v[70:73], v[174:177], v[46:49]
	v_mfma_f32_16x16x32_bf16 v[30:33], v[70:73], v[182:185], 0
	v_mfma_f32_16x16x32_bf16 v[30:33], v[82:85], v[186:189], v[30:33]
	v_mfma_f32_16x16x32_bf16 v[26:29], v[106:109], v[186:189], 0
	v_mfma_f32_16x16x32_bf16 v[26:29], v[94:97], v[182:185], v[26:29]
	v_mfma_f32_16x16x32_bf16 v[22:25], v[118:121], v[182:185], 0
	v_mfma_f32_16x16x32_bf16 v[22:25], v[130:133], v[186:189], v[22:25]
	v_mfma_f32_16x16x32_bf16 v[18:21], v[154:157], v[186:189], 0
	v_mfma_f32_16x16x32_bf16 v[18:21], v[142:145], v[182:185], v[18:21]
	v_mfma_f32_16x16x32_bf16 v[2:5], v[142:145], v[210:213], 0
	v_mfma_f32_16x16x32_bf16 v[2:5], v[154:157], v[214:217], v[2:5]
	v_mfma_f32_16x16x32_bf16 v[6:9], v[130:133], v[214:217], 0
	v_mfma_f32_16x16x32_bf16 v[6:9], v[118:121], v[210:213], v[6:9]
	v_mfma_f32_16x16x32_bf16 v[10:13], v[94:97], v[210:213], 0
	v_mfma_f32_16x16x32_bf16 v[10:13], v[106:109], v[214:217], v[10:13]
	v_mfma_f32_16x16x32_bf16 v[14:17], v[82:85], v[214:217], 0
	v_mfma_f32_16x16x32_bf16 v[14:17], v[70:73], v[210:213], v[14:17]
	s_barrier
	s_add_i32 s8, 0, 0x18000
	s_add_i32 s9, 0, 0x1c000
	ds_read_b128 v[70:73], v220
	ds_read_b128 v[82:85], v220 offset:1024
	ds_read_b128 v[94:97], v220 offset:2048
	ds_read_b128 v[106:109], v220 offset:3072
	ds_read_b128 v[118:121], v221
	ds_read_b128 v[130:133], v221 offset:1024
	ds_read_b128 v[142:145], v221 offset:2048
	ds_read_b128 v[154:157], v221 offset:3072
	s_add_u32 s0, s76, 0x160000
	s_addc_u32 s1, s77, 0
	s_mov_b32 m0, s33
	ds_read_b128 v[158:161], v237 offset:32768
	ds_read_b128 v[170:173], v237 offset:33792
	ds_read_b128 v[174:177], v237 offset:34816
	ds_read_b128 v[178:181], v237 offset:35840
	ds_read_b128 v[182:185], v237 offset:36864
	ds_read_b128 v[186:189], v237 offset:37888
	ds_read_b128 v[210:213], v237 offset:38912
	ds_read_b128 v[214:217], v237 offset:39936
	global_load_lds_dwordx4 v192, s[0:1]
	s_mov_b32 m0, s43
	s_nop 0
	global_load_lds_dwordx4 v190, s[0:1]
	s_waitcnt vmcnt(8)
	s_waitcnt lgkmcnt(0)
	s_barrier
	s_waitcnt lgkmcnt(0)
	v_mfma_f32_16x16x32_bf16 v[166:169], v[70:73], v[158:161], v[166:169]
	v_mfma_f32_16x16x32_bf16 v[166:169], v[82:85], v[170:173], v[166:169]
	v_mfma_f32_16x16x32_bf16 v[162:165], v[106:109], v[170:173], v[162:165]
	v_mfma_f32_16x16x32_bf16 v[162:165], v[94:97], v[158:161], v[162:165]
	v_mfma_f32_16x16x32_bf16 v[150:153], v[118:121], v[158:161], v[150:153]
	v_mfma_f32_16x16x32_bf16 v[150:153], v[130:133], v[170:173], v[150:153]
	v_mfma_f32_16x16x32_bf16 v[146:149], v[154:157], v[170:173], v[146:149]
	v_mfma_f32_16x16x32_bf16 v[146:149], v[142:145], v[158:161], v[146:149]
	v_mfma_f32_16x16x32_bf16 v[122:125], v[142:145], v[174:177], v[122:125]
	v_mfma_f32_16x16x32_bf16 v[122:125], v[154:157], v[178:181], v[122:125]
	v_mfma_f32_16x16x32_bf16 v[126:129], v[130:133], v[178:181], v[126:129]
	v_mfma_f32_16x16x32_bf16 v[126:129], v[118:121], v[174:177], v[126:129]
	v_mfma_f32_16x16x32_bf16 v[134:137], v[94:97], v[174:177], v[134:137]
	v_mfma_f32_16x16x32_bf16 v[134:137], v[106:109], v[178:181], v[134:137]
	v_mfma_f32_16x16x32_bf16 v[138:141], v[82:85], v[178:181], v[138:141]
	v_mfma_f32_16x16x32_bf16 v[138:141], v[70:73], v[174:177], v[138:141]
	v_mfma_f32_16x16x32_bf16 v[114:117], v[70:73], v[182:185], v[114:117]
	v_mfma_f32_16x16x32_bf16 v[114:117], v[82:85], v[186:189], v[114:117]
	v_mfma_f32_16x16x32_bf16 v[110:113], v[106:109], v[186:189], v[110:113]
	v_mfma_f32_16x16x32_bf16 v[110:113], v[94:97], v[182:185], v[110:113]
	v_mfma_f32_16x16x32_bf16 v[102:105], v[118:121], v[182:185], v[102:105]
	v_mfma_f32_16x16x32_bf16 v[102:105], v[130:133], v[186:189], v[102:105]
	v_mfma_f32_16x16x32_bf16 v[98:101], v[154:157], v[186:189], v[98:101]
	v_mfma_f32_16x16x32_bf16 v[98:101], v[142:145], v[182:185], v[98:101]
	v_mfma_f32_16x16x32_bf16 v[74:77], v[142:145], v[210:213], v[74:77]
	v_mfma_f32_16x16x32_bf16 v[74:77], v[154:157], v[214:217], v[74:77]
	v_mfma_f32_16x16x32_bf16 v[78:81], v[130:133], v[214:217], v[78:81]
	v_mfma_f32_16x16x32_bf16 v[78:81], v[118:121], v[210:213], v[78:81]
	v_mfma_f32_16x16x32_bf16 v[86:89], v[94:97], v[210:213], v[86:89]
	v_mfma_f32_16x16x32_bf16 v[86:89], v[106:109], v[214:217], v[86:89]
	v_mfma_f32_16x16x32_bf16 v[90:93], v[82:85], v[214:217], v[90:93]
	v_mfma_f32_16x16x32_bf16 v[90:93], v[70:73], v[210:213], v[90:93]
	s_barrier
	s_add_u32 s98, s70, 0x80
	s_addc_u32 s99, s71, 0
	s_add_u32 s100, s76, 0x80
	s_addc_u32 s101, s77, 0
	s_add_i32 s0, s8, s28
	s_mov_b32 m0, s0
	ds_read_b128 v[158:161], v237 offset:49152
	ds_read_b128 v[170:173], v237 offset:50176
	ds_read_b128 v[174:177], v237 offset:51200
	ds_read_b128 v[178:181], v237 offset:52224
	ds_read_b128 v[182:185], v237 offset:53248
	ds_read_b128 v[186:189], v237 offset:54272
	ds_read_b128 v[210:213], v237 offset:55296
	ds_read_b128 v[214:217], v237 offset:56320
	global_load_lds_dwordx4 v192, s[98:99]
	s_add_i32 m0, s0, 0x2000
	s_add_u32 s0, s70, 0x160080
	s_addc_u32 s1, s71, 0
	s_add_i32 s8, s9, s28
	global_load_lds_dwordx4 v190, s[98:99]
	s_mov_b32 m0, s8
	s_nop 0
	global_load_lds_dwordx4 v192, s[0:1]
	s_add_i32 m0, s8, 0x2000
	s_nop 0
	global_load_lds_dwordx4 v190, s[0:1]
	s_mov_b32 m0, s68
	s_nop 0
	global_load_lds_dwordx4 v192, s[100:101]
	s_mov_b32 m0, s79
	s_nop 0
	global_load_lds_dwordx4 v190, s[100:101]
	s_waitcnt vmcnt(8)
	s_waitcnt lgkmcnt(0)
	s_barrier
	s_waitcnt lgkmcnt(0)
	v_mfma_f32_16x16x32_bf16 v[62:65], v[70:73], v[158:161], v[62:65]
	v_mfma_f32_16x16x32_bf16 v[62:65], v[82:85], v[170:173], v[62:65]
	v_mfma_f32_16x16x32_bf16 v[58:61], v[106:109], v[170:173], v[58:61]
	v_mfma_f32_16x16x32_bf16 v[58:61], v[94:97], v[158:161], v[58:61]
	v_mfma_f32_16x16x32_bf16 v[54:57], v[118:121], v[158:161], v[54:57]
	v_mfma_f32_16x16x32_bf16 v[54:57], v[130:133], v[170:173], v[54:57]
	v_mfma_f32_16x16x32_bf16 v[50:53], v[154:157], v[170:173], v[50:53]
	v_mfma_f32_16x16x32_bf16 v[50:53], v[142:145], v[158:161], v[50:53]
	v_mfma_f32_16x16x32_bf16 v[34:37], v[142:145], v[174:177], v[34:37]
	v_mfma_f32_16x16x32_bf16 v[34:37], v[154:157], v[178:181], v[34:37]
	v_mfma_f32_16x16x32_bf16 v[38:41], v[130:133], v[178:181], v[38:41]
	v_mfma_f32_16x16x32_bf16 v[38:41], v[118:121], v[174:177], v[38:41]
	v_mfma_f32_16x16x32_bf16 v[42:45], v[94:97], v[174:177], v[42:45]
	v_mfma_f32_16x16x32_bf16 v[42:45], v[106:109], v[178:181], v[42:45]
	v_mfma_f32_16x16x32_bf16 v[46:49], v[82:85], v[178:181], v[46:49]
	v_mfma_f32_16x16x32_bf16 v[46:49], v[70:73], v[174:177], v[46:49]
	v_mfma_f32_16x16x32_bf16 v[30:33], v[70:73], v[182:185], v[30:33]
	v_mfma_f32_16x16x32_bf16 v[30:33], v[82:85], v[186:189], v[30:33]
	v_mfma_f32_16x16x32_bf16 v[26:29], v[106:109], v[186:189], v[26:29]
	v_mfma_f32_16x16x32_bf16 v[26:29], v[94:97], v[182:185], v[26:29]
	v_mfma_f32_16x16x32_bf16 v[22:25], v[118:121], v[182:185], v[22:25]
	v_mfma_f32_16x16x32_bf16 v[22:25], v[130:133], v[186:189], v[22:25]
	v_mfma_f32_16x16x32_bf16 v[18:21], v[154:157], v[186:189], v[18:21]
	v_mfma_f32_16x16x32_bf16 v[18:21], v[142:145], v[182:185], v[18:21]
	v_mfma_f32_16x16x32_bf16 v[2:5], v[142:145], v[210:213], v[2:5]
	v_mfma_f32_16x16x32_bf16 v[2:5], v[154:157], v[214:217], v[2:5]
	v_mfma_f32_16x16x32_bf16 v[6:9], v[130:133], v[214:217], v[6:9]
	v_mfma_f32_16x16x32_bf16 v[6:9], v[118:121], v[210:213], v[6:9]
	v_mfma_f32_16x16x32_bf16 v[10:13], v[94:97], v[210:213], v[10:13]
	v_mfma_f32_16x16x32_bf16 v[10:13], v[106:109], v[214:217], v[10:13]
	v_mfma_f32_16x16x32_bf16 v[14:17], v[82:85], v[214:217], v[14:17]
	v_mfma_f32_16x16x32_bf16 v[14:17], v[70:73], v[210:213], v[14:17]
	s_barrier
	s_add_i32 s41, s41, 2
	s_add_u32 s7, s7, 0x100
	s_addc_u32 s23, s23, 0
	s_cmpk_gt_u32 s41, 0x55
	s_mov_b64 s[8:9], s[64:65]
	s_cbranch_scc1 .LBB0_648
	s_branch .LBB0_646
